# GEMM main K-loops (5 instances): LDS-DMA addresses via scalar adds + saddr form, M0 values and B-fragment LDS addresses hoisted out of the loop (no VALU in load segments)
# speedup vs baseline: 1.0616x; 1.0070x over previous
; #define WAIT_V(n) asm volatile("s_waitcnt vmcnt(" #n ")" ::: "memory")
; #define BAR __builtin_amdgcn_s_barrier()
; template <bool OVL, bool PANEL = false, class Epi>
; __device__ __forceinline__ void gemm_phase(const bf16_t* __restrict__ A, long lda, const bf16_t* __restrict__ Bt, long ldb, int nM, int nN, int K,
;                                            const Epi& epi, bf16_t* shm, int w0) {
;     ...
;   if (have) { const int brow = pm * BM, bcol = pn * BM;
;     STAGE(SB(0, 0), Bt, ldb, boff, bcol, 0); STAGE(SA(0, 0), A, lda, aoff, brow, 0);
;     STAGE(SB(0, 1), Bt, ldb, boff, bcol + HALF, 0); STAGE(SA(0, 1), A, lda, aoff, brow + HALF, 0); }
;   for (int it = 0; have; ++it) {
;     const int brow = pm * BM, bcol = pn * BM;
;     f32x4 acc[2][2][4][2];
; #pragma unroll
;     for (int a0 = 0; a0 < 2; ++a0)
; #pragma unroll
;       for (int a1 = 0; a1 < 2; ++a1)
; #pragma unroll
;         for (int a2 = 0; a2 < 4; ++a2)
; #pragma unroll
;           for (int a3 = 0; a3 < 2; ++a3) acc[a0][a1][a2][a3] = (f32x4){0.f, 0.f, 0.f, 0.f};
;     bf16x8 At[4][2], B0[2][2], B1[2][2];
;     if (wr == 1) BAR;
;     WAIT_V(4); BAR;
;     STAGE(SB(1, 0), Bt, ldb, boff, bcol, 1); STAGE(SA(1, 0), A, lda, aoff, brow, 1); STAGE(SB(1, 1), Bt, ldb, boff, bcol + HALF, 1);
;     WAIT_V(6); BAR;
.LBB0_124:
	s_or_b64 exec, exec, s[0:1]
	s_mul_i32 s2, s29, 0xb0000
	v_readlane_b32 s40, v251, 49
	s_lshl_b32 s28, s10, 8
	s_lshl_b64 s[0:1], s[2:3], 1
	v_readlane_b32 s42, v251, 51
	v_readlane_b32 s43, v251, 52
	s_add_u32 s0, s42, s0
	s_addc_u32 s1, s43, s1
	v_mov_b32_e32 v0, v203
	v_add_u32_e32 v130, s96, v202
	s_waitcnt vmcnt(4)
	s_barrier
	v_readlane_b32 s41, v251, 50
	v_readlane_b32 s44, v251, 53
	v_readlane_b32 s45, v251, 54
	v_readlane_b32 s46, v251, 55
	v_readlane_b32 s47, v251, 56
	s_mov_b64 s[6:7], 0x80
	v_lshl_add_u64 v[2:3], s[0:1], 0, v[0:1]
	v_readfirstlane_b32 s2, v130
	v_add_u32_e32 v131, 0x2000, v130
	v_lshl_add_u64 v[4:5], v[2:3], 0, s[6:7]
	s_mov_b32 m0, s2
	v_readfirstlane_b32 s2, v131
	v_readlane_b32 s40, v252, 20
	global_load_lds_dwordx4 v[4:5], off
	s_mov_b32 m0, s2
	s_mul_i32 s2, s10, 0x160000
	v_readlane_b32 s54, v252, 34
	s_mov_b64 s[8:9], 0x58080
	s_mul_hi_i32 s5, s28, 0x1600
	v_readlane_b32 s55, v252, 35
	s_add_u32 s4, s54, s2
	v_lshl_add_u64 v[2:3], v[2:3], 0, s[8:9]
	s_addc_u32 s5, s55, s5
	v_mov_b32_e32 v0, v203
	v_add_u32_e32 v132, 0x8000, v206
	global_load_lds_dwordx4 v[2:3], off
	v_readfirstlane_b32 s2, v132
	v_lshl_add_u64 v[2:3], s[4:5], 0, v[0:1]
	v_add_u32_e32 v133, 0xa000, v206
	v_lshl_add_u64 v[4:5], v[2:3], 0, s[6:7]
	s_mov_b32 m0, s2
	v_readfirstlane_b32 s2, v133
	global_load_lds_dwordx4 v[4:5], off
	v_lshl_add_u64 v[2:3], v[2:3], 0, s[8:9]
	s_mov_b32 m0, s2
	v_mov_b32_e32 v0, v203
	v_add_u32_e32 v134, s75, v202
	global_load_lds_dwordx4 v[2:3], off
	s_mov_b64 s[14:15], 0xb0080
	v_lshl_add_u64 v[2:3], s[0:1], 0, v[0:1]
	v_readfirstlane_b32 s2, v134
	v_add_u32_e32 v135, 0x2000, v134
	v_lshl_add_u64 v[4:5], v[2:3], 0, s[14:15]
	s_mov_b32 m0, s2
	s_mov_b64 s[16:17], 0x108080
	v_readfirstlane_b32 s2, v135
	global_load_lds_dwordx4 v[4:5], off
	v_lshl_add_u64 v[2:3], v[2:3], 0, s[16:17]
	s_mov_b32 m0, s2
	v_readlane_b32 s41, v252, 21
	global_load_lds_dwordx4 v[2:3], off
	s_waitcnt vmcnt(6)
	v_readlane_b32 s42, v252, 22
	v_readlane_b32 s43, v252, 23
	v_mov_b32_e32 v2, 0
	s_mov_b32 s2, -2
	s_mov_b64 s[6:7], 0
	v_mov_b32_e32 v3, v2
	v_mov_b32_e32 v4, v2
	v_mov_b32_e32 v5, v2
	v_mov_b32_e32 v6, v2
	v_mov_b32_e32 v7, v2
	v_mov_b32_e32 v8, v2
	v_mov_b32_e32 v9, v2
	s_waitcnt vmcnt(0)
	v_mov_b32_e32 v10, v2
	v_mov_b32_e32 v11, v2
	v_mov_b32_e32 v12, v2
	v_mov_b32_e32 v13, v2
	s_waitcnt lgkmcnt(0)
	v_mov_b32_e32 v14, v2
	v_mov_b32_e32 v15, v2
	v_mov_b32_e32 v16, v2
	v_mov_b32_e32 v17, v2
	v_mov_b32_e32 v18, v2
	v_mov_b32_e32 v19, v2
	v_mov_b32_e32 v20, v2
	v_mov_b32_e32 v21, v2
	v_mov_b32_e32 v22, v2
	v_mov_b32_e32 v23, v2
	v_mov_b32_e32 v24, v2
	v_mov_b32_e32 v25, v2
	v_mov_b32_e32 v26, v2
	v_mov_b32_e32 v27, v2
	v_mov_b32_e32 v28, v2
	v_mov_b32_e32 v29, v2
	v_mov_b32_e32 v30, v2
	v_mov_b32_e32 v31, v2
	v_mov_b32_e32 v32, v2
	v_mov_b32_e32 v33, v2
	v_mov_b32_e32 v34, v2
	v_mov_b32_e32 v35, v2
	v_mov_b32_e32 v36, v2
	v_mov_b32_e32 v37, v2
	v_mov_b32_e32 v38, v2
	v_mov_b32_e32 v39, v2
	v_mov_b32_e32 v40, v2
	v_mov_b32_e32 v41, v2
	v_mov_b32_e32 v42, v2
	v_mov_b32_e32 v43, v2
	v_mov_b32_e32 v44, v2
	v_mov_b32_e32 v45, v2
	v_mov_b32_e32 v46, v2
	v_mov_b32_e32 v47, v2
	v_mov_b32_e32 v48, v2
	v_mov_b32_e32 v49, v2
	v_mov_b32_e32 v50, v2
	v_mov_b32_e32 v51, v2
	v_mov_b32_e32 v52, v2
	v_mov_b32_e32 v53, v2
	v_mov_b32_e32 v54, v2
	v_mov_b32_e32 v55, v2
	v_mov_b32_e32 v56, v2
	v_mov_b32_e32 v57, v2
	v_mov_b32_e32 v58, v2
	v_mov_b32_e32 v59, v2
	v_mov_b32_e32 v60, v2
	v_mov_b32_e32 v61, v2
	v_mov_b32_e32 v62, v2
	v_mov_b32_e32 v63, v2
	v_mov_b32_e32 v64, v2
	v_mov_b32_e32 v65, v2
	v_mov_b32_e32 v66, v2
	v_mov_b32_e32 v67, v2
	v_mov_b32_e32 v68, v2
	v_mov_b32_e32 v69, v2
	v_mov_b32_e32 v70, v2
	v_mov_b32_e32 v71, v2
	v_mov_b32_e32 v72, v2
	v_mov_b32_e32 v73, v2
	v_mov_b32_e32 v74, v2
	v_mov_b32_e32 v75, v2
	v_mov_b32_e32 v76, v2
	v_mov_b32_e32 v77, v2
	v_mov_b32_e32 v78, v2
	v_mov_b32_e32 v79, v2
	v_mov_b32_e32 v80, v2
	v_mov_b32_e32 v81, v2
	v_mov_b32_e32 v82, v2
	v_mov_b32_e32 v83, v2
	v_mov_b32_e32 v84, v2
	v_mov_b32_e32 v85, v2
	v_mov_b32_e32 v86, v2
	v_mov_b32_e32 v87, v2
	v_mov_b32_e32 v88, v2
	v_mov_b32_e32 v89, v2
	v_mov_b32_e32 v90, v2
	v_mov_b32_e32 v91, v2
	v_mov_b32_e32 v92, v2
	v_mov_b32_e32 v93, v2
	v_mov_b32_e32 v94, v2
	v_mov_b32_e32 v95, v2
	v_mov_b32_e32 v96, v2
	v_mov_b32_e32 v97, v2
	v_mov_b32_e32 v98, v2
	v_mov_b32_e32 v99, v2
	v_mov_b32_e32 v100, v2
	v_mov_b32_e32 v101, v2
	v_mov_b32_e32 v102, v2
	v_mov_b32_e32 v103, v2
	v_mov_b32_e32 v104, v2
	v_mov_b32_e32 v105, v2
	v_mov_b32_e32 v106, v2
	v_mov_b32_e32 v107, v2
	v_mov_b32_e32 v108, v2
	v_mov_b32_e32 v109, v2
	v_mov_b32_e32 v110, v2
	v_mov_b32_e32 v111, v2
	v_mov_b32_e32 v112, v2
	v_mov_b32_e32 v113, v2
	v_mov_b32_e32 v114, v2
	v_mov_b32_e32 v115, v2
	v_mov_b32_e32 v116, v2
	v_mov_b32_e32 v117, v2
	v_mov_b32_e32 v118, v2
	v_mov_b32_e32 v119, v2
	v_mov_b32_e32 v120, v2
	v_mov_b32_e32 v121, v2
	v_mov_b32_e32 v122, v2
	v_mov_b32_e32 v123, v2
	v_mov_b32_e32 v124, v2
	v_mov_b32_e32 v125, v2
	v_mov_b32_e32 v126, v2
	v_mov_b32_e32 v127, v2
	v_mov_b32_e32 v128, v2
	v_mov_b32_e32 v129, v2
	s_mov_b64 s[18:19], 0x58100
	s_mov_b64 s[30:31], 0xb0100
	s_mov_b64 s[40:41], 0x108100
	s_mov_b64 s[42:43], 0x58180
	v_readlane_b32 s44, v252, 24
	v_readlane_b32 s45, v252, 25
	v_readlane_b32 s46, v252, 26
	v_readlane_b32 s47, v252, 27
	v_readlane_b32 s48, v252, 28
	v_readlane_b32 s49, v252, 29
	v_readlane_b32 s50, v252, 30
	v_readlane_b32 s51, v252, 31
	v_readlane_b32 s52, v252, 32
	v_readlane_b32 s53, v252, 33
	s_barrier
	v_add_u32_e32 v218, s21, v212
	v_readfirstlane_b32 s25, v206
	s_add_u32 s25, s25, 0xc000
	v_readfirstlane_b32 s32, v206
	s_add_u32 s32, s32, 0xe000
	v_add_u32_e32 v219, s33, v212
	v_readfirstlane_b32 s44, v204
	v_readfirstlane_b32 s45, v205
	v_readfirstlane_b32 s46, v206
	v_readfirstlane_b32 s47, v207
	v_readfirstlane_b32 s48, v208
	v_readfirstlane_b32 s49, v209
	v_add_u32_e32 v220, s96, v212
	v_readfirstlane_b32 s50, v210
	v_readfirstlane_b32 s51, v211
	v_add_u32_e32 v221, s75, v212
	v_readfirstlane_b32 s52, v130
	v_readfirstlane_b32 s53, v131
	v_readfirstlane_b32 s54, v132
	v_readfirstlane_b32 s55, v133
	v_readfirstlane_b32 s60, v134
	v_readfirstlane_b32 s61, v135
	v_add_u32_e32 v136, 0xc000, v206
	v_add_u32_e32 v137, 0xe000, v206
; #define LDA(dst, b, h) for (int m = 0; m < 4; ++m) for (int k = 0; k < 2; ++k) \
;     dst[m][k] = *reinterpret_cast<const bf16x8*>((char*)SA(b, h) + a_thr + (m * 2 + k) * 1024)
; #define LDB(dst, b, h) for (int n = 0; n < 2; ++n) for (int k = 0; k < 2; ++k) \
;     dst[n][k] = *reinterpret_cast<const bf16x8*>((char*)SB(b, h) + b_thr + (n * 2 + k) * 1024)
; #define MMA(ai, bj, At, Btf) do { __builtin_amdgcn_s_setprio(1); \
;     for (int m = 0; m < 4; ++m) for (int n = 0; n < 2; ++n) for (int k = 0; k < 2; ++k) \
;       acc[ai][bj][m][n] = __builtin_amdgcn_mfma_f32_16x16x32_bf16(Btf[n][k], At[m][k], acc[ai][bj][m][n], 0, 0, 0); \
;     __builtin_amdgcn_s_setprio(0); } while (0)
; #define WAIT_V(n) asm volatile("s_waitcnt vmcnt(" #n ")" ::: "memory")
; #define WAIT_L(n) asm volatile("s_waitcnt lgkmcnt(" #n ")" ::: "memory")
; #define BAR __builtin_amdgcn_s_barrier()
; #define SCHED __builtin_amdgcn_sched_barrier(0)
; template <bool OVL, bool PANEL = false, class Epi>
; __device__ __forceinline__ void gemm_phase(const bf16_t* __restrict__ A, long lda, const bf16_t* __restrict__ Bt, long ldb, int nM, int nN, int K,
;                                            const Epi& epi, bf16_t* shm, int w0) {
;     ...
;     for (int t = 0; t < nt - 2; t += 2) {
;       LDB(B0, 0, 0); SCHED; LDA(At, 0, 0); STAGE(SA(1, 1), A, lda, aoff, brow + HALF, t + 1);
;       WAIT_L(8); BAR; WAIT_L(0); MMA(0, 0, At, B0); BAR; SCHED;
;       LDB(B1, 0, 1); STAGE(SB(0, 0), Bt, ldb, boff, bcol, t + 2);
;       BAR; WAIT_L(0); MMA(0, 1, At, B1); BAR;
;       LDA(At, 0, 1); STAGE(SA(0, 0), A, lda, aoff, brow, t + 2);
;       BAR; WAIT_L(0); MMA(1, 0, At, B0); BAR; SCHED;
;       STAGE(SB(0, 1), Bt, ldb, boff, bcol + HALF, t + 2);
;       WAIT_V(6); BAR; MMA(1, 1, At, B1); BAR;
.LBB0_125:
	ds_read_b128 v[138:141], v218
	ds_read_b128 v[142:145], v218 offset:1024
	ds_read_b128 v[146:149], v218 offset:2048
	ds_read_b128 v[150:153], v218 offset:3072
	s_add_u32 s8, s4, s6
	s_addc_u32 s9, s5, s7
	ds_read_b128 v[154:157], v213
	ds_read_b128 v[158:161], v213 offset:1024
	ds_read_b128 v[162:165], v213 offset:2048
	ds_read_b128 v[166:169], v213 offset:3072
	ds_read_b128 v[170:173], v213 offset:4096
	ds_read_b128 v[174:177], v213 offset:5120
	ds_read_b128 v[178:181], v213 offset:6144
	ds_read_b128 v[182:185], v213 offset:7168
	s_mov_b32 m0, s25
	s_add_u32 s98, s8, s14
	s_addc_u32 s99, s9, s15
	global_load_lds_dwordx4 v203, s[98:99]
	s_mov_b32 m0, s32
	s_add_u32 s98, s8, s16
	s_addc_u32 s99, s9, s17
	global_load_lds_dwordx4 v203, s[98:99]
	s_waitcnt lgkmcnt(8)
	s_barrier
	s_waitcnt lgkmcnt(0)
	s_setprio 1
	s_waitcnt lgkmcnt(0)
	v_mfma_f32_16x16x32_bf16 v[126:129], v[138:141], v[154:157], v[126:129]
	v_mfma_f32_16x16x32_bf16 v[122:125], v[146:149], v[154:157], v[122:125]
	v_mfma_f32_16x16x32_bf16 v[118:121], v[138:141], v[162:165], v[118:121]
	v_mfma_f32_16x16x32_bf16 v[114:117], v[146:149], v[162:165], v[114:117]
	v_mfma_f32_16x16x32_bf16 v[110:113], v[138:141], v[170:173], v[110:113]
	v_mfma_f32_16x16x32_bf16 v[106:109], v[146:149], v[170:173], v[106:109]
	v_mfma_f32_16x16x32_bf16 v[102:105], v[138:141], v[178:181], v[102:105]
	v_mfma_f32_16x16x32_bf16 v[98:101], v[146:149], v[178:181], v[98:101]
	v_mfma_f32_16x16x32_bf16 v[126:129], v[142:145], v[158:161], v[126:129]
	v_mfma_f32_16x16x32_bf16 v[122:125], v[150:153], v[158:161], v[122:125]
	v_mfma_f32_16x16x32_bf16 v[118:121], v[142:145], v[166:169], v[118:121]
	v_mfma_f32_16x16x32_bf16 v[114:117], v[150:153], v[166:169], v[114:117]
	v_mfma_f32_16x16x32_bf16 v[110:113], v[142:145], v[174:177], v[110:113]
	v_mfma_f32_16x16x32_bf16 v[106:109], v[150:153], v[174:177], v[106:109]
	v_mfma_f32_16x16x32_bf16 v[102:105], v[142:145], v[182:185], v[102:105]
	v_mfma_f32_16x16x32_bf16 v[98:101], v[150:153], v[182:185], v[98:101]
	s_setprio 0
	s_barrier
	s_add_u32 vcc_lo, s0, s6
	ds_read_b128 v[186:189], v219
	ds_read_b128 v[190:193], v219 offset:1024
	ds_read_b128 v[194:197], v219 offset:2048
	ds_read_b128 v[198:201], v219 offset:3072
	s_addc_u32 vcc_hi, s1, s7
	s_mov_b32 m0, s44
	s_add_u32 s98, vcc_lo, s34
	s_addc_u32 s99, vcc_hi, s35
	global_load_lds_dwordx4 v203, s[98:99]
	s_mov_b32 m0, s45
	s_add_u32 s98, vcc_lo, s18
	s_addc_u32 s99, vcc_hi, s19
	global_load_lds_dwordx4 v203, s[98:99]
	s_barrier
	s_waitcnt lgkmcnt(0)
	s_setprio 1
	s_waitcnt lgkmcnt(0)
	v_mfma_f32_16x16x32_bf16 v[94:97], v[186:189], v[154:157], v[94:97]
	v_mfma_f32_16x16x32_bf16 v[90:93], v[194:197], v[154:157], v[90:93]
	v_mfma_f32_16x16x32_bf16 v[86:89], v[186:189], v[162:165], v[86:89]
	v_mfma_f32_16x16x32_bf16 v[82:85], v[194:197], v[162:165], v[82:85]
	v_mfma_f32_16x16x32_bf16 v[78:81], v[186:189], v[170:173], v[78:81]
	v_mfma_f32_16x16x32_bf16 v[74:77], v[194:197], v[170:173], v[74:77]
	v_mfma_f32_16x16x32_bf16 v[70:73], v[186:189], v[178:181], v[70:73]
	v_mfma_f32_16x16x32_bf16 v[66:69], v[194:197], v[178:181], v[66:69]
	v_mfma_f32_16x16x32_bf16 v[94:97], v[190:193], v[158:161], v[94:97]
	v_mfma_f32_16x16x32_bf16 v[90:93], v[198:201], v[158:161], v[90:93]
	v_mfma_f32_16x16x32_bf16 v[86:89], v[190:193], v[166:169], v[86:89]
	v_mfma_f32_16x16x32_bf16 v[82:85], v[198:201], v[166:169], v[82:85]
	v_mfma_f32_16x16x32_bf16 v[78:81], v[190:193], v[174:177], v[78:81]
	v_mfma_f32_16x16x32_bf16 v[74:77], v[198:201], v[174:177], v[74:77]
	v_mfma_f32_16x16x32_bf16 v[70:73], v[190:193], v[182:185], v[70:73]
	v_mfma_f32_16x16x32_bf16 v[66:69], v[198:201], v[182:185], v[66:69]
	s_setprio 0
	s_barrier
	ds_read_b128 v[154:157], v213 offset:16384
	ds_read_b128 v[158:161], v213 offset:17408
	ds_read_b128 v[162:165], v213 offset:18432
	ds_read_b128 v[166:169], v213 offset:19456
	ds_read_b128 v[170:173], v213 offset:20480
	ds_read_b128 v[174:177], v213 offset:21504
	ds_read_b128 v[178:181], v213 offset:22528
	ds_read_b128 v[182:185], v213 offset:23552
	s_mov_b32 m0, s46
	s_add_u32 s98, s8, s34
	s_addc_u32 s99, s9, s35
	global_load_lds_dwordx4 v203, s[98:99]
	s_mov_b32 m0, s47
	s_add_u32 s98, s8, s18
	s_addc_u32 s99, s9, s19
	global_load_lds_dwordx4 v203, s[98:99]
	s_barrier
	s_waitcnt lgkmcnt(0)
	s_setprio 1
	s_waitcnt lgkmcnt(0)
	v_mfma_f32_16x16x32_bf16 v[62:65], v[138:141], v[154:157], v[62:65]
	v_mfma_f32_16x16x32_bf16 v[58:61], v[146:149], v[154:157], v[58:61]
	v_mfma_f32_16x16x32_bf16 v[54:57], v[138:141], v[162:165], v[54:57]
	v_mfma_f32_16x16x32_bf16 v[50:53], v[146:149], v[162:165], v[50:53]
	v_mfma_f32_16x16x32_bf16 v[46:49], v[138:141], v[170:173], v[46:49]
	v_mfma_f32_16x16x32_bf16 v[42:45], v[146:149], v[170:173], v[42:45]
	v_mfma_f32_16x16x32_bf16 v[38:41], v[138:141], v[178:181], v[38:41]
	v_mfma_f32_16x16x32_bf16 v[34:37], v[146:149], v[178:181], v[34:37]
	v_mfma_f32_16x16x32_bf16 v[62:65], v[142:145], v[158:161], v[62:65]
	v_mfma_f32_16x16x32_bf16 v[58:61], v[150:153], v[158:161], v[58:61]
	v_mfma_f32_16x16x32_bf16 v[54:57], v[142:145], v[166:169], v[54:57]
	v_mfma_f32_16x16x32_bf16 v[50:53], v[150:153], v[166:169], v[50:53]
	v_mfma_f32_16x16x32_bf16 v[46:49], v[142:145], v[174:177], v[46:49]
	v_mfma_f32_16x16x32_bf16 v[42:45], v[150:153], v[174:177], v[42:45]
	v_mfma_f32_16x16x32_bf16 v[38:41], v[142:145], v[182:185], v[38:41]
	v_mfma_f32_16x16x32_bf16 v[34:37], v[150:153], v[182:185], v[34:37]
	s_setprio 0
	s_barrier
	s_mov_b32 m0, s48
	s_add_u32 s98, vcc_lo, s30
	s_addc_u32 s99, vcc_hi, s31
	global_load_lds_dwordx4 v203, s[98:99]
	s_mov_b32 m0, s49
	s_add_u32 s98, vcc_lo, s40
	s_addc_u32 s99, vcc_hi, s41
	global_load_lds_dwordx4 v203, s[98:99]
	s_waitcnt vmcnt(6)
	s_barrier
; #define LDA(dst, b, h) for (int m = 0; m < 4; ++m) for (int k = 0; k < 2; ++k) \
;     dst[m][k] = *reinterpret_cast<const bf16x8*>((char*)SA(b, h) + a_thr + (m * 2 + k) * 1024)
; #define LDB(dst, b, h) for (int n = 0; n < 2; ++n) for (int k = 0; k < 2; ++k) \
;     dst[n][k] = *reinterpret_cast<const bf16x8*>((char*)SB(b, h) + b_thr + (n * 2 + k) * 1024)
; #define MMA(ai, bj, At, Btf) do { __builtin_amdgcn_s_setprio(1); \
;     for (int m = 0; m < 4; ++m) for (int n = 0; n < 2; ++n) for (int k = 0; k < 2; ++k) \
;       acc[ai][bj][m][n] = __builtin_amdgcn_mfma_f32_16x16x32_bf16(Btf[n][k], At[m][k], acc[ai][bj][m][n], 0, 0, 0); \
;     __builtin_amdgcn_s_setprio(0); } while (0)
; #define WAIT_V(n) asm volatile("s_waitcnt vmcnt(" #n ")" ::: "memory")
; #define WAIT_L(n) asm volatile("s_waitcnt lgkmcnt(" #n ")" ::: "memory")
; #define BAR __builtin_amdgcn_s_barrier()
; #define SCHED __builtin_amdgcn_sched_barrier(0)
; template <bool OVL, bool PANEL = false, class Epi>
; __device__ __forceinline__ void gemm_phase(const bf16_t* __restrict__ A, long lda, const bf16_t* __restrict__ Bt, long ldb, int nM, int nN, int K,
;                                            const Epi& epi, bf16_t* shm, int w0) {
;     ...
;       WAIT_V(6); BAR; MMA(1, 1, At, B1); BAR;
;       LDB(B0, 1, 0); SCHED; LDA(At, 1, 0); STAGE(SA(0, 1), A, lda, aoff, brow + HALF, t + 2);
;       WAIT_L(8); BAR; WAIT_L(0); MMA(0, 0, At, B0); BAR; SCHED;
;       LDB(B1, 1, 1); STAGE(SB(1, 0), Bt, ldb, boff, bcol, t + 3);
;       BAR; WAIT_L(0); MMA(0, 1, At, B1); BAR;
;       LDA(At, 1, 1); STAGE(SA(1, 0), A, lda, aoff, brow, t + 3);
	s_setprio 1
	v_mfma_f32_16x16x32_bf16 v[30:33], v[186:189], v[154:157], v[30:33]
	v_mfma_f32_16x16x32_bf16 v[26:29], v[194:197], v[154:157], v[26:29]
	v_mfma_f32_16x16x32_bf16 v[22:25], v[186:189], v[162:165], v[22:25]
	v_mfma_f32_16x16x32_bf16 v[18:21], v[194:197], v[162:165], v[18:21]
	v_mfma_f32_16x16x32_bf16 v[14:17], v[186:189], v[170:173], v[14:17]
	v_mfma_f32_16x16x32_bf16 v[10:13], v[194:197], v[170:173], v[10:13]
	v_mfma_f32_16x16x32_bf16 v[6:9], v[186:189], v[178:181], v[6:9]
	v_mfma_f32_16x16x32_bf16 v[2:5], v[194:197], v[178:181], v[2:5]
	v_mfma_f32_16x16x32_bf16 v[30:33], v[190:193], v[158:161], v[30:33]
	v_mfma_f32_16x16x32_bf16 v[26:29], v[198:201], v[158:161], v[26:29]
	v_mfma_f32_16x16x32_bf16 v[22:25], v[190:193], v[166:169], v[22:25]
	v_mfma_f32_16x16x32_bf16 v[18:21], v[198:201], v[166:169], v[18:21]
	v_mfma_f32_16x16x32_bf16 v[14:17], v[190:193], v[174:177], v[14:17]
	v_mfma_f32_16x16x32_bf16 v[10:13], v[198:201], v[174:177], v[10:13]
	v_mfma_f32_16x16x32_bf16 v[6:9], v[190:193], v[182:185], v[6:9]
	v_mfma_f32_16x16x32_bf16 v[2:5], v[198:201], v[182:185], v[2:5]
	s_setprio 0
	s_barrier
	ds_read_b128 v[138:141], v220
	ds_read_b128 v[142:145], v220 offset:1024
	ds_read_b128 v[146:149], v220 offset:2048
	ds_read_b128 v[150:153], v220 offset:3072
	ds_read_b128 v[154:157], v213 offset:32768
	ds_read_b128 v[158:161], v213 offset:33792
	ds_read_b128 v[162:165], v213 offset:34816
	ds_read_b128 v[166:169], v213 offset:35840
	ds_read_b128 v[170:173], v213 offset:36864
	ds_read_b128 v[174:177], v213 offset:37888
	ds_read_b128 v[178:181], v213 offset:38912
	ds_read_b128 v[182:185], v213 offset:39936
	s_mov_b32 m0, s50
	s_add_u32 s98, s8, s30
	s_addc_u32 s99, s9, s31
	global_load_lds_dwordx4 v203, s[98:99]
	s_mov_b32 m0, s51
	s_add_u32 s98, s8, s40
	s_addc_u32 s99, s9, s41
	global_load_lds_dwordx4 v203, s[98:99]
	s_waitcnt lgkmcnt(8)
	s_barrier
	s_waitcnt lgkmcnt(0)
	s_setprio 1
	s_waitcnt lgkmcnt(0)
	v_mfma_f32_16x16x32_bf16 v[126:129], v[138:141], v[154:157], v[126:129]
	v_mfma_f32_16x16x32_bf16 v[122:125], v[146:149], v[154:157], v[122:125]
	v_mfma_f32_16x16x32_bf16 v[118:121], v[138:141], v[162:165], v[118:121]
	v_mfma_f32_16x16x32_bf16 v[114:117], v[146:149], v[162:165], v[114:117]
	v_mfma_f32_16x16x32_bf16 v[110:113], v[138:141], v[170:173], v[110:113]
	v_mfma_f32_16x16x32_bf16 v[106:109], v[146:149], v[170:173], v[106:109]
	v_mfma_f32_16x16x32_bf16 v[102:105], v[138:141], v[178:181], v[102:105]
	v_mfma_f32_16x16x32_bf16 v[98:101], v[146:149], v[178:181], v[98:101]
	v_mfma_f32_16x16x32_bf16 v[126:129], v[142:145], v[158:161], v[126:129]
	v_mfma_f32_16x16x32_bf16 v[122:125], v[150:153], v[158:161], v[122:125]
	v_mfma_f32_16x16x32_bf16 v[118:121], v[142:145], v[166:169], v[118:121]
	v_mfma_f32_16x16x32_bf16 v[114:117], v[150:153], v[166:169], v[114:117]
	v_mfma_f32_16x16x32_bf16 v[110:113], v[142:145], v[174:177], v[110:113]
	v_mfma_f32_16x16x32_bf16 v[106:109], v[150:153], v[174:177], v[106:109]
	v_mfma_f32_16x16x32_bf16 v[102:105], v[142:145], v[182:185], v[102:105]
	v_mfma_f32_16x16x32_bf16 v[98:101], v[150:153], v[182:185], v[98:101]
	s_setprio 0
	s_barrier
	ds_read_b128 v[186:189], v221
	ds_read_b128 v[190:193], v221 offset:1024
	ds_read_b128 v[194:197], v221 offset:2048
	ds_read_b128 v[198:201], v221 offset:3072
	s_mov_b32 m0, s52
	s_add_u32 s98, vcc_lo, s94
	s_addc_u32 s99, vcc_hi, s95
	global_load_lds_dwordx4 v203, s[98:99]
	s_mov_b32 m0, s53
	s_add_u32 s98, vcc_lo, s42
	s_addc_u32 s99, vcc_hi, s43
	global_load_lds_dwordx4 v203, s[98:99]
	s_barrier
	s_waitcnt lgkmcnt(0)
	s_setprio 1
	s_waitcnt lgkmcnt(0)
	v_mfma_f32_16x16x32_bf16 v[94:97], v[186:189], v[154:157], v[94:97]
	v_mfma_f32_16x16x32_bf16 v[90:93], v[194:197], v[154:157], v[90:93]
	v_mfma_f32_16x16x32_bf16 v[86:89], v[186:189], v[162:165], v[86:89]
	v_mfma_f32_16x16x32_bf16 v[82:85], v[194:197], v[162:165], v[82:85]
	v_mfma_f32_16x16x32_bf16 v[78:81], v[186:189], v[170:173], v[78:81]
	v_mfma_f32_16x16x32_bf16 v[74:77], v[194:197], v[170:173], v[74:77]
	v_mfma_f32_16x16x32_bf16 v[70:73], v[186:189], v[178:181], v[70:73]
	v_mfma_f32_16x16x32_bf16 v[66:69], v[194:197], v[178:181], v[66:69]
	v_mfma_f32_16x16x32_bf16 v[94:97], v[190:193], v[158:161], v[94:97]
	v_mfma_f32_16x16x32_bf16 v[90:93], v[198:201], v[158:161], v[90:93]
	v_mfma_f32_16x16x32_bf16 v[86:89], v[190:193], v[166:169], v[86:89]
	v_mfma_f32_16x16x32_bf16 v[82:85], v[198:201], v[166:169], v[82:85]
	v_mfma_f32_16x16x32_bf16 v[78:81], v[190:193], v[174:177], v[78:81]
	v_mfma_f32_16x16x32_bf16 v[74:77], v[198:201], v[174:177], v[74:77]
	v_mfma_f32_16x16x32_bf16 v[70:73], v[190:193], v[182:185], v[70:73]
	v_mfma_f32_16x16x32_bf16 v[66:69], v[198:201], v[182:185], v[66:69]
	s_setprio 0
	s_barrier
	ds_read_b128 v[154:157], v213 offset:49152
	ds_read_b128 v[158:161], v213 offset:50176
	ds_read_b128 v[162:165], v213 offset:51200
	ds_read_b128 v[166:169], v213 offset:52224
	ds_read_b128 v[170:173], v213 offset:53248
	ds_read_b128 v[174:177], v213 offset:54272
	ds_read_b128 v[178:181], v213 offset:55296
	ds_read_b128 v[182:185], v213 offset:56320
	s_mov_b32 m0, s54
	s_add_u32 s98, s8, s94
	s_addc_u32 s99, s9, s95
	global_load_lds_dwordx4 v203, s[98:99]
	s_mov_b32 m0, s55
	s_add_u32 s98, s8, s42
	s_addc_u32 s99, s9, s43
	global_load_lds_dwordx4 v203, s[98:99]
	s_barrier
; #define LDA(dst, b, h) for (int m = 0; m < 4; ++m) for (int k = 0; k < 2; ++k) \
;     dst[m][k] = *reinterpret_cast<const bf16x8*>((char*)SA(b, h) + a_thr + (m * 2 + k) * 1024)
; #define LDB(dst, b, h) for (int n = 0; n < 2; ++n) for (int k = 0; k < 2; ++k) \
;     dst[n][k] = *reinterpret_cast<const bf16x8*>((char*)SB(b, h) + b_thr + (n * 2 + k) * 1024)
; #define MMA(ai, bj, At, Btf) do { __builtin_amdgcn_s_setprio(1); \
;     for (int m = 0; m < 4; ++m) for (int n = 0; n < 2; ++n) for (int k = 0; k < 2; ++k) \
;       acc[ai][bj][m][n] = __builtin_amdgcn_mfma_f32_16x16x32_bf16(Btf[n][k], At[m][k], acc[ai][bj][m][n], 0, 0, 0); \
;     __builtin_amdgcn_s_setprio(0); } while (0)
; #define WAIT_V(n) asm volatile("s_waitcnt vmcnt(" #n ")" ::: "memory")
; #define WAIT_L(n) asm volatile("s_waitcnt lgkmcnt(" #n ")" ::: "memory")
; #define BAR __builtin_amdgcn_s_barrier()
; #define SCHED __builtin_amdgcn_sched_barrier(0)
; template <bool OVL, bool PANEL = false, class Epi>
; __device__ __forceinline__ void gemm_phase(const bf16_t* __restrict__ A, long lda, const bf16_t* __restrict__ Bt, long ldb, int nM, int nN, int K,
;                                            const Epi& epi, bf16_t* shm, int w0) {
;     ...
;       BAR; WAIT_L(0); MMA(1, 0, At, B0); BAR; SCHED;
;       STAGE(SB(1, 1), Bt, ldb, boff, bcol + HALF, t + 3);
;       WAIT_V(6); BAR; MMA(1, 1, At, B1); BAR;
;     }
;     { LDB(B0, 0, 0); LDA(At, 0, 0); STAGE(SA(1, 1), A, lda, aoff, brow + HALF, nt - 1);
;       BAR; WAIT_L(0); MMA(0, 0, At, B0); BAR;
;       LDB(B1, 0, 1); BAR; WAIT_L(0); MMA(0, 1, At, B1); BAR;
;       LDA(At, 0, 1); WAIT_V(4); BAR; WAIT_L(0); MMA(1, 0, At, B0); MMA(1, 1, At, B1); BAR; }
	s_waitcnt lgkmcnt(0)
	s_setprio 1
	s_waitcnt lgkmcnt(0)
	v_mfma_f32_16x16x32_bf16 v[62:65], v[138:141], v[154:157], v[62:65]
	v_mfma_f32_16x16x32_bf16 v[58:61], v[146:149], v[154:157], v[58:61]
	v_mfma_f32_16x16x32_bf16 v[54:57], v[138:141], v[162:165], v[54:57]
	v_mfma_f32_16x16x32_bf16 v[50:53], v[146:149], v[162:165], v[50:53]
	v_mfma_f32_16x16x32_bf16 v[46:49], v[138:141], v[170:173], v[46:49]
	v_mfma_f32_16x16x32_bf16 v[42:45], v[146:149], v[170:173], v[42:45]
	v_mfma_f32_16x16x32_bf16 v[38:41], v[138:141], v[178:181], v[38:41]
	v_mfma_f32_16x16x32_bf16 v[34:37], v[146:149], v[178:181], v[34:37]
	v_mfma_f32_16x16x32_bf16 v[62:65], v[142:145], v[158:161], v[62:65]
	v_mfma_f32_16x16x32_bf16 v[58:61], v[150:153], v[158:161], v[58:61]
	v_mfma_f32_16x16x32_bf16 v[54:57], v[142:145], v[166:169], v[54:57]
	v_mfma_f32_16x16x32_bf16 v[50:53], v[150:153], v[166:169], v[50:53]
	v_mfma_f32_16x16x32_bf16 v[46:49], v[142:145], v[174:177], v[46:49]
	v_mfma_f32_16x16x32_bf16 v[42:45], v[150:153], v[174:177], v[42:45]
	v_mfma_f32_16x16x32_bf16 v[38:41], v[142:145], v[182:185], v[38:41]
	v_mfma_f32_16x16x32_bf16 v[34:37], v[150:153], v[182:185], v[34:37]
	s_setprio 0
	s_barrier
	s_mov_b64 s[8:9], 0xb0180
	s_mov_b64 s[8:9], 0x108180
	s_mov_b32 m0, s60
	s_add_u32 s98, vcc_lo, 0xb0180
	s_addc_u32 s99, vcc_hi, 0
	global_load_lds_dwordx4 v203, s[98:99]
	s_mov_b32 m0, s61
	s_add_u32 s98, vcc_lo, 0x108180
	s_addc_u32 s99, vcc_hi, 0
	global_load_lds_dwordx4 v203, s[98:99]
	s_waitcnt vmcnt(6)
	s_barrier
	s_setprio 1
	v_mfma_f32_16x16x32_bf16 v[30:33], v[186:189], v[154:157], v[30:33]
	v_mfma_f32_16x16x32_bf16 v[26:29], v[194:197], v[154:157], v[26:29]
	v_mfma_f32_16x16x32_bf16 v[22:25], v[186:189], v[162:165], v[22:25]
	v_mfma_f32_16x16x32_bf16 v[18:21], v[194:197], v[162:165], v[18:21]
	v_mfma_f32_16x16x32_bf16 v[14:17], v[186:189], v[170:173], v[14:17]
	v_mfma_f32_16x16x32_bf16 v[10:13], v[194:197], v[170:173], v[10:13]
	v_mfma_f32_16x16x32_bf16 v[6:9], v[186:189], v[178:181], v[6:9]
	v_mfma_f32_16x16x32_bf16 v[2:5], v[194:197], v[178:181], v[2:5]
	v_mfma_f32_16x16x32_bf16 v[30:33], v[190:193], v[158:161], v[30:33]
	v_mfma_f32_16x16x32_bf16 v[26:29], v[198:201], v[158:161], v[26:29]
	v_mfma_f32_16x16x32_bf16 v[22:25], v[190:193], v[166:169], v[22:25]
	v_mfma_f32_16x16x32_bf16 v[18:21], v[198:201], v[166:169], v[18:21]
	v_mfma_f32_16x16x32_bf16 v[14:17], v[190:193], v[174:177], v[14:17]
	v_mfma_f32_16x16x32_bf16 v[10:13], v[198:201], v[174:177], v[10:13]
	v_mfma_f32_16x16x32_bf16 v[6:9], v[190:193], v[182:185], v[6:9]
	v_mfma_f32_16x16x32_bf16 v[2:5], v[198:201], v[182:185], v[2:5]
	s_setprio 0
	s_add_i32 s2, s2, 2
	s_add_u32 s6, s6, 0x100
	s_addc_u32 s7, s7, 0
	s_cmp_gt_u32 s2, 39
	s_barrier
	s_cbranch_scc0 .LBB0_125
	s_or_b32 s0, s28, 0x80
	s_mul_hi_i32 s1, s0, 0x1600
	s_mulk_i32 s0, 0x1600
	v_readlane_b32 s2, v250, 49
	v_add_u32_e32 v227, 16, v212
	s_add_u32 s0, s2, s0
	v_readlane_b32 s2, v250, 50
	v_add_u32_e32 v0, 0x10000, v227
	s_addc_u32 s1, s2, s1
	v_readfirstlane_b32 s2, v136
	ds_read_b128 v[130:133], v0
	ds_read_b128 v[138:141], v0 offset:1024
	ds_read_b128 v[142:145], v0 offset:2048
	ds_read_b128 v[146:149], v0 offset:3072
	ds_read_b128 v[150:153], v213
	ds_read_b128 v[154:157], v213 offset:1024
	ds_read_b128 v[158:161], v213 offset:2048
	ds_read_b128 v[162:165], v213 offset:3072
	ds_read_b128 v[166:169], v213 offset:4096
	ds_read_b128 v[170:173], v213 offset:5120
	ds_read_b128 v[174:177], v213 offset:6144
	ds_read_b128 v[178:181], v213 offset:7168
	v_mov_b32_e32 v0, v203
	s_mov_b32 m0, s2
	s_nop 0
	v_lshl_add_u64 v[134:135], s[0:1], 0, v[0:1]
	global_load_lds_dwordx4 v0, s[0:1]
	v_readfirstlane_b32 s0, v137
	v_lshl_add_u64 v[134:135], v[134:135], 0, s[26:27]
	s_mov_b32 m0, s0
	s_nop 0
	global_load_lds_dwordx4 v[134:135], off
	s_barrier
	s_waitcnt lgkmcnt(0)
	s_setprio 1
	s_waitcnt lgkmcnt(0)
	v_mfma_f32_16x16x32_bf16 v[126:129], v[130:133], v[150:153], v[126:129]
	v_mfma_f32_16x16x32_bf16 v[122:125], v[142:145], v[150:153], v[122:125]
	v_mfma_f32_16x16x32_bf16 v[118:121], v[130:133], v[158:161], v[118:121]
	v_mfma_f32_16x16x32_bf16 v[114:117], v[142:145], v[158:161], v[114:117]
	v_mfma_f32_16x16x32_bf16 v[110:113], v[130:133], v[166:169], v[110:113]
	v_mfma_f32_16x16x32_bf16 v[106:109], v[142:145], v[166:169], v[106:109]
	v_mfma_f32_16x16x32_bf16 v[102:105], v[130:133], v[174:177], v[102:105]
	v_mfma_f32_16x16x32_bf16 v[98:101], v[142:145], v[174:177], v[98:101]
	v_mfma_f32_16x16x32_bf16 v[126:129], v[138:141], v[154:157], v[126:129]
	v_mfma_f32_16x16x32_bf16 v[122:125], v[146:149], v[154:157], v[122:125]
	v_mfma_f32_16x16x32_bf16 v[118:121], v[138:141], v[162:165], v[118:121]
	v_mfma_f32_16x16x32_bf16 v[114:117], v[146:149], v[162:165], v[114:117]
	v_mfma_f32_16x16x32_bf16 v[110:113], v[138:141], v[170:173], v[110:113]
	v_mfma_f32_16x16x32_bf16 v[106:109], v[146:149], v[170:173], v[106:109]
	v_mfma_f32_16x16x32_bf16 v[102:105], v[138:141], v[178:181], v[102:105]
	v_mfma_f32_16x16x32_bf16 v[98:101], v[146:149], v[178:181], v[98:101]
	s_setprio 0
	v_add_u32_e32 v0, 0x14000, v227
	s_barrier
	ds_read_b128 v[134:137], v0
	ds_read_b128 v[182:185], v0 offset:1024
	ds_read_b128 v[186:189], v0 offset:2048
	ds_read_b128 v[190:193], v0 offset:3072
	s_barrier
; #define LDA(dst, b, h) for (int m = 0; m < 4; ++m) for (int k = 0; k < 2; ++k) \
;     dst[m][k] = *reinterpret_cast<const bf16x8*>((char*)SA(b, h) + a_thr + (m * 2 + k) * 1024)
; #define LDB(dst, b, h) for (int n = 0; n < 2; ++n) for (int k = 0; k < 2; ++k) \
;     dst[n][k] = *reinterpret_cast<const bf16x8*>((char*)SB(b, h) + b_thr + (n * 2 + k) * 1024)
; #define MMA(ai, bj, At, Btf) do { __builtin_amdgcn_s_setprio(1); \
;     for (int m = 0; m < 4; ++m) for (int n = 0; n < 2; ++n) for (int k = 0; k < 2; ++k) \
;       acc[ai][bj][m][n] = __builtin_amdgcn_mfma_f32_16x16x32_bf16(Btf[n][k], At[m][k], acc[ai][bj][m][n], 0, 0, 0); \
;     __builtin_amdgcn_s_setprio(0); } while (0)
; #define WAIT_V(n) asm volatile("s_waitcnt vmcnt(" #n ")" ::: "memory")
; #define WAIT_L(n) asm volatile("s_waitcnt lgkmcnt(" #n ")" ::: "memory")
; #define BAR __builtin_amdgcn_s_barrier()
; template <bool OVL, bool PANEL = false, class Epi>
; __device__ __forceinline__ void gemm_phase(const bf16_t* __restrict__ A, long lda, const bf16_t* __restrict__ Bt, long ldb, int nM, int nN, int K,
;                                            const Epi& epi, bf16_t* shm, int w0) {
;     ...
;       LDA(At, 0, 1); WAIT_V(4); BAR; WAIT_L(0); MMA(1, 0, At, B0); MMA(1, 1, At, B1); BAR; }
;     { LDB(B0, 1, 0); LDA(At, 1, 0); WAIT_V(2); BAR; WAIT_L(0); MMA(0, 0, At, B0); BAR;
;       LDB(B1, 1, 1); WAIT_V(0); BAR; WAIT_L(0); MMA(0, 1, At, B1); BAR;
	s_waitcnt lgkmcnt(0)
	s_setprio 1
	s_waitcnt lgkmcnt(0)
	v_mfma_f32_16x16x32_bf16 v[94:97], v[134:137], v[150:153], v[94:97]
	v_mfma_f32_16x16x32_bf16 v[90:93], v[186:189], v[150:153], v[90:93]
	v_mfma_f32_16x16x32_bf16 v[86:89], v[134:137], v[158:161], v[86:89]
	v_mfma_f32_16x16x32_bf16 v[82:85], v[186:189], v[158:161], v[82:85]
	v_mfma_f32_16x16x32_bf16 v[78:81], v[134:137], v[166:169], v[78:81]
	v_mfma_f32_16x16x32_bf16 v[66:69], v[186:189], v[174:177], v[66:69]
	v_mfma_f32_16x16x32_bf16 v[94:97], v[182:185], v[154:157], v[94:97]
	v_mfma_f32_16x16x32_bf16 v[90:93], v[190:193], v[154:157], v[90:93]
	v_mfma_f32_16x16x32_bf16 v[86:89], v[182:185], v[162:165], v[86:89]
	v_mfma_f32_16x16x32_bf16 v[82:85], v[190:193], v[162:165], v[82:85]
	v_mfma_f32_16x16x32_bf16 v[78:81], v[182:185], v[170:173], v[78:81]
	v_mfma_f32_16x16x32_bf16 v[74:77], v[186:189], v[166:169], v[74:77]
	v_mfma_f32_16x16x32_bf16 v[70:73], v[134:137], v[174:177], v[70:73]
	v_mfma_f32_16x16x32_bf16 v[66:69], v[190:193], v[178:181], v[66:69]
	v_mfma_f32_16x16x32_bf16 v[150:153], v[190:193], v[170:173], v[74:77]
	v_mfma_f32_16x16x32_bf16 v[154:157], v[182:185], v[178:181], v[70:73]
	s_setprio 0
	s_barrier
	s_nop 2
	ds_read_b128 v[70:73], v213 offset:16384
	ds_read_b128 v[74:77], v213 offset:17408
	ds_read_b128 v[158:161], v213 offset:18432
	ds_read_b128 v[162:165], v213 offset:19456
	ds_read_b128 v[166:169], v213 offset:20480
	ds_read_b128 v[170:173], v213 offset:21504
	ds_read_b128 v[174:177], v213 offset:22528
	ds_read_b128 v[178:181], v213 offset:23552
	s_waitcnt vmcnt(4)
	s_barrier
	s_waitcnt lgkmcnt(0)
	s_setprio 1
	s_waitcnt lgkmcnt(0)
	v_mfma_f32_16x16x32_bf16 v[58:61], v[142:145], v[70:73], v[58:61]
	v_mfma_f32_16x16x32_bf16 v[54:57], v[130:133], v[158:161], v[54:57]
	v_mfma_f32_16x16x32_bf16 v[62:65], v[130:133], v[70:73], v[62:65]
	v_mfma_f32_16x16x32_bf16 v[58:61], v[146:149], v[74:77], v[58:61]
	v_mfma_f32_16x16x32_bf16 v[54:57], v[138:141], v[162:165], v[54:57]
	v_mfma_f32_16x16x32_bf16 v[50:53], v[142:145], v[158:161], v[50:53]
	v_mfma_f32_16x16x32_bf16 v[46:49], v[130:133], v[166:169], v[46:49]
	v_mfma_f32_16x16x32_bf16 v[42:45], v[142:145], v[166:169], v[42:45]
	v_mfma_f32_16x16x32_bf16 v[38:41], v[130:133], v[174:177], v[38:41]
	v_mfma_f32_16x16x32_bf16 v[34:37], v[142:145], v[174:177], v[34:37]
	v_mfma_f32_16x16x32_bf16 v[194:197], v[138:141], v[74:77], v[62:65]
	v_mfma_f32_16x16x32_bf16 v[198:201], v[146:149], v[162:165], v[50:53]
	v_mfma_f32_16x16x32_bf16 v[214:217], v[138:141], v[170:173], v[46:49]
	v_mfma_f32_16x16x32_bf16 v[218:221], v[146:149], v[170:173], v[42:45]
	v_mfma_f32_16x16x32_bf16 v[130:133], v[138:141], v[178:181], v[38:41]
	v_mfma_f32_16x16x32_bf16 v[138:141], v[146:149], v[178:181], v[34:37]
	s_setprio 0
	s_setprio 1
	v_mfma_f32_16x16x32_bf16 v[30:33], v[134:137], v[70:73], v[30:33]
	v_mfma_f32_16x16x32_bf16 v[26:29], v[186:189], v[70:73], v[26:29]
	v_mfma_f32_16x16x32_bf16 v[22:25], v[134:137], v[158:161], v[22:25]
	v_mfma_f32_16x16x32_bf16 v[18:21], v[186:189], v[158:161], v[18:21]
	v_mfma_f32_16x16x32_bf16 v[14:17], v[134:137], v[166:169], v[14:17]
	v_mfma_f32_16x16x32_bf16 v[10:13], v[186:189], v[166:169], v[10:13]
	v_mfma_f32_16x16x32_bf16 v[6:9], v[134:137], v[174:177], v[6:9]
	v_mfma_f32_16x16x32_bf16 v[2:5], v[186:189], v[174:177], v[2:5]
	v_mfma_f32_16x16x32_bf16 v[142:145], v[182:185], v[74:77], v[30:33]
	v_mfma_f32_16x16x32_bf16 v[146:149], v[190:193], v[74:77], v[26:29]
	v_mfma_f32_16x16x32_bf16 v[222:225], v[182:185], v[162:165], v[22:25]
	v_mfma_f32_16x16x32_bf16 v[158:161], v[190:193], v[162:165], v[18:21]
	v_mfma_f32_16x16x32_bf16 v[162:165], v[182:185], v[170:173], v[14:17]
	v_mfma_f32_16x16x32_bf16 v[166:169], v[190:193], v[170:173], v[10:13]
	v_mfma_f32_16x16x32_bf16 v[134:137], v[182:185], v[178:181], v[6:9]
	v_mfma_f32_16x16x32_bf16 v[170:173], v[190:193], v[178:181], v[2:5]
	s_setprio 0
	v_add_u32_e32 v0, 0x18000, v227
	s_barrier
	ds_read_b128 v[34:37], v0
	ds_read_b128 v[174:177], v0 offset:1024
	ds_read_b128 v[178:181], v0 offset:2048
	ds_read_b128 v[182:185], v0 offset:3072
	ds_read_b128 v[18:21], v213 offset:32768
	ds_read_b128 v[22:25], v213 offset:33792
	ds_read_b128 v[26:29], v213 offset:34816
	ds_read_b128 v[50:53], v213 offset:35840
	ds_read_b128 v[186:189], v213 offset:36864
	ds_read_b128 v[190:193], v213 offset:37888
	ds_read_b128 v[228:231], v213 offset:38912
	ds_read_b128 v[232:235], v213 offset:39936
	s_waitcnt vmcnt(2)
	s_barrier
; #define LDA(dst, b, h) for (int m = 0; m < 4; ++m) for (int k = 0; k < 2; ++k) \
;     dst[m][k] = *reinterpret_cast<const bf16x8*>((char*)SA(b, h) + a_thr + (m * 2 + k) * 1024)
; #define LDB(dst, b, h) for (int n = 0; n < 2; ++n) for (int k = 0; k < 2; ++k) \
;     dst[n][k] = *reinterpret_cast<const bf16x8*>((char*)SB(b, h) + b_thr + (n * 2 + k) * 1024)
; #define MMA(ai, bj, At, Btf) do { __builtin_amdgcn_s_setprio(1); \
;     for (int m = 0; m < 4; ++m) for (int n = 0; n < 2; ++n) for (int k = 0; k < 2; ++k) \
;       acc[ai][bj][m][n] = __builtin_amdgcn_mfma_f32_16x16x32_bf16(Btf[n][k], At[m][k], acc[ai][bj][m][n], 0, 0, 0); \
;     __builtin_amdgcn_s_setprio(0); } while (0)
; #define WAIT_V(n) asm volatile("s_waitcnt vmcnt(" #n ")" ::: "memory")
; #define WAIT_L(n) asm volatile("s_waitcnt lgkmcnt(" #n ")" ::: "memory")
; #define BAR __builtin_amdgcn_s_barrier()
; template <bool OVL, bool PANEL = false, class Epi>
; __device__ __forceinline__ void gemm_phase(const bf16_t* __restrict__ A, long lda, const bf16_t* __restrict__ Bt, long ldb, int nM, int nN, int K,
;                                            const Epi& epi, bf16_t* shm, int w0) {
;     ...
;     { LDB(B0, 1, 0); LDA(At, 1, 0); WAIT_V(2); BAR; WAIT_L(0); MMA(0, 0, At, B0); BAR;
;       LDB(B1, 1, 1); WAIT_V(0); BAR; WAIT_L(0); MMA(0, 1, At, B1); BAR;
;       LDA(At, 1, 1); BAR; WAIT_L(0); MMA(1, 0, At, B0); MMA(1, 1, At, B1); BAR; }
;     if (wr == 0) BAR;
	s_waitcnt lgkmcnt(0)
	s_setprio 1
	s_waitcnt lgkmcnt(0)
	v_mfma_f32_16x16x32_bf16 v[6:9], v[178:181], v[18:21], v[122:125]
	v_mfma_f32_16x16x32_bf16 v[10:13], v[178:181], v[26:29], v[114:117]
	v_mfma_f32_16x16x32_bf16 v[14:17], v[178:181], v[186:189], v[106:109]
	v_mfma_f32_16x16x32_bf16 v[2:5], v[34:37], v[18:21], v[126:129]
	v_mfma_f32_16x16x32_bf16 v[30:33], v[182:185], v[22:25], v[6:9]
	v_mfma_f32_16x16x32_bf16 v[6:9], v[34:37], v[26:29], v[118:121]
	v_mfma_f32_16x16x32_bf16 v[38:41], v[182:185], v[50:53], v[10:13]
	v_mfma_f32_16x16x32_bf16 v[10:13], v[34:37], v[186:189], v[110:113]
	v_mfma_f32_16x16x32_bf16 v[42:45], v[182:185], v[190:193], v[14:17]
	v_mfma_f32_16x16x32_bf16 v[14:17], v[34:37], v[228:231], v[102:105]
	v_mfma_f32_16x16x32_bf16 v[46:49], v[178:181], v[228:231], v[98:101]
	v_mfma_f32_16x16x32_bf16 v[2:5], v[174:177], v[22:25], v[2:5]
	v_mfma_f32_16x16x32_bf16 v[6:9], v[174:177], v[50:53], v[6:9]
	v_mfma_f32_16x16x32_bf16 v[10:13], v[174:177], v[190:193], v[10:13]
	v_mfma_f32_16x16x32_bf16 v[14:17], v[174:177], v[232:235], v[14:17]
	v_mfma_f32_16x16x32_bf16 v[46:49], v[182:185], v[232:235], v[46:49]
	s_setprio 0
	v_add_u32_e32 v0, 0x1c000, v227
	s_barrier
	ds_read_b128 v[102:105], v0
	ds_read_b128 v[236:239], v0 offset:1024
	ds_read_b128 v[240:243], v0 offset:2048
	ds_read_b128 v[244:247], v0 offset:3072
	s_waitcnt vmcnt(0)
	s_barrier
	s_waitcnt lgkmcnt(0)
	s_setprio 1
	s_waitcnt lgkmcnt(0)
	v_mfma_f32_16x16x32_bf16 v[62:65], v[102:105], v[18:21], v[94:97]
	v_mfma_f32_16x16x32_bf16 v[18:21], v[240:243], v[18:21], v[90:93]
	v_mfma_f32_16x16x32_bf16 v[98:101], v[244:247], v[22:25], v[18:21]
	v_mfma_f32_16x16x32_bf16 v[18:21], v[102:105], v[26:29], v[86:89]
	v_mfma_f32_16x16x32_bf16 v[70:73], v[236:239], v[50:53], v[18:21]
	v_mfma_f32_16x16x32_bf16 v[18:21], v[240:243], v[26:29], v[82:85]
	v_mfma_f32_16x16x32_bf16 v[106:109], v[244:247], v[50:53], v[18:21]
	v_mfma_f32_16x16x32_bf16 v[18:21], v[102:105], v[186:189], v[78:81]
	v_mfma_f32_16x16x32_bf16 v[74:77], v[236:239], v[190:193], v[18:21]
	v_mfma_f32_16x16x32_bf16 v[18:21], v[240:243], v[186:189], v[150:153]
	v_mfma_f32_16x16x32_bf16 v[110:113], v[244:247], v[190:193], v[18:21]
	v_mfma_f32_16x16x32_bf16 v[18:21], v[102:105], v[228:231], v[154:157]
	v_mfma_f32_16x16x32_bf16 v[78:81], v[236:239], v[232:235], v[18:21]
	v_mfma_f32_16x16x32_bf16 v[18:21], v[240:243], v[228:231], v[66:69]
	v_mfma_f32_16x16x32_bf16 v[62:65], v[236:239], v[22:25], v[62:65]
	v_mfma_f32_16x16x32_bf16 v[114:117], v[244:247], v[232:235], v[18:21]
	s_setprio 0
	s_barrier
	ds_read_b128 v[86:89], v213 offset:49152
	ds_read_b128 v[90:93], v213 offset:50176
	ds_read_b128 v[94:97], v213 offset:51200
	ds_read_b128 v[118:121], v213 offset:52224
	ds_read_b128 v[150:153], v213 offset:53248
	ds_read_b128 v[154:157], v213 offset:54272
	ds_read_b128 v[186:189], v213 offset:55296
	ds_read_b128 v[190:193], v213 offset:56320
	s_barrier
	s_waitcnt lgkmcnt(0)
	s_setprio 1
	s_waitcnt lgkmcnt(0)
	v_mfma_f32_16x16x32_bf16 v[22:25], v[178:181], v[86:89], v[58:61]
	v_mfma_f32_16x16x32_bf16 v[26:29], v[178:181], v[94:97], v[198:201]
	v_mfma_f32_16x16x32_bf16 v[18:21], v[34:37], v[86:89], v[194:197]
	v_mfma_f32_16x16x32_bf16 v[50:53], v[182:185], v[90:93], v[22:25]
	v_mfma_f32_16x16x32_bf16 v[22:25], v[34:37], v[94:97], v[54:57]
	v_mfma_f32_16x16x32_bf16 v[54:57], v[182:185], v[118:121], v[26:29]
	v_mfma_f32_16x16x32_bf16 v[26:29], v[34:37], v[150:153], v[214:217]
	v_mfma_f32_16x16x32_bf16 v[58:61], v[178:181], v[150:153], v[218:221]
	v_mfma_f32_16x16x32_bf16 v[34:37], v[34:37], v[186:189], v[130:133]
	v_mfma_f32_16x16x32_bf16 v[66:69], v[178:181], v[186:189], v[138:141]
	v_mfma_f32_16x16x32_bf16 v[18:21], v[174:177], v[90:93], v[18:21]
	v_mfma_f32_16x16x32_bf16 v[22:25], v[174:177], v[118:121], v[22:25]
	v_mfma_f32_16x16x32_bf16 v[26:29], v[174:177], v[154:157], v[26:29]
	v_mfma_f32_16x16x32_bf16 v[58:61], v[182:185], v[154:157], v[58:61]
	v_mfma_f32_16x16x32_bf16 v[34:37], v[174:177], v[190:193], v[34:37]
	v_mfma_f32_16x16x32_bf16 v[66:69], v[182:185], v[190:193], v[66:69]
	s_setprio 0
	s_setprio 1
	v_mfma_f32_16x16x32_bf16 v[82:85], v[102:105], v[86:89], v[142:145]
	v_mfma_f32_16x16x32_bf16 v[86:89], v[240:243], v[86:89], v[146:149]
	v_mfma_f32_16x16x32_bf16 v[82:85], v[236:239], v[90:93], v[82:85]
	v_mfma_f32_16x16x32_bf16 v[122:125], v[244:247], v[90:93], v[86:89]
	v_mfma_f32_16x16x32_bf16 v[86:89], v[102:105], v[94:97], v[222:225]
	v_mfma_f32_16x16x32_bf16 v[90:93], v[240:243], v[94:97], v[158:161]
	v_mfma_f32_16x16x32_bf16 v[94:97], v[240:243], v[150:153], v[166:169]
	v_mfma_f32_16x16x32_bf16 v[86:89], v[236:239], v[118:121], v[86:89]
	v_mfma_f32_16x16x32_bf16 v[126:129], v[244:247], v[118:121], v[90:93]
	v_mfma_f32_16x16x32_bf16 v[118:121], v[244:247], v[154:157], v[94:97]
	v_mfma_f32_16x16x32_bf16 v[94:97], v[102:105], v[186:189], v[134:137]
	v_mfma_f32_16x16x32_bf16 v[90:93], v[102:105], v[150:153], v[162:165]
	v_mfma_f32_16x16x32_bf16 v[102:105], v[236:239], v[190:193], v[94:97]
	v_mfma_f32_16x16x32_bf16 v[94:97], v[240:243], v[186:189], v[170:173]
	v_mfma_f32_16x16x32_bf16 v[90:93], v[236:239], v[154:157], v[90:93]
	v_mfma_f32_16x16x32_bf16 v[94:97], v[244:247], v[190:193], v[94:97]
	s_setprio 0
	s_barrier
	s_and_saveexec_b64 s[0:1], s[58:59]
	s_cbranch_execz .LBB0_128
	s_barrier

; #define WAIT_V(n) asm volatile("s_waitcnt vmcnt(" #n ")" ::: "memory")
; #define BAR __builtin_amdgcn_s_barrier()
; template <bool OVL, bool PANEL = false, class Epi>
; __device__ __forceinline__ void gemm_phase(const bf16_t* __restrict__ A, long lda, const bf16_t* __restrict__ Bt, long ldb, int nM, int nN, int K,
;                                            const Epi& epi, bf16_t* shm, int w0) {
;     ...
;   if (have) { const int brow = pm * BM, bcol = pn * BM;
;     STAGE(SB(0, 0), Bt, ldb, boff, bcol, 0); STAGE(SA(0, 0), A, lda, aoff, brow, 0);
;     STAGE(SB(0, 1), Bt, ldb, boff, bcol + HALF, 0); STAGE(SA(0, 1), A, lda, aoff, brow + HALF, 0); }
;   for (int it = 0; have; ++it) {
;     const int brow = pm * BM, bcol = pn * BM;
;     f32x4 acc[2][2][4][2];
; #pragma unroll
;     for (int a0 = 0; a0 < 2; ++a0)
; #pragma unroll
;       for (int a1 = 0; a1 < 2; ++a1)
; #pragma unroll
;         for (int a2 = 0; a2 < 4; ++a2)
; #pragma unroll
;           for (int a3 = 0; a3 < 2; ++a3) acc[a0][a1][a2][a3] = (f32x4){0.f, 0.f, 0.f, 0.f};
;     bf16x8 At[4][2], B0[2][2], B1[2][2];
;     if (wr == 1) BAR;
;     WAIT_V(4); BAR;
;     STAGE(SB(1, 0), Bt, ldb, boff, bcol, 1); STAGE(SA(1, 0), A, lda, aoff, brow, 1); STAGE(SB(1, 1), Bt, ldb, boff, bcol + HALF, 1);
;     WAIT_V(6); BAR;
.LBB0_385:
	s_or_b64 exec, exec, s[6:7]
	s_lshl_b32 s6, s24, 8
	s_ashr_i32 s7, s6, 31
	s_lshl_b32 s2, s25, 8
	s_lshl_b64 s[8:9], s[6:7], 11
	v_readlane_b32 s80, v251, 49
	v_readlane_b32 s81, v251, 50
	s_add_u32 s8, s80, s8
	s_addc_u32 s9, s81, s9
	v_mov_b32_e32 v0, v131
	v_add_u32_e32 v142, s96, v130
	s_waitcnt vmcnt(4)
	s_barrier
	s_mov_b64 s[30:31], 0x80
	v_lshl_add_u64 v[2:3], s[8:9], 0, v[0:1]
	v_readfirstlane_b32 s10, v142
	v_add_u32_e32 v143, 0x2000, v142
	v_lshl_add_u64 v[4:5], v[2:3], 0, s[30:31]
	s_mov_b32 m0, s10
	v_readfirstlane_b32 s10, v143
	v_readlane_b32 s44, v252, 20
	global_load_lds_dwordx4 v[4:5], off
	s_mov_b32 m0, s10
	s_lshl_b64 s[10:11], s[2:3], 11
	v_readlane_b32 s50, v252, 26
	v_readlane_b32 s51, v252, 27
	s_add_u32 s10, s50, s10
	s_mov_b64 s[42:43], 0x20080
	s_addc_u32 s11, s51, s11
	s_or_b32 s28, s6, 0x80
	v_lshl_add_u64 v[2:3], v[2:3], 0, s[42:43]
	v_mov_b32_e32 v0, v131
	v_add_u32_e32 v144, 0x8000, v134
	s_ashr_i32 s29, s28, 31
	global_load_lds_dwordx4 v[2:3], off
	v_readfirstlane_b32 s18, v144
	v_lshl_add_u64 v[2:3], s[10:11], 0, v[0:1]
	v_add_u32_e32 v145, 0xa000, v134
	s_lshl_b64 s[28:29], s[28:29], 11
	v_lshl_add_u64 v[4:5], v[2:3], 0, s[30:31]
	s_mov_b32 m0, s18
	v_readfirstlane_b32 s18, v145
	s_add_u32 s28, s80, s28
	global_load_lds_dwordx4 v[4:5], off
	v_lshl_add_u64 v[2:3], v[2:3], 0, s[42:43]
	s_mov_b32 m0, s18
	s_addc_u32 s29, s81, s29
	v_mov_b32_e32 v0, v131
	v_add_u32_e32 v146, s75, v130
	global_load_lds_dwordx4 v[2:3], off
	v_readfirstlane_b32 s18, v146
	v_lshl_add_u64 v[2:3], s[28:29], 0, v[0:1]
	v_add_u32_e32 v147, 0x2000, v146
	v_lshl_add_u64 v[4:5], v[2:3], 0, s[30:31]
	s_mov_b32 m0, s18
	v_readfirstlane_b32 s18, v147
	global_load_lds_dwordx4 v[4:5], off
	v_lshl_add_u64 v[2:3], v[2:3], 0, s[42:43]
	s_mov_b32 m0, s18
	v_readlane_b32 s45, v252, 21
	global_load_lds_dwordx4 v[2:3], off
	s_waitcnt vmcnt(6)
	v_mov_b32_e32 v2, 0
	s_mov_b32 s18, -2
	s_mov_b64 vcc, 0
	v_mov_b32_e32 v3, v2
	v_mov_b32_e32 v4, v2
	v_mov_b32_e32 v5, v2
	v_mov_b32_e32 v6, v2
	v_mov_b32_e32 v7, v2
	v_mov_b32_e32 v8, v2
	v_mov_b32_e32 v9, v2
	s_waitcnt vmcnt(0)
	v_mov_b32_e32 v10, v2
	v_mov_b32_e32 v11, v2
	v_mov_b32_e32 v12, v2
	v_mov_b32_e32 v13, v2
	s_waitcnt lgkmcnt(0)
	v_mov_b32_e32 v14, v2
	v_mov_b32_e32 v15, v2
	v_mov_b32_e32 v16, v2
	v_mov_b32_e32 v17, v2
	v_mov_b32_e32 v18, v2
	v_mov_b32_e32 v19, v2
	v_mov_b32_e32 v20, v2
	v_mov_b32_e32 v21, v2
	v_mov_b32_e32 v22, v2
	v_mov_b32_e32 v23, v2
	v_mov_b32_e32 v24, v2
	v_mov_b32_e32 v25, v2
	v_mov_b32_e32 v26, v2
	v_mov_b32_e32 v27, v2
	v_mov_b32_e32 v28, v2
	v_mov_b32_e32 v29, v2
	v_mov_b32_e32 v30, v2
	v_mov_b32_e32 v31, v2
	v_mov_b32_e32 v32, v2
	v_mov_b32_e32 v33, v2
	v_mov_b32_e32 v34, v2
	v_mov_b32_e32 v35, v2
	v_mov_b32_e32 v36, v2
	v_mov_b32_e32 v37, v2
	v_mov_b32_e32 v38, v2
	v_mov_b32_e32 v39, v2
	v_mov_b32_e32 v40, v2
	v_mov_b32_e32 v41, v2
	v_mov_b32_e32 v42, v2
	v_mov_b32_e32 v43, v2
	v_mov_b32_e32 v44, v2
	v_mov_b32_e32 v45, v2
	v_mov_b32_e32 v46, v2
	v_mov_b32_e32 v47, v2
	v_mov_b32_e32 v48, v2
	v_mov_b32_e32 v49, v2
	v_mov_b32_e32 v50, v2
	v_mov_b32_e32 v51, v2
	v_mov_b32_e32 v52, v2
	v_mov_b32_e32 v53, v2
	v_mov_b32_e32 v54, v2
	v_mov_b32_e32 v55, v2
	v_mov_b32_e32 v56, v2
	v_mov_b32_e32 v57, v2
	v_mov_b32_e32 v58, v2
	v_mov_b32_e32 v59, v2
	v_mov_b32_e32 v60, v2
	v_mov_b32_e32 v61, v2
	v_mov_b32_e32 v62, v2
	v_mov_b32_e32 v63, v2
	v_mov_b32_e32 v64, v2
	v_mov_b32_e32 v65, v2
	v_mov_b32_e32 v66, v2
	v_mov_b32_e32 v67, v2
	v_mov_b32_e32 v68, v2
	v_mov_b32_e32 v69, v2
	v_mov_b32_e32 v70, v2
	v_mov_b32_e32 v71, v2
	v_mov_b32_e32 v72, v2
	v_mov_b32_e32 v73, v2
	v_mov_b32_e32 v74, v2
	v_mov_b32_e32 v75, v2
	v_mov_b32_e32 v76, v2
	v_mov_b32_e32 v77, v2
	v_mov_b32_e32 v78, v2
	v_mov_b32_e32 v79, v2
	v_mov_b32_e32 v80, v2
	v_mov_b32_e32 v81, v2
	v_mov_b32_e32 v82, v2
	v_mov_b32_e32 v83, v2
	v_mov_b32_e32 v84, v2
	v_mov_b32_e32 v85, v2
	v_mov_b32_e32 v86, v2
	v_mov_b32_e32 v87, v2
	v_mov_b32_e32 v88, v2
	v_mov_b32_e32 v89, v2
	v_mov_b32_e32 v90, v2
	v_mov_b32_e32 v91, v2
	v_mov_b32_e32 v92, v2
	v_mov_b32_e32 v93, v2
	v_mov_b32_e32 v94, v2
	v_mov_b32_e32 v95, v2
	v_mov_b32_e32 v96, v2
	v_mov_b32_e32 v97, v2
	v_mov_b32_e32 v98, v2
	v_mov_b32_e32 v99, v2
	v_mov_b32_e32 v100, v2
	v_mov_b32_e32 v101, v2
	v_mov_b32_e32 v102, v2
	v_mov_b32_e32 v103, v2
	v_mov_b32_e32 v104, v2
	v_mov_b32_e32 v105, v2
	v_mov_b32_e32 v106, v2
	v_mov_b32_e32 v107, v2
	v_mov_b32_e32 v108, v2
	v_mov_b32_e32 v109, v2
	v_mov_b32_e32 v110, v2
	v_mov_b32_e32 v111, v2
	v_mov_b32_e32 v112, v2
	v_mov_b32_e32 v113, v2
	v_mov_b32_e32 v114, v2
	v_mov_b32_e32 v115, v2
	v_mov_b32_e32 v116, v2
	v_mov_b32_e32 v117, v2
	v_mov_b32_e32 v118, v2
	v_mov_b32_e32 v119, v2
	v_mov_b32_e32 v120, v2
	v_mov_b32_e32 v121, v2
	v_mov_b32_e32 v122, v2
	v_mov_b32_e32 v123, v2
	v_mov_b32_e32 v124, v2
	v_mov_b32_e32 v125, v2
	v_mov_b32_e32 v126, v2
	v_mov_b32_e32 v127, v2
	v_mov_b32_e32 v128, v2
	v_mov_b32_e32 v129, v2
	s_mov_b64 s[28:29], 0x40080
	s_mov_b64 s[30:31], 0x40180
	s_mov_b64 s[44:45], 0x60180
	v_readlane_b32 s82, v251, 51
	v_readlane_b32 s83, v251, 52
	v_readlane_b32 s84, v251, 53
	v_readlane_b32 s85, v251, 54
	v_readlane_b32 s86, v251, 55
	v_readlane_b32 s87, v251, 56
	v_readlane_b32 s46, v252, 22
	v_readlane_b32 s47, v252, 23
	v_readlane_b32 s48, v252, 24
	v_readlane_b32 s49, v252, 25
	v_readlane_b32 s52, v252, 28
	v_readlane_b32 s53, v252, 29
	v_readlane_b32 s54, v252, 30
	v_readlane_b32 s55, v252, 31
	v_readlane_b32 s56, v252, 32
	v_readlane_b32 s57, v252, 33
	v_readlane_b32 s58, v252, 34
	v_readlane_b32 s59, v252, 35
	s_barrier
	v_add_u32_e32 v218, s21, v140
	v_readfirstlane_b32 s16, v134
	s_add_u32 s16, s16, 0xc000
	v_readfirstlane_b32 s32, v134
	s_add_u32 s32, s32, 0xe000
	v_add_u32_e32 v219, s33, v140
	v_readfirstlane_b32 s46, v132
	v_readfirstlane_b32 s47, v133
	v_readfirstlane_b32 s48, v134
	v_readfirstlane_b32 s49, v135
	v_readfirstlane_b32 s50, v136
	v_readfirstlane_b32 s51, v137
	v_add_u32_e32 v220, s96, v140
	v_readfirstlane_b32 s52, v138
	v_readfirstlane_b32 s53, v139
	v_add_u32_e32 v221, s75, v140
	v_readfirstlane_b32 s54, v142
	v_readfirstlane_b32 s55, v143
	v_readfirstlane_b32 s56, v144
	v_readfirstlane_b32 s57, v145
	v_readfirstlane_b32 s58, v146
	v_readfirstlane_b32 s59, v147
	v_add_u32_e32 v148, 0xc000, v134
	v_add_u32_e32 v149, 0xe000, v134
; #define LDA(dst, b, h) for (int m = 0; m < 4; ++m) for (int k = 0; k < 2; ++k) \
;     dst[m][k] = *reinterpret_cast<const bf16x8*>((char*)SA(b, h) + a_thr + (m * 2 + k) * 1024)
; #define LDB(dst, b, h) for (int n = 0; n < 2; ++n) for (int k = 0; k < 2; ++k) \
;     dst[n][k] = *reinterpret_cast<const bf16x8*>((char*)SB(b, h) + b_thr + (n * 2 + k) * 1024)
; #define MMA(ai, bj, At, Btf) do { __builtin_amdgcn_s_setprio(1); \
;     for (int m = 0; m < 4; ++m) for (int n = 0; n < 2; ++n) for (int k = 0; k < 2; ++k) \
;       acc[ai][bj][m][n] = __builtin_amdgcn_mfma_f32_16x16x32_bf16(Btf[n][k], At[m][k], acc[ai][bj][m][n], 0, 0, 0); \
;     __builtin_amdgcn_s_setprio(0); } while (0)
; #define WAIT_V(n) asm volatile("s_waitcnt vmcnt(" #n ")" ::: "memory")
; #define WAIT_L(n) asm volatile("s_waitcnt lgkmcnt(" #n ")" ::: "memory")
; #define BAR __builtin_amdgcn_s_barrier()
; #define SCHED __builtin_amdgcn_sched_barrier(0)
; template <bool OVL, bool PANEL = false, class Epi>
; __device__ __forceinline__ void gemm_phase(const bf16_t* __restrict__ A, long lda, const bf16_t* __restrict__ Bt, long ldb, int nM, int nN, int K,
;                                            const Epi& epi, bf16_t* shm, int w0) {
;     ...
;     for (int t = 0; t < nt - 2; t += 2) {
;       LDB(B0, 0, 0); SCHED; LDA(At, 0, 0); STAGE(SA(1, 1), A, lda, aoff, brow + HALF, t + 1);
;       WAIT_L(8); BAR; WAIT_L(0); MMA(0, 0, At, B0); BAR; SCHED;
;       LDB(B1, 0, 1); STAGE(SB(0, 0), Bt, ldb, boff, bcol, t + 2);
;       BAR; WAIT_L(0); MMA(0, 1, At, B1); BAR;
;       LDA(At, 0, 1); STAGE(SA(0, 0), A, lda, aoff, brow, t + 2);
;       BAR; WAIT_L(0); MMA(1, 0, At, B0); BAR; SCHED;
;       STAGE(SB(0, 1), Bt, ldb, boff, bcol + HALF, t + 2);
;       WAIT_V(6); BAR; MMA(1, 1, At, B1); BAR;
.LBB0_386:
	ds_read_b128 v[150:153], v218
	ds_read_b128 v[154:157], v218 offset:1024
	ds_read_b128 v[158:161], v218 offset:2048
	ds_read_b128 v[162:165], v218 offset:3072
	s_add_u32 s42, s10, vcc_lo
	s_addc_u32 s43, s11, vcc_hi
	ds_read_b128 v[166:169], v141
	ds_read_b128 v[170:173], v141 offset:1024
	ds_read_b128 v[174:177], v141 offset:2048
	ds_read_b128 v[178:181], v141 offset:3072
	ds_read_b128 v[182:185], v141 offset:4096
	ds_read_b128 v[186:189], v141 offset:5120
	ds_read_b128 v[190:193], v141 offset:6144
	ds_read_b128 v[194:197], v141 offset:7168
	s_mov_b32 m0, s16
	s_add_u32 s98, s42, s28
	s_addc_u32 s99, s43, s29
	global_load_lds_dwordx4 v131, s[98:99]
	s_mov_b32 m0, s32
	s_add_u32 s98, s42, s36
	s_addc_u32 s99, s43, s37
	global_load_lds_dwordx4 v131, s[98:99]
	s_waitcnt lgkmcnt(8)
	s_barrier
	s_waitcnt lgkmcnt(0)
	s_setprio 1
	s_waitcnt lgkmcnt(0)
	v_mfma_f32_16x16x32_bf16 v[126:129], v[150:153], v[166:169], v[126:129]
	v_mfma_f32_16x16x32_bf16 v[122:125], v[158:161], v[166:169], v[122:125]
	v_mfma_f32_16x16x32_bf16 v[118:121], v[150:153], v[174:177], v[118:121]
	v_mfma_f32_16x16x32_bf16 v[114:117], v[158:161], v[174:177], v[114:117]
	v_mfma_f32_16x16x32_bf16 v[110:113], v[150:153], v[182:185], v[110:113]
	v_mfma_f32_16x16x32_bf16 v[106:109], v[158:161], v[182:185], v[106:109]
	v_mfma_f32_16x16x32_bf16 v[102:105], v[150:153], v[190:193], v[102:105]
	v_mfma_f32_16x16x32_bf16 v[98:101], v[158:161], v[190:193], v[98:101]
	v_mfma_f32_16x16x32_bf16 v[126:129], v[154:157], v[170:173], v[126:129]
	v_mfma_f32_16x16x32_bf16 v[122:125], v[162:165], v[170:173], v[122:125]
	v_mfma_f32_16x16x32_bf16 v[118:121], v[154:157], v[178:181], v[118:121]
	v_mfma_f32_16x16x32_bf16 v[114:117], v[162:165], v[178:181], v[114:117]
	v_mfma_f32_16x16x32_bf16 v[110:113], v[154:157], v[186:189], v[110:113]
	v_mfma_f32_16x16x32_bf16 v[106:109], v[162:165], v[186:189], v[106:109]
	v_mfma_f32_16x16x32_bf16 v[102:105], v[154:157], v[194:197], v[102:105]
	v_mfma_f32_16x16x32_bf16 v[98:101], v[162:165], v[194:197], v[98:101]
	s_setprio 0
	s_barrier
	s_add_u32 s66, s8, vcc_lo
	ds_read_b128 v[198:201], v219
	ds_read_b128 v[202:205], v219 offset:1024
	ds_read_b128 v[206:209], v219 offset:2048
	ds_read_b128 v[210:213], v219 offset:3072
	s_addc_u32 s67, s9, vcc_hi
	s_mov_b32 m0, s46
	s_add_u32 s98, s66, s34
	s_addc_u32 s99, s67, s35
	global_load_lds_dwordx4 v131, s[98:99]
	s_mov_b32 m0, s47
	s_add_u32 s98, s66, s64
	s_addc_u32 s99, s67, s65
	global_load_lds_dwordx4 v131, s[98:99]
	s_barrier
	s_waitcnt lgkmcnt(0)
	s_setprio 1
	s_waitcnt lgkmcnt(0)
	v_mfma_f32_16x16x32_bf16 v[94:97], v[198:201], v[166:169], v[94:97]
	v_mfma_f32_16x16x32_bf16 v[90:93], v[206:209], v[166:169], v[90:93]
	v_mfma_f32_16x16x32_bf16 v[86:89], v[198:201], v[174:177], v[86:89]
	v_mfma_f32_16x16x32_bf16 v[82:85], v[206:209], v[174:177], v[82:85]
	v_mfma_f32_16x16x32_bf16 v[78:81], v[198:201], v[182:185], v[78:81]
	v_mfma_f32_16x16x32_bf16 v[74:77], v[206:209], v[182:185], v[74:77]
	v_mfma_f32_16x16x32_bf16 v[70:73], v[198:201], v[190:193], v[70:73]
	v_mfma_f32_16x16x32_bf16 v[66:69], v[206:209], v[190:193], v[66:69]
	v_mfma_f32_16x16x32_bf16 v[94:97], v[202:205], v[170:173], v[94:97]
	v_mfma_f32_16x16x32_bf16 v[90:93], v[210:213], v[170:173], v[90:93]
	v_mfma_f32_16x16x32_bf16 v[86:89], v[202:205], v[178:181], v[86:89]
	v_mfma_f32_16x16x32_bf16 v[82:85], v[210:213], v[178:181], v[82:85]
	v_mfma_f32_16x16x32_bf16 v[78:81], v[202:205], v[186:189], v[78:81]
	v_mfma_f32_16x16x32_bf16 v[74:77], v[210:213], v[186:189], v[74:77]
	v_mfma_f32_16x16x32_bf16 v[70:73], v[202:205], v[194:197], v[70:73]
	v_mfma_f32_16x16x32_bf16 v[66:69], v[210:213], v[194:197], v[66:69]
	s_setprio 0
	s_barrier
	ds_read_b128 v[166:169], v141 offset:16384
	ds_read_b128 v[170:173], v141 offset:17408
	ds_read_b128 v[174:177], v141 offset:18432
	ds_read_b128 v[178:181], v141 offset:19456
	ds_read_b128 v[182:185], v141 offset:20480
	ds_read_b128 v[186:189], v141 offset:21504
	ds_read_b128 v[190:193], v141 offset:22528
	ds_read_b128 v[194:197], v141 offset:23552
	s_mov_b32 m0, s48
	s_add_u32 s98, s42, s34
	s_addc_u32 s99, s43, s35
	global_load_lds_dwordx4 v131, s[98:99]
	s_mov_b32 m0, s49
	s_add_u32 s98, s42, s64
	s_addc_u32 s99, s43, s65
	global_load_lds_dwordx4 v131, s[98:99]
	s_barrier
	s_waitcnt lgkmcnt(0)
	s_setprio 1
	s_waitcnt lgkmcnt(0)
	v_mfma_f32_16x16x32_bf16 v[62:65], v[150:153], v[166:169], v[62:65]
	v_mfma_f32_16x16x32_bf16 v[58:61], v[158:161], v[166:169], v[58:61]
	v_mfma_f32_16x16x32_bf16 v[54:57], v[150:153], v[174:177], v[54:57]
	v_mfma_f32_16x16x32_bf16 v[50:53], v[158:161], v[174:177], v[50:53]
	v_mfma_f32_16x16x32_bf16 v[46:49], v[150:153], v[182:185], v[46:49]
	v_mfma_f32_16x16x32_bf16 v[42:45], v[158:161], v[182:185], v[42:45]
	v_mfma_f32_16x16x32_bf16 v[38:41], v[150:153], v[190:193], v[38:41]
	v_mfma_f32_16x16x32_bf16 v[34:37], v[158:161], v[190:193], v[34:37]
	v_mfma_f32_16x16x32_bf16 v[62:65], v[154:157], v[170:173], v[62:65]
	v_mfma_f32_16x16x32_bf16 v[58:61], v[162:165], v[170:173], v[58:61]
	v_mfma_f32_16x16x32_bf16 v[54:57], v[154:157], v[178:181], v[54:57]
	v_mfma_f32_16x16x32_bf16 v[50:53], v[162:165], v[178:181], v[50:53]
	v_mfma_f32_16x16x32_bf16 v[46:49], v[154:157], v[186:189], v[46:49]
	v_mfma_f32_16x16x32_bf16 v[42:45], v[162:165], v[186:189], v[42:45]
	v_mfma_f32_16x16x32_bf16 v[38:41], v[154:157], v[194:197], v[38:41]
	v_mfma_f32_16x16x32_bf16 v[34:37], v[162:165], v[194:197], v[34:37]
	s_setprio 0
	s_barrier
	s_mov_b32 m0, s50
	s_add_u32 s98, s66, s68
	s_addc_u32 s99, s67, s69
	global_load_lds_dwordx4 v131, s[98:99]
	s_mov_b32 m0, s51
	s_add_u32 s98, s66, s70
	s_addc_u32 s99, s67, s71
	global_load_lds_dwordx4 v131, s[98:99]
	s_waitcnt vmcnt(6)
	s_barrier
; #define LDA(dst, b, h) for (int m = 0; m < 4; ++m) for (int k = 0; k < 2; ++k) \
;     dst[m][k] = *reinterpret_cast<const bf16x8*>((char*)SA(b, h) + a_thr + (m * 2 + k) * 1024)
; #define LDB(dst, b, h) for (int n = 0; n < 2; ++n) for (int k = 0; k < 2; ++k) \
;     dst[n][k] = *reinterpret_cast<const bf16x8*>((char*)SB(b, h) + b_thr + (n * 2 + k) * 1024)
; #define MMA(ai, bj, At, Btf) do { __builtin_amdgcn_s_setprio(1); \
;     for (int m = 0; m < 4; ++m) for (int n = 0; n < 2; ++n) for (int k = 0; k < 2; ++k) \
;       acc[ai][bj][m][n] = __builtin_amdgcn_mfma_f32_16x16x32_bf16(Btf[n][k], At[m][k], acc[ai][bj][m][n], 0, 0, 0); \
;     __builtin_amdgcn_s_setprio(0); } while (0)
; #define WAIT_V(n) asm volatile("s_waitcnt vmcnt(" #n ")" ::: "memory")
; #define WAIT_L(n) asm volatile("s_waitcnt lgkmcnt(" #n ")" ::: "memory")
; #define BAR __builtin_amdgcn_s_barrier()
; #define SCHED __builtin_amdgcn_sched_barrier(0)
; template <bool OVL, bool PANEL = false, class Epi>
; __device__ __forceinline__ void gemm_phase(const bf16_t* __restrict__ A, long lda, const bf16_t* __restrict__ Bt, long ldb, int nM, int nN, int K,
;                                            const Epi& epi, bf16_t* shm, int w0) {
;     ...
;       WAIT_V(6); BAR; MMA(1, 1, At, B1); BAR;
;       LDB(B0, 1, 0); SCHED; LDA(At, 1, 0); STAGE(SA(0, 1), A, lda, aoff, brow + HALF, t + 2);
;       WAIT_L(8); BAR; WAIT_L(0); MMA(0, 0, At, B0); BAR; SCHED;
;       LDB(B1, 1, 1); STAGE(SB(1, 0), Bt, ldb, boff, bcol, t + 3);
;       BAR; WAIT_L(0); MMA(0, 1, At, B1); BAR;
;       LDA(At, 1, 1); STAGE(SA(1, 0), A, lda, aoff, brow, t + 3);
	s_setprio 1
	v_mfma_f32_16x16x32_bf16 v[30:33], v[198:201], v[166:169], v[30:33]
	v_mfma_f32_16x16x32_bf16 v[26:29], v[206:209], v[166:169], v[26:29]
	v_mfma_f32_16x16x32_bf16 v[22:25], v[198:201], v[174:177], v[22:25]
	v_mfma_f32_16x16x32_bf16 v[18:21], v[206:209], v[174:177], v[18:21]
	v_mfma_f32_16x16x32_bf16 v[14:17], v[198:201], v[182:185], v[14:17]
	v_mfma_f32_16x16x32_bf16 v[10:13], v[206:209], v[182:185], v[10:13]
	v_mfma_f32_16x16x32_bf16 v[6:9], v[198:201], v[190:193], v[6:9]
	v_mfma_f32_16x16x32_bf16 v[2:5], v[206:209], v[190:193], v[2:5]
	v_mfma_f32_16x16x32_bf16 v[30:33], v[202:205], v[170:173], v[30:33]
	v_mfma_f32_16x16x32_bf16 v[26:29], v[210:213], v[170:173], v[26:29]
	v_mfma_f32_16x16x32_bf16 v[22:25], v[202:205], v[178:181], v[22:25]
	v_mfma_f32_16x16x32_bf16 v[18:21], v[210:213], v[178:181], v[18:21]
	v_mfma_f32_16x16x32_bf16 v[14:17], v[202:205], v[186:189], v[14:17]
	v_mfma_f32_16x16x32_bf16 v[10:13], v[210:213], v[186:189], v[10:13]
	v_mfma_f32_16x16x32_bf16 v[6:9], v[202:205], v[194:197], v[6:9]
	v_mfma_f32_16x16x32_bf16 v[2:5], v[210:213], v[194:197], v[2:5]
	s_setprio 0
	s_barrier
	ds_read_b128 v[150:153], v220
	ds_read_b128 v[154:157], v220 offset:1024
	ds_read_b128 v[158:161], v220 offset:2048
	ds_read_b128 v[162:165], v220 offset:3072
	ds_read_b128 v[166:169], v141 offset:32768
	ds_read_b128 v[170:173], v141 offset:33792
	ds_read_b128 v[174:177], v141 offset:34816
	ds_read_b128 v[178:181], v141 offset:35840
	ds_read_b128 v[182:185], v141 offset:36864
	ds_read_b128 v[186:189], v141 offset:37888
	ds_read_b128 v[190:193], v141 offset:38912
	ds_read_b128 v[194:197], v141 offset:39936
	s_mov_b32 m0, s52
	s_add_u32 s98, s42, s68
	s_addc_u32 s99, s43, s69
	global_load_lds_dwordx4 v131, s[98:99]
	s_mov_b32 m0, s53
	s_add_u32 s98, s42, s70
	s_addc_u32 s99, s43, s71
	global_load_lds_dwordx4 v131, s[98:99]
	s_waitcnt lgkmcnt(8)
	s_barrier
	s_waitcnt lgkmcnt(0)
	s_setprio 1
	s_waitcnt lgkmcnt(0)
	v_mfma_f32_16x16x32_bf16 v[126:129], v[150:153], v[166:169], v[126:129]
	v_mfma_f32_16x16x32_bf16 v[122:125], v[158:161], v[166:169], v[122:125]
	v_mfma_f32_16x16x32_bf16 v[118:121], v[150:153], v[174:177], v[118:121]
	v_mfma_f32_16x16x32_bf16 v[114:117], v[158:161], v[174:177], v[114:117]
	v_mfma_f32_16x16x32_bf16 v[110:113], v[150:153], v[182:185], v[110:113]
	v_mfma_f32_16x16x32_bf16 v[106:109], v[158:161], v[182:185], v[106:109]
	v_mfma_f32_16x16x32_bf16 v[102:105], v[150:153], v[190:193], v[102:105]
	v_mfma_f32_16x16x32_bf16 v[98:101], v[158:161], v[190:193], v[98:101]
	v_mfma_f32_16x16x32_bf16 v[126:129], v[154:157], v[170:173], v[126:129]
	v_mfma_f32_16x16x32_bf16 v[122:125], v[162:165], v[170:173], v[122:125]
	v_mfma_f32_16x16x32_bf16 v[118:121], v[154:157], v[178:181], v[118:121]
	v_mfma_f32_16x16x32_bf16 v[114:117], v[162:165], v[178:181], v[114:117]
	v_mfma_f32_16x16x32_bf16 v[110:113], v[154:157], v[186:189], v[110:113]
	v_mfma_f32_16x16x32_bf16 v[106:109], v[162:165], v[186:189], v[106:109]
	v_mfma_f32_16x16x32_bf16 v[102:105], v[154:157], v[194:197], v[102:105]
	v_mfma_f32_16x16x32_bf16 v[98:101], v[162:165], v[194:197], v[98:101]
	s_setprio 0
	s_barrier
	ds_read_b128 v[198:201], v221
	ds_read_b128 v[202:205], v221 offset:1024
	ds_read_b128 v[206:209], v221 offset:2048
	ds_read_b128 v[210:213], v221 offset:3072
	s_mov_b32 m0, s54
	s_add_u32 s98, s66, s94
	s_addc_u32 s99, s67, s95
	global_load_lds_dwordx4 v131, s[98:99]
	s_mov_b32 m0, s55
	s_add_u32 s98, s66, s72
	s_addc_u32 s99, s67, s73
	global_load_lds_dwordx4 v131, s[98:99]
	s_barrier
	s_waitcnt lgkmcnt(0)
	s_setprio 1
	s_waitcnt lgkmcnt(0)
	v_mfma_f32_16x16x32_bf16 v[94:97], v[198:201], v[166:169], v[94:97]
	v_mfma_f32_16x16x32_bf16 v[90:93], v[206:209], v[166:169], v[90:93]
	v_mfma_f32_16x16x32_bf16 v[86:89], v[198:201], v[174:177], v[86:89]
	v_mfma_f32_16x16x32_bf16 v[82:85], v[206:209], v[174:177], v[82:85]
	v_mfma_f32_16x16x32_bf16 v[78:81], v[198:201], v[182:185], v[78:81]
	v_mfma_f32_16x16x32_bf16 v[74:77], v[206:209], v[182:185], v[74:77]
	v_mfma_f32_16x16x32_bf16 v[70:73], v[198:201], v[190:193], v[70:73]
	v_mfma_f32_16x16x32_bf16 v[66:69], v[206:209], v[190:193], v[66:69]
	v_mfma_f32_16x16x32_bf16 v[94:97], v[202:205], v[170:173], v[94:97]
	v_mfma_f32_16x16x32_bf16 v[90:93], v[210:213], v[170:173], v[90:93]
	v_mfma_f32_16x16x32_bf16 v[86:89], v[202:205], v[178:181], v[86:89]
	v_mfma_f32_16x16x32_bf16 v[82:85], v[210:213], v[178:181], v[82:85]
	v_mfma_f32_16x16x32_bf16 v[78:81], v[202:205], v[186:189], v[78:81]
	v_mfma_f32_16x16x32_bf16 v[74:77], v[210:213], v[186:189], v[74:77]
	v_mfma_f32_16x16x32_bf16 v[70:73], v[202:205], v[194:197], v[70:73]
	v_mfma_f32_16x16x32_bf16 v[66:69], v[210:213], v[194:197], v[66:69]
	s_setprio 0
	s_barrier
	ds_read_b128 v[166:169], v141 offset:49152
	ds_read_b128 v[170:173], v141 offset:50176
	ds_read_b128 v[174:177], v141 offset:51200
	ds_read_b128 v[178:181], v141 offset:52224
	ds_read_b128 v[182:185], v141 offset:53248
	ds_read_b128 v[186:189], v141 offset:54272
	ds_read_b128 v[190:193], v141 offset:55296
	ds_read_b128 v[194:197], v141 offset:56320
	s_mov_b32 m0, s56
	s_add_u32 s98, s42, s94
	s_addc_u32 s99, s43, s95
	global_load_lds_dwordx4 v131, s[98:99]
	s_mov_b32 m0, s57
	s_add_u32 s98, s42, s72
	s_addc_u32 s99, s43, s73
	global_load_lds_dwordx4 v131, s[98:99]
	s_barrier
; #define LDA(dst, b, h) for (int m = 0; m < 4; ++m) for (int k = 0; k < 2; ++k) \
;     dst[m][k] = *reinterpret_cast<const bf16x8*>((char*)SA(b, h) + a_thr + (m * 2 + k) * 1024)
; #define LDB(dst, b, h) for (int n = 0; n < 2; ++n) for (int k = 0; k < 2; ++k) \
;     dst[n][k] = *reinterpret_cast<const bf16x8*>((char*)SB(b, h) + b_thr + (n * 2 + k) * 1024)
; #define MMA(ai, bj, At, Btf) do { __builtin_amdgcn_s_setprio(1); \
;     for (int m = 0; m < 4; ++m) for (int n = 0; n < 2; ++n) for (int k = 0; k < 2; ++k) \
;       acc[ai][bj][m][n] = __builtin_amdgcn_mfma_f32_16x16x32_bf16(Btf[n][k], At[m][k], acc[ai][bj][m][n], 0, 0, 0); \
;     __builtin_amdgcn_s_setprio(0); } while (0)
; #define WAIT_V(n) asm volatile("s_waitcnt vmcnt(" #n ")" ::: "memory")
; #define WAIT_L(n) asm volatile("s_waitcnt lgkmcnt(" #n ")" ::: "memory")
; #define BAR __builtin_amdgcn_s_barrier()
; #define SCHED __builtin_amdgcn_sched_barrier(0)
; template <bool OVL, bool PANEL = false, class Epi>
; __device__ __forceinline__ void gemm_phase(const bf16_t* __restrict__ A, long lda, const bf16_t* __restrict__ Bt, long ldb, int nM, int nN, int K,
;                                            const Epi& epi, bf16_t* shm, int w0) {
;     ...
;       BAR; WAIT_L(0); MMA(1, 0, At, B0); BAR; SCHED;
;       STAGE(SB(1, 1), Bt, ldb, boff, bcol + HALF, t + 3);
;       WAIT_V(6); BAR; MMA(1, 1, At, B1); BAR;
;     }
;     { LDB(B0, 0, 0); LDA(At, 0, 0); STAGE(SA(1, 1), A, lda, aoff, brow + HALF, nt - 1);
;       BAR; WAIT_L(0); MMA(0, 0, At, B0); BAR;
;       LDB(B1, 0, 1); BAR; WAIT_L(0); MMA(0, 1, At, B1); BAR;
;       LDA(At, 0, 1); WAIT_V(4); BAR; WAIT_L(0); MMA(1, 0, At, B0); MMA(1, 1, At, B1); BAR; }
	s_waitcnt lgkmcnt(0)
	s_setprio 1
	s_waitcnt lgkmcnt(0)
	v_mfma_f32_16x16x32_bf16 v[62:65], v[150:153], v[166:169], v[62:65]
	v_mfma_f32_16x16x32_bf16 v[58:61], v[158:161], v[166:169], v[58:61]
	v_mfma_f32_16x16x32_bf16 v[54:57], v[150:153], v[174:177], v[54:57]
	v_mfma_f32_16x16x32_bf16 v[50:53], v[158:161], v[174:177], v[50:53]
	v_mfma_f32_16x16x32_bf16 v[46:49], v[150:153], v[182:185], v[46:49]
	v_mfma_f32_16x16x32_bf16 v[42:45], v[158:161], v[182:185], v[42:45]
	v_mfma_f32_16x16x32_bf16 v[38:41], v[150:153], v[190:193], v[38:41]
	v_mfma_f32_16x16x32_bf16 v[34:37], v[158:161], v[190:193], v[34:37]
	v_mfma_f32_16x16x32_bf16 v[62:65], v[154:157], v[170:173], v[62:65]
	v_mfma_f32_16x16x32_bf16 v[58:61], v[162:165], v[170:173], v[58:61]
	v_mfma_f32_16x16x32_bf16 v[54:57], v[154:157], v[178:181], v[54:57]
	v_mfma_f32_16x16x32_bf16 v[50:53], v[162:165], v[178:181], v[50:53]
	v_mfma_f32_16x16x32_bf16 v[46:49], v[154:157], v[186:189], v[46:49]
	v_mfma_f32_16x16x32_bf16 v[42:45], v[162:165], v[186:189], v[42:45]
	v_mfma_f32_16x16x32_bf16 v[38:41], v[154:157], v[194:197], v[38:41]
	v_mfma_f32_16x16x32_bf16 v[34:37], v[162:165], v[194:197], v[34:37]
	s_setprio 0
	s_barrier
	s_mov_b32 m0, s58
	s_add_u32 s98, s66, s30
	s_addc_u32 s99, s67, s31
	global_load_lds_dwordx4 v131, s[98:99]
	s_mov_b32 m0, s59
	s_add_u32 s98, s66, s44
	s_addc_u32 s99, s67, s45
	global_load_lds_dwordx4 v131, s[98:99]
	s_waitcnt vmcnt(6)
	s_barrier
	s_setprio 1
	v_mfma_f32_16x16x32_bf16 v[30:33], v[198:201], v[166:169], v[30:33]
	v_mfma_f32_16x16x32_bf16 v[26:29], v[206:209], v[166:169], v[26:29]
	v_mfma_f32_16x16x32_bf16 v[22:25], v[198:201], v[174:177], v[22:25]
	v_mfma_f32_16x16x32_bf16 v[18:21], v[206:209], v[174:177], v[18:21]
	v_mfma_f32_16x16x32_bf16 v[14:17], v[198:201], v[182:185], v[14:17]
	v_mfma_f32_16x16x32_bf16 v[10:13], v[206:209], v[182:185], v[10:13]
	v_mfma_f32_16x16x32_bf16 v[6:9], v[198:201], v[190:193], v[6:9]
	v_mfma_f32_16x16x32_bf16 v[2:5], v[206:209], v[190:193], v[2:5]
	v_mfma_f32_16x16x32_bf16 v[30:33], v[202:205], v[170:173], v[30:33]
	v_mfma_f32_16x16x32_bf16 v[26:29], v[210:213], v[170:173], v[26:29]
	v_mfma_f32_16x16x32_bf16 v[22:25], v[202:205], v[178:181], v[22:25]
	v_mfma_f32_16x16x32_bf16 v[18:21], v[210:213], v[178:181], v[18:21]
	v_mfma_f32_16x16x32_bf16 v[14:17], v[202:205], v[186:189], v[14:17]
	v_mfma_f32_16x16x32_bf16 v[10:13], v[210:213], v[186:189], v[10:13]
	v_mfma_f32_16x16x32_bf16 v[6:9], v[202:205], v[194:197], v[6:9]
	v_mfma_f32_16x16x32_bf16 v[2:5], v[210:213], v[194:197], v[2:5]
	s_setprio 0
	s_add_i32 s18, s18, 2
	s_add_u32 vcc_lo, vcc_lo, 0x100
	s_addc_u32 vcc_hi, vcc_hi, 0
	s_cmp_lt_u32 s18, 12
	s_barrier
	s_cbranch_scc1 .LBB0_386
	s_or_b32 s8, s2, 0x80
	s_mov_b32 s9, s3
	v_readlane_b32 s44, v252, 20
	s_lshl_b64 s[8:9], s[8:9], 11
	v_readlane_b32 s50, v252, 26
	v_add_u32_e32 v214, 16, v140
	v_readlane_b32 s51, v252, 27
	s_add_u32 s8, s50, s8
	v_add_u32_e32 v0, 0x10000, v214
	s_addc_u32 s9, s51, s9
	ds_read_b128 v[142:145], v0
	ds_read_b128 v[150:153], v0 offset:1024
	ds_read_b128 v[154:157], v0 offset:2048
	ds_read_b128 v[158:161], v0 offset:3072
	ds_read_b128 v[162:165], v141
	ds_read_b128 v[166:169], v141 offset:1024
	ds_read_b128 v[170:173], v141 offset:2048
	ds_read_b128 v[174:177], v141 offset:3072
	ds_read_b128 v[178:181], v141 offset:4096
	ds_read_b128 v[182:185], v141 offset:5120
	ds_read_b128 v[186:189], v141 offset:6144
	ds_read_b128 v[190:193], v141 offset:7168
	v_mov_b32_e32 v0, v131
	v_readlane_b32 s45, v252, 21
	v_lshl_add_u64 v[146:147], s[8:9], 0, v[0:1]
	s_mov_b64 s[8:9], 0x780
	v_lshl_add_u64 v[194:195], v[146:147], 0, s[8:9]
	v_readfirstlane_b32 s8, v148
	s_mov_b32 m0, s8
	s_mov_b64 s[8:9], 0x20780
	v_lshl_add_u64 v[146:147], v[146:147], 0, s[8:9]
	v_readfirstlane_b32 s8, v149
	global_load_lds_dwordx4 v[194:195], off
	s_mov_b32 m0, s8
	v_readlane_b32 s46, v252, 22
	global_load_lds_dwordx4 v[146:147], off
	s_barrier
	s_waitcnt lgkmcnt(0)
	v_readlane_b32 s47, v252, 23
	v_readlane_b32 s48, v252, 24
	v_readlane_b32 s49, v252, 25
	v_readlane_b32 s52, v252, 28
	v_readlane_b32 s53, v252, 29
	v_readlane_b32 s54, v252, 30
	v_readlane_b32 s55, v252, 31
	v_readlane_b32 s56, v252, 32
	v_readlane_b32 s57, v252, 33
	v_readlane_b32 s58, v252, 34
	v_readlane_b32 s59, v252, 35
	s_setprio 1
	s_waitcnt lgkmcnt(0)
	v_mfma_f32_16x16x32_bf16 v[126:129], v[142:145], v[162:165], v[126:129]
	v_mfma_f32_16x16x32_bf16 v[122:125], v[154:157], v[162:165], v[122:125]
	v_mfma_f32_16x16x32_bf16 v[118:121], v[142:145], v[170:173], v[118:121]
	v_mfma_f32_16x16x32_bf16 v[114:117], v[154:157], v[170:173], v[114:117]
	v_mfma_f32_16x16x32_bf16 v[110:113], v[142:145], v[178:181], v[110:113]
	v_mfma_f32_16x16x32_bf16 v[106:109], v[154:157], v[178:181], v[106:109]
	v_mfma_f32_16x16x32_bf16 v[98:101], v[154:157], v[186:189], v[98:101]
	v_mfma_f32_16x16x32_bf16 v[126:129], v[150:153], v[166:169], v[126:129]
	v_mfma_f32_16x16x32_bf16 v[122:125], v[158:161], v[166:169], v[122:125]
	v_mfma_f32_16x16x32_bf16 v[118:121], v[150:153], v[174:177], v[118:121]
	v_mfma_f32_16x16x32_bf16 v[114:117], v[158:161], v[174:177], v[114:117]
	v_mfma_f32_16x16x32_bf16 v[110:113], v[150:153], v[182:185], v[110:113]
	v_mfma_f32_16x16x32_bf16 v[106:109], v[158:161], v[182:185], v[106:109]
	v_mfma_f32_16x16x32_bf16 v[102:105], v[142:145], v[186:189], v[102:105]
	v_mfma_f32_16x16x32_bf16 v[98:101], v[158:161], v[190:193], v[98:101]
	v_mfma_f32_16x16x32_bf16 v[146:149], v[150:153], v[190:193], v[102:105]
	s_setprio 0
	v_add_u32_e32 v0, 0x14000, v214
	s_barrier
	s_nop 2
	ds_read_b128 v[102:105], v0
	ds_read_b128 v[194:197], v0 offset:1024
	ds_read_b128 v[198:201], v0 offset:2048
	ds_read_b128 v[202:205], v0 offset:3072
	s_barrier
; #define LDA(dst, b, h) for (int m = 0; m < 4; ++m) for (int k = 0; k < 2; ++k) \
;     dst[m][k] = *reinterpret_cast<const bf16x8*>((char*)SA(b, h) + a_thr + (m * 2 + k) * 1024)
; #define LDB(dst, b, h) for (int n = 0; n < 2; ++n) for (int k = 0; k < 2; ++k) \
;     dst[n][k] = *reinterpret_cast<const bf16x8*>((char*)SB(b, h) + b_thr + (n * 2 + k) * 1024)
; #define MMA(ai, bj, At, Btf) do { __builtin_amdgcn_s_setprio(1); \
;     for (int m = 0; m < 4; ++m) for (int n = 0; n < 2; ++n) for (int k = 0; k < 2; ++k) \
;       acc[ai][bj][m][n] = __builtin_amdgcn_mfma_f32_16x16x32_bf16(Btf[n][k], At[m][k], acc[ai][bj][m][n], 0, 0, 0); \
;     __builtin_amdgcn_s_setprio(0); } while (0)
; #define WAIT_V(n) asm volatile("s_waitcnt vmcnt(" #n ")" ::: "memory")
; #define WAIT_L(n) asm volatile("s_waitcnt lgkmcnt(" #n ")" ::: "memory")
; #define BAR __builtin_amdgcn_s_barrier()
; template <bool OVL, bool PANEL = false, class Epi>
; __device__ __forceinline__ void gemm_phase(const bf16_t* __restrict__ A, long lda, const bf16_t* __restrict__ Bt, long ldb, int nM, int nN, int K,
;                                            const Epi& epi, bf16_t* shm, int w0) {
;     ...
;       LDA(At, 0, 1); WAIT_V(4); BAR; WAIT_L(0); MMA(1, 0, At, B0); MMA(1, 1, At, B1); BAR; }
;     { LDB(B0, 1, 0); LDA(At, 1, 0); WAIT_V(2); BAR; WAIT_L(0); MMA(0, 0, At, B0); BAR;
;       LDB(B1, 1, 1); WAIT_V(0); BAR; WAIT_L(0); MMA(0, 1, At, B1); BAR;
	s_waitcnt lgkmcnt(0)
	s_setprio 1
	s_waitcnt lgkmcnt(0)
	v_mfma_f32_16x16x32_bf16 v[94:97], v[102:105], v[162:165], v[94:97]
	v_mfma_f32_16x16x32_bf16 v[86:89], v[102:105], v[170:173], v[86:89]
	v_mfma_f32_16x16x32_bf16 v[78:81], v[102:105], v[178:181], v[78:81]
	v_mfma_f32_16x16x32_bf16 v[74:77], v[198:201], v[178:181], v[74:77]
	v_mfma_f32_16x16x32_bf16 v[94:97], v[194:197], v[166:169], v[94:97]
	v_mfma_f32_16x16x32_bf16 v[90:93], v[198:201], v[162:165], v[90:93]
	v_mfma_f32_16x16x32_bf16 v[86:89], v[194:197], v[174:177], v[86:89]
	v_mfma_f32_16x16x32_bf16 v[82:85], v[198:201], v[170:173], v[82:85]
	v_mfma_f32_16x16x32_bf16 v[78:81], v[194:197], v[182:185], v[78:81]
	v_mfma_f32_16x16x32_bf16 v[74:77], v[202:205], v[182:185], v[74:77]
	v_mfma_f32_16x16x32_bf16 v[70:73], v[102:105], v[186:189], v[70:73]
	v_mfma_f32_16x16x32_bf16 v[66:69], v[198:201], v[186:189], v[66:69]
	v_mfma_f32_16x16x32_bf16 v[162:165], v[202:205], v[166:169], v[90:93]
	v_mfma_f32_16x16x32_bf16 v[166:169], v[202:205], v[174:177], v[82:85]
	v_mfma_f32_16x16x32_bf16 v[170:173], v[194:197], v[190:193], v[70:73]
	v_mfma_f32_16x16x32_bf16 v[174:177], v[202:205], v[190:193], v[66:69]
	s_setprio 0
	s_barrier
	s_nop 1
	ds_read_b128 v[66:69], v141 offset:16384
	ds_read_b128 v[70:73], v141 offset:17408
	ds_read_b128 v[82:85], v141 offset:18432
	ds_read_b128 v[90:93], v141 offset:19456
	ds_read_b128 v[178:181], v141 offset:20480
	ds_read_b128 v[182:185], v141 offset:21504
	ds_read_b128 v[186:189], v141 offset:22528
	ds_read_b128 v[190:193], v141 offset:23552
	s_waitcnt vmcnt(4)
	s_barrier
	s_waitcnt lgkmcnt(0)
	s_setprio 1
	s_waitcnt lgkmcnt(0)
	v_mfma_f32_16x16x32_bf16 v[62:65], v[142:145], v[66:69], v[62:65]
	v_mfma_f32_16x16x32_bf16 v[54:57], v[142:145], v[82:85], v[54:57]
	v_mfma_f32_16x16x32_bf16 v[46:49], v[142:145], v[178:181], v[46:49]
	v_mfma_f32_16x16x32_bf16 v[42:45], v[154:157], v[178:181], v[42:45]
	v_mfma_f32_16x16x32_bf16 v[38:41], v[142:145], v[186:189], v[38:41]
	v_mfma_f32_16x16x32_bf16 v[34:37], v[154:157], v[186:189], v[34:37]
	v_mfma_f32_16x16x32_bf16 v[62:65], v[150:153], v[70:73], v[62:65]
	v_mfma_f32_16x16x32_bf16 v[58:61], v[154:157], v[66:69], v[58:61]
	v_mfma_f32_16x16x32_bf16 v[54:57], v[150:153], v[90:93], v[54:57]
	v_mfma_f32_16x16x32_bf16 v[50:53], v[154:157], v[82:85], v[50:53]
	v_mfma_f32_16x16x32_bf16 v[46:49], v[150:153], v[182:185], v[46:49]
	v_mfma_f32_16x16x32_bf16 v[42:45], v[158:161], v[182:185], v[42:45]
	v_mfma_f32_16x16x32_bf16 v[38:41], v[150:153], v[190:193], v[38:41]
	v_mfma_f32_16x16x32_bf16 v[34:37], v[158:161], v[190:193], v[34:37]
	v_mfma_f32_16x16x32_bf16 v[206:209], v[158:161], v[70:73], v[58:61]
	v_mfma_f32_16x16x32_bf16 v[210:213], v[158:161], v[90:93], v[50:53]
	s_setprio 0
	s_setprio 1
	v_mfma_f32_16x16x32_bf16 v[30:33], v[102:105], v[66:69], v[30:33]
	v_mfma_f32_16x16x32_bf16 v[26:29], v[198:201], v[66:69], v[26:29]
	v_mfma_f32_16x16x32_bf16 v[22:25], v[102:105], v[82:85], v[22:25]
	v_mfma_f32_16x16x32_bf16 v[18:21], v[198:201], v[82:85], v[18:21]
	v_mfma_f32_16x16x32_bf16 v[14:17], v[102:105], v[178:181], v[14:17]
	v_mfma_f32_16x16x32_bf16 v[10:13], v[198:201], v[178:181], v[10:13]
	v_mfma_f32_16x16x32_bf16 v[6:9], v[102:105], v[186:189], v[6:9]
	v_mfma_f32_16x16x32_bf16 v[2:5], v[198:201], v[186:189], v[2:5]
	v_mfma_f32_16x16x32_bf16 v[30:33], v[194:197], v[70:73], v[30:33]
	v_mfma_f32_16x16x32_bf16 v[26:29], v[202:205], v[70:73], v[26:29]
	v_mfma_f32_16x16x32_bf16 v[22:25], v[194:197], v[90:93], v[22:25]
	v_mfma_f32_16x16x32_bf16 v[18:21], v[202:205], v[90:93], v[18:21]
	v_mfma_f32_16x16x32_bf16 v[14:17], v[194:197], v[182:185], v[14:17]
	v_mfma_f32_16x16x32_bf16 v[10:13], v[202:205], v[182:185], v[10:13]
	v_mfma_f32_16x16x32_bf16 v[6:9], v[194:197], v[190:193], v[6:9]
	v_mfma_f32_16x16x32_bf16 v[2:5], v[202:205], v[190:193], v[2:5]
	s_setprio 0
	v_add_u32_e32 v0, 0x18000, v214
	s_barrier
	ds_read_b128 v[142:145], v0
	ds_read_b128 v[150:153], v0 offset:1024
	ds_read_b128 v[154:157], v0 offset:2048
	ds_read_b128 v[158:161], v0 offset:3072
	ds_read_b128 v[50:53], v141 offset:32768
	ds_read_b128 v[58:61], v141 offset:33792
	ds_read_b128 v[66:69], v141 offset:34816
	ds_read_b128 v[70:73], v141 offset:35840
	ds_read_b128 v[178:181], v141 offset:36864
	ds_read_b128 v[182:185], v141 offset:37888
	ds_read_b128 v[186:189], v141 offset:38912
	ds_read_b128 v[190:193], v141 offset:39936
	s_waitcnt vmcnt(2)
	s_barrier
; #define LDA(dst, b, h) for (int m = 0; m < 4; ++m) for (int k = 0; k < 2; ++k) \
;     dst[m][k] = *reinterpret_cast<const bf16x8*>((char*)SA(b, h) + a_thr + (m * 2 + k) * 1024)
; #define LDB(dst, b, h) for (int n = 0; n < 2; ++n) for (int k = 0; k < 2; ++k) \
;     dst[n][k] = *reinterpret_cast<const bf16x8*>((char*)SB(b, h) + b_thr + (n * 2 + k) * 1024)
; #define MMA(ai, bj, At, Btf) do { __builtin_amdgcn_s_setprio(1); \
;     for (int m = 0; m < 4; ++m) for (int n = 0; n < 2; ++n) for (int k = 0; k < 2; ++k) \
;       acc[ai][bj][m][n] = __builtin_amdgcn_mfma_f32_16x16x32_bf16(Btf[n][k], At[m][k], acc[ai][bj][m][n], 0, 0, 0); \
;     __builtin_amdgcn_s_setprio(0); } while (0)
; #define WAIT_V(n) asm volatile("s_waitcnt vmcnt(" #n ")" ::: "memory")
; #define WAIT_L(n) asm volatile("s_waitcnt lgkmcnt(" #n ")" ::: "memory")
; #define BAR __builtin_amdgcn_s_barrier()
; template <bool OVL, bool PANEL = false, class Epi>
; __device__ __forceinline__ void gemm_phase(const bf16_t* __restrict__ A, long lda, const bf16_t* __restrict__ Bt, long ldb, int nM, int nN, int K,
;                                            const Epi& epi, bf16_t* shm, int w0) {
;     ...
;     { LDB(B0, 1, 0); LDA(At, 1, 0); WAIT_V(2); BAR; WAIT_L(0); MMA(0, 0, At, B0); BAR;
;       LDB(B1, 1, 1); WAIT_V(0); BAR; WAIT_L(0); MMA(0, 1, At, B1); BAR;
;       LDA(At, 1, 1); BAR; WAIT_L(0); MMA(1, 0, At, B0); MMA(1, 1, At, B1); BAR; }
;     if (wr == 0) BAR;
	s_waitcnt lgkmcnt(0)
	s_setprio 1
	s_waitcnt lgkmcnt(0)
	v_mfma_f32_16x16x32_bf16 v[82:85], v[142:145], v[50:53], v[126:129]
	v_mfma_f32_16x16x32_bf16 v[126:129], v[150:153], v[58:61], v[82:85]
	v_mfma_f32_16x16x32_bf16 v[82:85], v[154:157], v[50:53], v[122:125]
	v_mfma_f32_16x16x32_bf16 v[122:125], v[158:161], v[58:61], v[82:85]
	v_mfma_f32_16x16x32_bf16 v[82:85], v[142:145], v[66:69], v[118:121]
	v_mfma_f32_16x16x32_bf16 v[118:121], v[150:153], v[70:73], v[82:85]
	v_mfma_f32_16x16x32_bf16 v[82:85], v[154:157], v[66:69], v[114:117]
	v_mfma_f32_16x16x32_bf16 v[114:117], v[158:161], v[70:73], v[82:85]
	v_mfma_f32_16x16x32_bf16 v[82:85], v[142:145], v[178:181], v[110:113]
	v_mfma_f32_16x16x32_bf16 v[110:113], v[150:153], v[182:185], v[82:85]
	v_mfma_f32_16x16x32_bf16 v[82:85], v[154:157], v[178:181], v[106:109]
	v_mfma_f32_16x16x32_bf16 v[102:105], v[158:161], v[182:185], v[82:85]
	v_mfma_f32_16x16x32_bf16 v[82:85], v[142:145], v[186:189], v[146:149]
	v_mfma_f32_16x16x32_bf16 v[90:93], v[150:153], v[190:193], v[82:85]
	v_mfma_f32_16x16x32_bf16 v[82:85], v[154:157], v[186:189], v[98:101]
	v_mfma_f32_16x16x32_bf16 v[82:85], v[158:161], v[190:193], v[82:85]
	s_setprio 0
	v_add_u32_e32 v0, 0x1c000, v214
	s_barrier
	ds_read_b128 v[146:149], v0
	ds_read_b128 v[194:197], v0 offset:1024
	ds_read_b128 v[198:201], v0 offset:2048
	ds_read_b128 v[202:205], v0 offset:3072
	s_waitcnt vmcnt(0)
	s_barrier
	s_waitcnt lgkmcnt(0)
	s_setprio 1
	s_waitcnt lgkmcnt(0)
	v_mfma_f32_16x16x32_bf16 v[94:97], v[146:149], v[50:53], v[94:97]
	v_mfma_f32_16x16x32_bf16 v[50:53], v[198:201], v[50:53], v[162:165]
	v_mfma_f32_16x16x32_bf16 v[98:101], v[202:205], v[58:61], v[50:53]
	v_mfma_f32_16x16x32_bf16 v[50:53], v[146:149], v[66:69], v[86:89]
	v_mfma_f32_16x16x32_bf16 v[106:109], v[194:197], v[58:61], v[94:97]
	v_mfma_f32_16x16x32_bf16 v[94:97], v[194:197], v[70:73], v[50:53]
	v_mfma_f32_16x16x32_bf16 v[50:53], v[198:201], v[66:69], v[166:169]
	v_mfma_f32_16x16x32_bf16 v[86:89], v[202:205], v[70:73], v[50:53]
	v_mfma_f32_16x16x32_bf16 v[50:53], v[146:149], v[178:181], v[78:81]
	v_mfma_f32_16x16x32_bf16 v[70:73], v[194:197], v[182:185], v[50:53]
	v_mfma_f32_16x16x32_bf16 v[50:53], v[198:201], v[178:181], v[74:77]
	v_mfma_f32_16x16x32_bf16 v[66:69], v[202:205], v[182:185], v[50:53]
	v_mfma_f32_16x16x32_bf16 v[50:53], v[146:149], v[186:189], v[170:173]
	v_mfma_f32_16x16x32_bf16 v[58:61], v[194:197], v[190:193], v[50:53]
	v_mfma_f32_16x16x32_bf16 v[50:53], v[198:201], v[186:189], v[174:177]
	v_mfma_f32_16x16x32_bf16 v[50:53], v[202:205], v[190:193], v[50:53]
	s_setprio 0
	s_barrier
	ds_read_b128 v[162:165], v141 offset:49152
	ds_read_b128 v[166:169], v141 offset:50176
	ds_read_b128 v[170:173], v141 offset:51200
	ds_read_b128 v[174:177], v141 offset:52224
	ds_read_b128 v[178:181], v141 offset:53248
	ds_read_b128 v[182:185], v141 offset:54272
	ds_read_b128 v[186:189], v141 offset:55296
	ds_read_b128 v[190:193], v141 offset:56320
	s_barrier
	s_waitcnt lgkmcnt(0)
	s_setprio 1
	s_waitcnt lgkmcnt(0)
	v_mfma_f32_16x16x32_bf16 v[62:65], v[142:145], v[162:165], v[62:65]
	v_mfma_f32_16x16x32_bf16 v[78:81], v[150:153], v[166:169], v[62:65]
	v_mfma_f32_16x16x32_bf16 v[62:65], v[154:157], v[162:165], v[206:209]
	v_mfma_f32_16x16x32_bf16 v[54:57], v[142:145], v[170:173], v[54:57]
	v_mfma_f32_16x16x32_bf16 v[74:77], v[158:161], v[166:169], v[62:65]
	v_mfma_f32_16x16x32_bf16 v[62:65], v[150:153], v[174:177], v[54:57]
	v_mfma_f32_16x16x32_bf16 v[54:57], v[154:157], v[170:173], v[210:213]
	v_mfma_f32_16x16x32_bf16 v[46:49], v[142:145], v[178:181], v[46:49]
	v_mfma_f32_16x16x32_bf16 v[42:45], v[154:157], v[178:181], v[42:45]
	v_mfma_f32_16x16x32_bf16 v[38:41], v[142:145], v[186:189], v[38:41]
	v_mfma_f32_16x16x32_bf16 v[34:37], v[154:157], v[186:189], v[34:37]
	v_mfma_f32_16x16x32_bf16 v[54:57], v[158:161], v[174:177], v[54:57]
	v_mfma_f32_16x16x32_bf16 v[46:49], v[150:153], v[182:185], v[46:49]
	v_mfma_f32_16x16x32_bf16 v[42:45], v[158:161], v[182:185], v[42:45]
	v_mfma_f32_16x16x32_bf16 v[38:41], v[150:153], v[190:193], v[38:41]
	v_mfma_f32_16x16x32_bf16 v[34:37], v[158:161], v[190:193], v[34:37]
	s_setprio 0
	s_setprio 1
	v_mfma_f32_16x16x32_bf16 v[30:33], v[146:149], v[162:165], v[30:33]
	v_mfma_f32_16x16x32_bf16 v[26:29], v[198:201], v[162:165], v[26:29]
	v_mfma_f32_16x16x32_bf16 v[22:25], v[146:149], v[170:173], v[22:25]
	v_mfma_f32_16x16x32_bf16 v[18:21], v[198:201], v[170:173], v[18:21]
	v_mfma_f32_16x16x32_bf16 v[14:17], v[146:149], v[178:181], v[14:17]
	v_mfma_f32_16x16x32_bf16 v[10:13], v[198:201], v[178:181], v[10:13]
	v_mfma_f32_16x16x32_bf16 v[6:9], v[146:149], v[186:189], v[6:9]
	v_mfma_f32_16x16x32_bf16 v[2:5], v[198:201], v[186:189], v[2:5]
	v_mfma_f32_16x16x32_bf16 v[30:33], v[194:197], v[166:169], v[30:33]
	v_mfma_f32_16x16x32_bf16 v[26:29], v[202:205], v[166:169], v[26:29]
	v_mfma_f32_16x16x32_bf16 v[22:25], v[194:197], v[174:177], v[22:25]
	v_mfma_f32_16x16x32_bf16 v[18:21], v[202:205], v[174:177], v[18:21]
	v_mfma_f32_16x16x32_bf16 v[14:17], v[194:197], v[182:185], v[14:17]
	v_mfma_f32_16x16x32_bf16 v[10:13], v[202:205], v[182:185], v[10:13]
	v_mfma_f32_16x16x32_bf16 v[6:9], v[194:197], v[190:193], v[6:9]
	v_mfma_f32_16x16x32_bf16 v[2:5], v[202:205], v[190:193], v[2:5]
	s_setprio 0
	s_barrier
	s_and_saveexec_b64 s[8:9], s[78:79]
	s_cbranch_execz .LBB0_389
	s_barrier

; #define WAIT_V(n) asm volatile("s_waitcnt vmcnt(" #n ")" ::: "memory")
; #define BAR __builtin_amdgcn_s_barrier()
; template <bool OVL, bool PANEL = false, class Epi>
; __device__ __forceinline__ void gemm_phase(const bf16_t* __restrict__ A, long lda, const bf16_t* __restrict__ Bt, long ldb, int nM, int nN, int K,
;                                            const Epi& epi, bf16_t* shm, int w0) {
;     ...
;   if (have) { const int brow = pm * BM, bcol = pn * BM;
;     STAGE(SB(0, 0), Bt, ldb, boff, bcol, 0); STAGE(SA(0, 0), A, lda, aoff, brow, 0);
;     STAGE(SB(0, 1), Bt, ldb, boff, bcol + HALF, 0); STAGE(SA(0, 1), A, lda, aoff, brow + HALF, 0); }
;   for (int it = 0; have; ++it) {
;     const int brow = pm * BM, bcol = pn * BM;
;     f32x4 acc[2][2][4][2];
; #pragma unroll
;     for (int a0 = 0; a0 < 2; ++a0)
; #pragma unroll
;       for (int a1 = 0; a1 < 2; ++a1)
; #pragma unroll
;         for (int a2 = 0; a2 < 4; ++a2)
; #pragma unroll
;           for (int a3 = 0; a3 < 2; ++a3) acc[a0][a1][a2][a3] = (f32x4){0.f, 0.f, 0.f, 0.f};
;     bf16x8 At[4][2], B0[2][2], B1[2][2];
;     if (wr == 1) BAR;
;     WAIT_V(4); BAR;
;     STAGE(SB(1, 0), Bt, ldb, boff, bcol, 1); STAGE(SA(1, 0), A, lda, aoff, brow, 1); STAGE(SB(1, 1), Bt, ldb, boff, bcol + HALF, 1);
;     WAIT_V(6); BAR;
.LBB0_409:
	s_or_b64 exec, exec, s[0:1]
	s_lshl_b32 s0, s18, 19
	v_readlane_b32 s8, v251, 49
	v_readlane_b32 s9, v251, 50
	s_add_u32 s0, s8, s0
	v_readlane_b32 s10, v251, 51
	v_readlane_b32 s11, v251, 52
	s_addc_u32 s1, s9, 0
	v_mov_b32_e32 v0, v131
	v_add_u32_e32 v144, s96, v130
	s_waitcnt vmcnt(4)
	s_barrier
	s_mov_b64 s[10:11], 0x80
	v_lshl_add_u64 v[2:3], s[0:1], 0, v[0:1]
	v_readfirstlane_b32 s8, v144
	v_add_u32_e32 v145, 0x2000, v144
	v_lshl_add_u64 v[4:5], v[2:3], 0, s[10:11]
	s_mov_b32 m0, s8
	v_readfirstlane_b32 s8, v145
	v_readlane_b32 s40, v252, 20
	v_readlane_b32 s12, v251, 53
	v_readlane_b32 s13, v251, 54
	global_load_lds_dwordx4 v[4:5], off
	s_mov_b32 m0, s8
	s_lshl_b32 s8, s20, 19
	v_readlane_b32 s50, v252, 30
	s_mov_b64 s[12:13], 0x20080
	v_readlane_b32 s51, v252, 31
	s_add_u32 s8, s50, s8
	v_lshl_add_u64 v[2:3], v[2:3], 0, s[12:13]
	s_addc_u32 s9, s51, 0
	v_mov_b32_e32 v0, v131
	global_load_lds_dwordx4 v[2:3], off
	v_add_u32_e32 v146, 0x8000, v134
	v_lshl_add_u64 v[2:3], s[8:9], 0, v[0:1]
	v_lshl_add_u64 v[4:5], v[2:3], 0, s[10:11]
	v_readfirstlane_b32 s10, v146
	v_add_u32_e32 v147, 0xa000, v134
	s_mov_b32 m0, s10
	v_readfirstlane_b32 s10, v147
	global_load_lds_dwordx4 v[4:5], off
	v_lshl_add_u64 v[2:3], v[2:3], 0, s[12:13]
	s_mov_b32 m0, s10
	v_mov_b32_e32 v0, v131
	v_add_u32_e32 v148, s75, v130
	global_load_lds_dwordx4 v[2:3], off
	s_mov_b64 s[24:25], 0x40080
	v_lshl_add_u64 v[2:3], s[0:1], 0, v[0:1]
	v_readfirstlane_b32 s10, v148
	v_add_u32_e32 v149, 0x2000, v148
	v_lshl_add_u64 v[4:5], v[2:3], 0, s[24:25]
	s_mov_b32 m0, s10
	v_readfirstlane_b32 s10, v149
	global_load_lds_dwordx4 v[4:5], off
	v_lshl_add_u64 v[2:3], v[2:3], 0, s[36:37]
	s_mov_b32 m0, s10
	s_mov_b32 s21, -2
	global_load_lds_dwordx4 v[2:3], off
	s_waitcnt vmcnt(6)
	v_mov_b32_e32 v2, 0
	s_mov_b64 s[10:11], 0
	v_mov_b32_e32 v3, v2
	v_mov_b32_e32 v4, v2
	v_mov_b32_e32 v5, v2
	v_mov_b32_e32 v6, v2
	v_mov_b32_e32 v7, v2
	v_mov_b32_e32 v8, v2
	v_mov_b32_e32 v9, v2
	s_waitcnt vmcnt(0)
	v_mov_b32_e32 v10, v2
	v_mov_b32_e32 v11, v2
	v_mov_b32_e32 v12, v2
	v_mov_b32_e32 v13, v2
	s_waitcnt lgkmcnt(0)
	v_mov_b32_e32 v14, v2
	v_mov_b32_e32 v15, v2
	v_mov_b32_e32 v16, v2
	v_mov_b32_e32 v17, v2
	v_mov_b32_e32 v18, v2
	v_mov_b32_e32 v19, v2
	v_mov_b32_e32 v20, v2
	v_mov_b32_e32 v21, v2
	v_mov_b32_e32 v22, v2
	v_mov_b32_e32 v23, v2
	v_mov_b32_e32 v24, v2
	v_mov_b32_e32 v25, v2
	v_mov_b32_e32 v26, v2
	v_mov_b32_e32 v27, v2
	v_mov_b32_e32 v28, v2
	v_mov_b32_e32 v29, v2
	v_mov_b32_e32 v30, v2
	v_mov_b32_e32 v31, v2
	v_mov_b32_e32 v32, v2
	v_mov_b32_e32 v33, v2
	v_mov_b32_e32 v34, v2
	v_mov_b32_e32 v35, v2
	v_mov_b32_e32 v36, v2
	v_mov_b32_e32 v37, v2
	v_mov_b32_e32 v38, v2
	v_mov_b32_e32 v39, v2
	v_mov_b32_e32 v40, v2
	v_mov_b32_e32 v41, v2
	v_mov_b32_e32 v42, v2
	v_mov_b32_e32 v43, v2
	v_mov_b32_e32 v44, v2
	v_mov_b32_e32 v45, v2
	v_mov_b32_e32 v46, v2
	v_mov_b32_e32 v47, v2
	v_mov_b32_e32 v48, v2
	v_mov_b32_e32 v49, v2
	v_mov_b32_e32 v50, v2
	v_mov_b32_e32 v51, v2
	v_mov_b32_e32 v52, v2
	v_mov_b32_e32 v53, v2
	v_mov_b32_e32 v54, v2
	v_mov_b32_e32 v55, v2
	v_mov_b32_e32 v56, v2
	v_mov_b32_e32 v57, v2
	v_mov_b32_e32 v58, v2
	v_mov_b32_e32 v59, v2
	v_mov_b32_e32 v60, v2
	v_mov_b32_e32 v61, v2
	v_mov_b32_e32 v62, v2
	v_mov_b32_e32 v63, v2
	v_mov_b32_e32 v64, v2
	v_mov_b32_e32 v65, v2
	v_mov_b32_e32 v66, v2
	v_mov_b32_e32 v67, v2
	v_mov_b32_e32 v68, v2
	v_mov_b32_e32 v69, v2
	v_mov_b32_e32 v70, v2
	v_mov_b32_e32 v71, v2
	v_mov_b32_e32 v72, v2
	v_mov_b32_e32 v73, v2
	v_mov_b32_e32 v74, v2
	v_mov_b32_e32 v75, v2
	v_mov_b32_e32 v76, v2
	v_mov_b32_e32 v77, v2
	v_mov_b32_e32 v78, v2
	v_mov_b32_e32 v79, v2
	v_mov_b32_e32 v80, v2
	v_mov_b32_e32 v81, v2
	v_mov_b32_e32 v82, v2
	v_mov_b32_e32 v83, v2
	v_mov_b32_e32 v84, v2
	v_mov_b32_e32 v85, v2
	v_mov_b32_e32 v86, v2
	v_mov_b32_e32 v87, v2
	v_mov_b32_e32 v88, v2
	v_mov_b32_e32 v89, v2
	v_mov_b32_e32 v90, v2
	v_mov_b32_e32 v91, v2
	v_mov_b32_e32 v92, v2
	v_mov_b32_e32 v93, v2
	v_mov_b32_e32 v94, v2
	v_mov_b32_e32 v95, v2
	v_mov_b32_e32 v96, v2
	v_mov_b32_e32 v97, v2
	v_mov_b32_e32 v98, v2
	v_mov_b32_e32 v99, v2
	v_mov_b32_e32 v100, v2
	v_mov_b32_e32 v101, v2
	v_mov_b32_e32 v102, v2
	v_mov_b32_e32 v103, v2
	v_mov_b32_e32 v104, v2
	v_mov_b32_e32 v105, v2
	v_mov_b32_e32 v106, v2
	v_mov_b32_e32 v107, v2
	v_mov_b32_e32 v108, v2
	v_mov_b32_e32 v109, v2
	v_mov_b32_e32 v110, v2
	v_mov_b32_e32 v111, v2
	v_mov_b32_e32 v112, v2
	v_mov_b32_e32 v113, v2
	v_mov_b32_e32 v114, v2
	v_mov_b32_e32 v115, v2
	v_mov_b32_e32 v116, v2
	v_mov_b32_e32 v117, v2
	v_mov_b32_e32 v118, v2
	v_mov_b32_e32 v119, v2
	v_mov_b32_e32 v120, v2
	v_mov_b32_e32 v121, v2
	v_mov_b32_e32 v122, v2
	v_mov_b32_e32 v123, v2
	v_mov_b32_e32 v124, v2
	v_mov_b32_e32 v125, v2
	v_mov_b32_e32 v126, v2
	v_mov_b32_e32 v127, v2
	v_mov_b32_e32 v128, v2
	v_mov_b32_e32 v129, v2
	s_mov_b64 s[26:27], 0x40180
	s_mov_b64 s[28:29], 0x60180
	v_readlane_b32 s14, v251, 55
	v_readlane_b32 s15, v251, 56
	v_readlane_b32 s41, v252, 21
	v_readlane_b32 s42, v252, 22
	v_readlane_b32 s43, v252, 23
	v_readlane_b32 s44, v252, 24
	v_readlane_b32 s45, v252, 25
	v_readlane_b32 s46, v252, 26
	v_readlane_b32 s47, v252, 27
	v_readlane_b32 s48, v252, 28
	v_readlane_b32 s49, v252, 29
	v_readlane_b32 s52, v252, 32
	v_readlane_b32 s53, v252, 33
	v_readlane_b32 s54, v252, 34
	v_readlane_b32 s55, v252, 35
	s_barrier
	v_add_u32_e32 v220, s2, v140
	v_readfirstlane_b32 s16, v134
	s_add_u32 s16, s16, 0xc000
	v_readfirstlane_b32 s23, v134
	s_add_u32 s23, s23, 0xe000
	v_add_u32_e32 v221, s33, v140
	v_readfirstlane_b32 s30, v132
	v_readfirstlane_b32 s31, v133
	v_readfirstlane_b32 s32, v134
	v_readfirstlane_b32 s40, v135
	v_readfirstlane_b32 s41, v136
	v_readfirstlane_b32 s42, v137
	v_add_u32_e32 v222, s96, v140
	v_readfirstlane_b32 s43, v138
	v_readfirstlane_b32 s44, v139
	v_add_u32_e32 v223, s75, v140
	v_readfirstlane_b32 s45, v144
	v_readfirstlane_b32 s46, v145
	v_readfirstlane_b32 s47, v146
	v_readfirstlane_b32 s48, v147
	v_readfirstlane_b32 s49, v148
	v_readfirstlane_b32 s50, v149
	v_add_u32_e32 v150, 0xc000, v134
	v_add_u32_e32 v151, 0xe000, v134
; #define LDA(dst, b, h) for (int m = 0; m < 4; ++m) for (int k = 0; k < 2; ++k) \
;     dst[m][k] = *reinterpret_cast<const bf16x8*>((char*)SA(b, h) + a_thr + (m * 2 + k) * 1024)
; #define LDB(dst, b, h) for (int n = 0; n < 2; ++n) for (int k = 0; k < 2; ++k) \
;     dst[n][k] = *reinterpret_cast<const bf16x8*>((char*)SB(b, h) + b_thr + (n * 2 + k) * 1024)
; #define MMA(ai, bj, At, Btf) do { __builtin_amdgcn_s_setprio(1); \
;     for (int m = 0; m < 4; ++m) for (int n = 0; n < 2; ++n) for (int k = 0; k < 2; ++k) \
;       acc[ai][bj][m][n] = __builtin_amdgcn_mfma_f32_16x16x32_bf16(Btf[n][k], At[m][k], acc[ai][bj][m][n], 0, 0, 0); \
;     __builtin_amdgcn_s_setprio(0); } while (0)
; #define WAIT_V(n) asm volatile("s_waitcnt vmcnt(" #n ")" ::: "memory")
; #define WAIT_L(n) asm volatile("s_waitcnt lgkmcnt(" #n ")" ::: "memory")
; #define BAR __builtin_amdgcn_s_barrier()
; #define SCHED __builtin_amdgcn_sched_barrier(0)
; template <bool OVL, bool PANEL = false, class Epi>
; __device__ __forceinline__ void gemm_phase(const bf16_t* __restrict__ A, long lda, const bf16_t* __restrict__ Bt, long ldb, int nM, int nN, int K,
;                                            const Epi& epi, bf16_t* shm, int w0) {
;     ...
;     for (int t = 0; t < nt - 2; t += 2) {
;       LDB(B0, 0, 0); SCHED; LDA(At, 0, 0); STAGE(SA(1, 1), A, lda, aoff, brow + HALF, t + 1);
;       WAIT_L(8); BAR; WAIT_L(0); MMA(0, 0, At, B0); BAR; SCHED;
;       LDB(B1, 0, 1); STAGE(SB(0, 0), Bt, ldb, boff, bcol, t + 2);
;       BAR; WAIT_L(0); MMA(0, 1, At, B1); BAR;
;       LDA(At, 0, 1); STAGE(SA(0, 0), A, lda, aoff, brow, t + 2);
;       BAR; WAIT_L(0); MMA(1, 0, At, B0); BAR; SCHED;
;       STAGE(SB(0, 1), Bt, ldb, boff, bcol + HALF, t + 2);
;       WAIT_V(6); BAR; MMA(1, 1, At, B1); BAR;
.LBB0_410:
	ds_read_b128 v[152:155], v220
	ds_read_b128 v[156:159], v220 offset:1024
	ds_read_b128 v[160:163], v220 offset:2048
	ds_read_b128 v[164:167], v220 offset:3072
	s_add_u32 s12, s8, s10
	s_addc_u32 s13, s9, s11
	ds_read_b128 v[168:171], v143
	ds_read_b128 v[172:175], v143 offset:1024
	ds_read_b128 v[176:179], v143 offset:2048
	ds_read_b128 v[180:183], v143 offset:3072
	ds_read_b128 v[184:187], v143 offset:4096
	ds_read_b128 v[188:191], v143 offset:5120
	ds_read_b128 v[192:195], v143 offset:6144
	ds_read_b128 v[196:199], v143 offset:7168
	s_mov_b32 m0, s16
	s_add_u32 s98, s12, s24
	s_addc_u32 s99, s13, s25
	global_load_lds_dwordx4 v131, s[98:99]
	s_mov_b32 m0, s23
	s_add_u32 s98, s12, s36
	s_addc_u32 s99, s13, s37
	global_load_lds_dwordx4 v131, s[98:99]
	s_waitcnt lgkmcnt(8)
	s_barrier
	s_waitcnt lgkmcnt(0)
	s_setprio 1
	s_waitcnt lgkmcnt(0)
	v_mfma_f32_16x16x32_bf16 v[126:129], v[152:155], v[168:171], v[126:129]
	v_mfma_f32_16x16x32_bf16 v[122:125], v[160:163], v[168:171], v[122:125]
	v_mfma_f32_16x16x32_bf16 v[118:121], v[152:155], v[176:179], v[118:121]
	v_mfma_f32_16x16x32_bf16 v[114:117], v[160:163], v[176:179], v[114:117]
	v_mfma_f32_16x16x32_bf16 v[110:113], v[152:155], v[184:187], v[110:113]
	v_mfma_f32_16x16x32_bf16 v[106:109], v[160:163], v[184:187], v[106:109]
	v_mfma_f32_16x16x32_bf16 v[102:105], v[152:155], v[192:195], v[102:105]
	v_mfma_f32_16x16x32_bf16 v[98:101], v[160:163], v[192:195], v[98:101]
	v_mfma_f32_16x16x32_bf16 v[126:129], v[156:159], v[172:175], v[126:129]
	v_mfma_f32_16x16x32_bf16 v[122:125], v[164:167], v[172:175], v[122:125]
	v_mfma_f32_16x16x32_bf16 v[118:121], v[156:159], v[180:183], v[118:121]
	v_mfma_f32_16x16x32_bf16 v[114:117], v[164:167], v[180:183], v[114:117]
	v_mfma_f32_16x16x32_bf16 v[110:113], v[156:159], v[188:191], v[110:113]
	v_mfma_f32_16x16x32_bf16 v[106:109], v[164:167], v[188:191], v[106:109]
	v_mfma_f32_16x16x32_bf16 v[102:105], v[156:159], v[196:199], v[102:105]
	v_mfma_f32_16x16x32_bf16 v[98:101], v[164:167], v[196:199], v[98:101]
	s_setprio 0
	s_barrier
	s_add_u32 s14, s0, s10
	ds_read_b128 v[200:203], v221
	ds_read_b128 v[204:207], v221 offset:1024
	ds_read_b128 v[208:211], v221 offset:2048
	ds_read_b128 v[212:215], v221 offset:3072
	s_addc_u32 s15, s1, s11
	s_mov_b32 m0, s30
	s_add_u32 s98, s14, s34
	s_addc_u32 s99, s15, s35
	global_load_lds_dwordx4 v131, s[98:99]
	s_mov_b32 m0, s31
	s_add_u32 s98, s14, s64
	s_addc_u32 s99, s15, s65
	global_load_lds_dwordx4 v131, s[98:99]
	s_barrier
	s_waitcnt lgkmcnt(0)
	s_setprio 1
	s_waitcnt lgkmcnt(0)
	v_mfma_f32_16x16x32_bf16 v[94:97], v[200:203], v[168:171], v[94:97]
	v_mfma_f32_16x16x32_bf16 v[90:93], v[208:211], v[168:171], v[90:93]
	v_mfma_f32_16x16x32_bf16 v[86:89], v[200:203], v[176:179], v[86:89]
	v_mfma_f32_16x16x32_bf16 v[82:85], v[208:211], v[176:179], v[82:85]
	v_mfma_f32_16x16x32_bf16 v[78:81], v[200:203], v[184:187], v[78:81]
	v_mfma_f32_16x16x32_bf16 v[74:77], v[208:211], v[184:187], v[74:77]
	v_mfma_f32_16x16x32_bf16 v[70:73], v[200:203], v[192:195], v[70:73]
	v_mfma_f32_16x16x32_bf16 v[66:69], v[208:211], v[192:195], v[66:69]
	v_mfma_f32_16x16x32_bf16 v[94:97], v[204:207], v[172:175], v[94:97]
	v_mfma_f32_16x16x32_bf16 v[90:93], v[212:215], v[172:175], v[90:93]
	v_mfma_f32_16x16x32_bf16 v[86:89], v[204:207], v[180:183], v[86:89]
	v_mfma_f32_16x16x32_bf16 v[82:85], v[212:215], v[180:183], v[82:85]
	v_mfma_f32_16x16x32_bf16 v[78:81], v[204:207], v[188:191], v[78:81]
	v_mfma_f32_16x16x32_bf16 v[74:77], v[212:215], v[188:191], v[74:77]
	v_mfma_f32_16x16x32_bf16 v[70:73], v[204:207], v[196:199], v[70:73]
	v_mfma_f32_16x16x32_bf16 v[66:69], v[212:215], v[196:199], v[66:69]
	s_setprio 0
	s_barrier
	ds_read_b128 v[168:171], v143 offset:16384
	ds_read_b128 v[172:175], v143 offset:17408
	ds_read_b128 v[176:179], v143 offset:18432
	ds_read_b128 v[180:183], v143 offset:19456
	ds_read_b128 v[184:187], v143 offset:20480
	ds_read_b128 v[188:191], v143 offset:21504
	ds_read_b128 v[192:195], v143 offset:22528
	ds_read_b128 v[196:199], v143 offset:23552
	s_mov_b32 m0, s32
	s_add_u32 s98, s12, s34
	s_addc_u32 s99, s13, s35
	global_load_lds_dwordx4 v131, s[98:99]
	s_mov_b32 m0, s40
	s_add_u32 s98, s12, s64
	s_addc_u32 s99, s13, s65
	global_load_lds_dwordx4 v131, s[98:99]
	s_barrier
	s_waitcnt lgkmcnt(0)
	s_setprio 1
	s_waitcnt lgkmcnt(0)
	v_mfma_f32_16x16x32_bf16 v[62:65], v[152:155], v[168:171], v[62:65]
	v_mfma_f32_16x16x32_bf16 v[58:61], v[160:163], v[168:171], v[58:61]
	v_mfma_f32_16x16x32_bf16 v[54:57], v[152:155], v[176:179], v[54:57]
	v_mfma_f32_16x16x32_bf16 v[50:53], v[160:163], v[176:179], v[50:53]
	v_mfma_f32_16x16x32_bf16 v[46:49], v[152:155], v[184:187], v[46:49]
	v_mfma_f32_16x16x32_bf16 v[42:45], v[160:163], v[184:187], v[42:45]
	v_mfma_f32_16x16x32_bf16 v[38:41], v[152:155], v[192:195], v[38:41]
	v_mfma_f32_16x16x32_bf16 v[34:37], v[160:163], v[192:195], v[34:37]
	v_mfma_f32_16x16x32_bf16 v[62:65], v[156:159], v[172:175], v[62:65]
	v_mfma_f32_16x16x32_bf16 v[58:61], v[164:167], v[172:175], v[58:61]
	v_mfma_f32_16x16x32_bf16 v[54:57], v[156:159], v[180:183], v[54:57]
	v_mfma_f32_16x16x32_bf16 v[50:53], v[164:167], v[180:183], v[50:53]
	v_mfma_f32_16x16x32_bf16 v[46:49], v[156:159], v[188:191], v[46:49]
	v_mfma_f32_16x16x32_bf16 v[42:45], v[164:167], v[188:191], v[42:45]
	v_mfma_f32_16x16x32_bf16 v[38:41], v[156:159], v[196:199], v[38:41]
	v_mfma_f32_16x16x32_bf16 v[34:37], v[164:167], v[196:199], v[34:37]
	s_setprio 0
	s_barrier
	s_mov_b32 m0, s41
	s_add_u32 s98, s14, s68
	s_addc_u32 s99, s15, s69
	global_load_lds_dwordx4 v131, s[98:99]
	s_mov_b32 m0, s42
	s_add_u32 s98, s14, s70
	s_addc_u32 s99, s15, s71
	global_load_lds_dwordx4 v131, s[98:99]
	s_waitcnt vmcnt(6)
	s_barrier
; #define LDA(dst, b, h) for (int m = 0; m < 4; ++m) for (int k = 0; k < 2; ++k) \
;     dst[m][k] = *reinterpret_cast<const bf16x8*>((char*)SA(b, h) + a_thr + (m * 2 + k) * 1024)
; #define LDB(dst, b, h) for (int n = 0; n < 2; ++n) for (int k = 0; k < 2; ++k) \
;     dst[n][k] = *reinterpret_cast<const bf16x8*>((char*)SB(b, h) + b_thr + (n * 2 + k) * 1024)
; #define MMA(ai, bj, At, Btf) do { __builtin_amdgcn_s_setprio(1); \
;     for (int m = 0; m < 4; ++m) for (int n = 0; n < 2; ++n) for (int k = 0; k < 2; ++k) \
;       acc[ai][bj][m][n] = __builtin_amdgcn_mfma_f32_16x16x32_bf16(Btf[n][k], At[m][k], acc[ai][bj][m][n], 0, 0, 0); \
;     __builtin_amdgcn_s_setprio(0); } while (0)
; #define WAIT_V(n) asm volatile("s_waitcnt vmcnt(" #n ")" ::: "memory")
; #define WAIT_L(n) asm volatile("s_waitcnt lgkmcnt(" #n ")" ::: "memory")
; #define BAR __builtin_amdgcn_s_barrier()
; #define SCHED __builtin_amdgcn_sched_barrier(0)
; template <bool OVL, bool PANEL = false, class Epi>
; __device__ __forceinline__ void gemm_phase(const bf16_t* __restrict__ A, long lda, const bf16_t* __restrict__ Bt, long ldb, int nM, int nN, int K,
;                                            const Epi& epi, bf16_t* shm, int w0) {
;     ...
;       WAIT_V(6); BAR; MMA(1, 1, At, B1); BAR;
;       LDB(B0, 1, 0); SCHED; LDA(At, 1, 0); STAGE(SA(0, 1), A, lda, aoff, brow + HALF, t + 2);
;       WAIT_L(8); BAR; WAIT_L(0); MMA(0, 0, At, B0); BAR; SCHED;
;       LDB(B1, 1, 1); STAGE(SB(1, 0), Bt, ldb, boff, bcol, t + 3);
;       BAR; WAIT_L(0); MMA(0, 1, At, B1); BAR;
;       LDA(At, 1, 1); STAGE(SA(1, 0), A, lda, aoff, brow, t + 3);
	s_setprio 1
	v_mfma_f32_16x16x32_bf16 v[30:33], v[200:203], v[168:171], v[30:33]
	v_mfma_f32_16x16x32_bf16 v[26:29], v[208:211], v[168:171], v[26:29]
	v_mfma_f32_16x16x32_bf16 v[22:25], v[200:203], v[176:179], v[22:25]
	v_mfma_f32_16x16x32_bf16 v[18:21], v[208:211], v[176:179], v[18:21]
	v_mfma_f32_16x16x32_bf16 v[14:17], v[200:203], v[184:187], v[14:17]
	v_mfma_f32_16x16x32_bf16 v[10:13], v[208:211], v[184:187], v[10:13]
	v_mfma_f32_16x16x32_bf16 v[6:9], v[200:203], v[192:195], v[6:9]
	v_mfma_f32_16x16x32_bf16 v[2:5], v[208:211], v[192:195], v[2:5]
	v_mfma_f32_16x16x32_bf16 v[30:33], v[204:207], v[172:175], v[30:33]
	v_mfma_f32_16x16x32_bf16 v[26:29], v[212:215], v[172:175], v[26:29]
	v_mfma_f32_16x16x32_bf16 v[22:25], v[204:207], v[180:183], v[22:25]
	v_mfma_f32_16x16x32_bf16 v[18:21], v[212:215], v[180:183], v[18:21]
	v_mfma_f32_16x16x32_bf16 v[14:17], v[204:207], v[188:191], v[14:17]
	v_mfma_f32_16x16x32_bf16 v[10:13], v[212:215], v[188:191], v[10:13]
	v_mfma_f32_16x16x32_bf16 v[6:9], v[204:207], v[196:199], v[6:9]
	v_mfma_f32_16x16x32_bf16 v[2:5], v[212:215], v[196:199], v[2:5]
	s_setprio 0
	s_barrier
	ds_read_b128 v[152:155], v222
	ds_read_b128 v[156:159], v222 offset:1024
	ds_read_b128 v[160:163], v222 offset:2048
	ds_read_b128 v[164:167], v222 offset:3072
	ds_read_b128 v[168:171], v143 offset:32768
	ds_read_b128 v[172:175], v143 offset:33792
	ds_read_b128 v[176:179], v143 offset:34816
	ds_read_b128 v[180:183], v143 offset:35840
	ds_read_b128 v[184:187], v143 offset:36864
	ds_read_b128 v[188:191], v143 offset:37888
	ds_read_b128 v[192:195], v143 offset:38912
	ds_read_b128 v[196:199], v143 offset:39936
	s_mov_b32 m0, s43
	s_add_u32 s98, s12, s68
	s_addc_u32 s99, s13, s69
	global_load_lds_dwordx4 v131, s[98:99]
	s_mov_b32 m0, s44
	s_add_u32 s98, s12, s70
	s_addc_u32 s99, s13, s71
	global_load_lds_dwordx4 v131, s[98:99]
	s_waitcnt lgkmcnt(8)
	s_barrier
	s_waitcnt lgkmcnt(0)
	s_setprio 1
	s_waitcnt lgkmcnt(0)
	v_mfma_f32_16x16x32_bf16 v[126:129], v[152:155], v[168:171], v[126:129]
	v_mfma_f32_16x16x32_bf16 v[122:125], v[160:163], v[168:171], v[122:125]
	v_mfma_f32_16x16x32_bf16 v[118:121], v[152:155], v[176:179], v[118:121]
	v_mfma_f32_16x16x32_bf16 v[114:117], v[160:163], v[176:179], v[114:117]
	v_mfma_f32_16x16x32_bf16 v[110:113], v[152:155], v[184:187], v[110:113]
	v_mfma_f32_16x16x32_bf16 v[106:109], v[160:163], v[184:187], v[106:109]
	v_mfma_f32_16x16x32_bf16 v[102:105], v[152:155], v[192:195], v[102:105]
	v_mfma_f32_16x16x32_bf16 v[98:101], v[160:163], v[192:195], v[98:101]
	v_mfma_f32_16x16x32_bf16 v[126:129], v[156:159], v[172:175], v[126:129]
	v_mfma_f32_16x16x32_bf16 v[122:125], v[164:167], v[172:175], v[122:125]
	v_mfma_f32_16x16x32_bf16 v[118:121], v[156:159], v[180:183], v[118:121]
	v_mfma_f32_16x16x32_bf16 v[114:117], v[164:167], v[180:183], v[114:117]
	v_mfma_f32_16x16x32_bf16 v[110:113], v[156:159], v[188:191], v[110:113]
	v_mfma_f32_16x16x32_bf16 v[106:109], v[164:167], v[188:191], v[106:109]
	v_mfma_f32_16x16x32_bf16 v[102:105], v[156:159], v[196:199], v[102:105]
	v_mfma_f32_16x16x32_bf16 v[98:101], v[164:167], v[196:199], v[98:101]
	s_setprio 0
	s_barrier
	ds_read_b128 v[200:203], v223
	ds_read_b128 v[204:207], v223 offset:1024
	ds_read_b128 v[208:211], v223 offset:2048
	ds_read_b128 v[212:215], v223 offset:3072
	s_mov_b32 m0, s45
	s_add_u32 s98, s14, s94
	s_addc_u32 s99, s15, s95
	global_load_lds_dwordx4 v131, s[98:99]
	s_mov_b32 m0, s46
	s_add_u32 s98, s14, s72
	s_addc_u32 s99, s15, s73
	global_load_lds_dwordx4 v131, s[98:99]
	s_barrier
	s_waitcnt lgkmcnt(0)
	s_setprio 1
	s_waitcnt lgkmcnt(0)
	v_mfma_f32_16x16x32_bf16 v[94:97], v[200:203], v[168:171], v[94:97]
	v_mfma_f32_16x16x32_bf16 v[90:93], v[208:211], v[168:171], v[90:93]
	v_mfma_f32_16x16x32_bf16 v[86:89], v[200:203], v[176:179], v[86:89]
	v_mfma_f32_16x16x32_bf16 v[82:85], v[208:211], v[176:179], v[82:85]
	v_mfma_f32_16x16x32_bf16 v[78:81], v[200:203], v[184:187], v[78:81]
	v_mfma_f32_16x16x32_bf16 v[74:77], v[208:211], v[184:187], v[74:77]
	v_mfma_f32_16x16x32_bf16 v[70:73], v[200:203], v[192:195], v[70:73]
	v_mfma_f32_16x16x32_bf16 v[66:69], v[208:211], v[192:195], v[66:69]
	v_mfma_f32_16x16x32_bf16 v[94:97], v[204:207], v[172:175], v[94:97]
	v_mfma_f32_16x16x32_bf16 v[90:93], v[212:215], v[172:175], v[90:93]
	v_mfma_f32_16x16x32_bf16 v[86:89], v[204:207], v[180:183], v[86:89]
	v_mfma_f32_16x16x32_bf16 v[82:85], v[212:215], v[180:183], v[82:85]
	v_mfma_f32_16x16x32_bf16 v[78:81], v[204:207], v[188:191], v[78:81]
	v_mfma_f32_16x16x32_bf16 v[74:77], v[212:215], v[188:191], v[74:77]
	v_mfma_f32_16x16x32_bf16 v[70:73], v[204:207], v[196:199], v[70:73]
	v_mfma_f32_16x16x32_bf16 v[66:69], v[212:215], v[196:199], v[66:69]
	s_setprio 0
	s_barrier
	ds_read_b128 v[168:171], v143 offset:49152
	ds_read_b128 v[172:175], v143 offset:50176
	ds_read_b128 v[176:179], v143 offset:51200
	ds_read_b128 v[180:183], v143 offset:52224
	ds_read_b128 v[184:187], v143 offset:53248
	ds_read_b128 v[188:191], v143 offset:54272
	ds_read_b128 v[192:195], v143 offset:55296
	ds_read_b128 v[196:199], v143 offset:56320
	s_mov_b32 m0, s47
	s_add_u32 s98, s12, s94
	s_addc_u32 s99, s13, s95
	global_load_lds_dwordx4 v131, s[98:99]
	s_mov_b32 m0, s48
	s_add_u32 s98, s12, s72
	s_addc_u32 s99, s13, s73
	global_load_lds_dwordx4 v131, s[98:99]
	s_barrier
; #define LDA(dst, b, h) for (int m = 0; m < 4; ++m) for (int k = 0; k < 2; ++k) \
;     dst[m][k] = *reinterpret_cast<const bf16x8*>((char*)SA(b, h) + a_thr + (m * 2 + k) * 1024)
; #define LDB(dst, b, h) for (int n = 0; n < 2; ++n) for (int k = 0; k < 2; ++k) \
;     dst[n][k] = *reinterpret_cast<const bf16x8*>((char*)SB(b, h) + b_thr + (n * 2 + k) * 1024)
; #define MMA(ai, bj, At, Btf) do { __builtin_amdgcn_s_setprio(1); \
;     for (int m = 0; m < 4; ++m) for (int n = 0; n < 2; ++n) for (int k = 0; k < 2; ++k) \
;       acc[ai][bj][m][n] = __builtin_amdgcn_mfma_f32_16x16x32_bf16(Btf[n][k], At[m][k], acc[ai][bj][m][n], 0, 0, 0); \
;     __builtin_amdgcn_s_setprio(0); } while (0)
; #define WAIT_V(n) asm volatile("s_waitcnt vmcnt(" #n ")" ::: "memory")
; #define WAIT_L(n) asm volatile("s_waitcnt lgkmcnt(" #n ")" ::: "memory")
; #define BAR __builtin_amdgcn_s_barrier()
; #define SCHED __builtin_amdgcn_sched_barrier(0)
; template <bool OVL, bool PANEL = false, class Epi>
; __device__ __forceinline__ void gemm_phase(const bf16_t* __restrict__ A, long lda, const bf16_t* __restrict__ Bt, long ldb, int nM, int nN, int K,
;                                            const Epi& epi, bf16_t* shm, int w0) {
;     ...
;       BAR; WAIT_L(0); MMA(1, 0, At, B0); BAR; SCHED;
;       STAGE(SB(1, 1), Bt, ldb, boff, bcol + HALF, t + 3);
;       WAIT_V(6); BAR; MMA(1, 1, At, B1); BAR;
;     }
;     { LDB(B0, 0, 0); LDA(At, 0, 0); STAGE(SA(1, 1), A, lda, aoff, brow + HALF, nt - 1);
;       BAR; WAIT_L(0); MMA(0, 0, At, B0); BAR;
;       LDB(B1, 0, 1); BAR; WAIT_L(0); MMA(0, 1, At, B1); BAR;
;       LDA(At, 0, 1); WAIT_V(4); BAR; WAIT_L(0); MMA(1, 0, At, B0); MMA(1, 1, At, B1); BAR; }
	s_waitcnt lgkmcnt(0)
	s_setprio 1
	s_waitcnt lgkmcnt(0)
	v_mfma_f32_16x16x32_bf16 v[62:65], v[152:155], v[168:171], v[62:65]
	v_mfma_f32_16x16x32_bf16 v[58:61], v[160:163], v[168:171], v[58:61]
	v_mfma_f32_16x16x32_bf16 v[54:57], v[152:155], v[176:179], v[54:57]
	v_mfma_f32_16x16x32_bf16 v[50:53], v[160:163], v[176:179], v[50:53]
	v_mfma_f32_16x16x32_bf16 v[46:49], v[152:155], v[184:187], v[46:49]
	v_mfma_f32_16x16x32_bf16 v[42:45], v[160:163], v[184:187], v[42:45]
	v_mfma_f32_16x16x32_bf16 v[38:41], v[152:155], v[192:195], v[38:41]
	v_mfma_f32_16x16x32_bf16 v[34:37], v[160:163], v[192:195], v[34:37]
	v_mfma_f32_16x16x32_bf16 v[62:65], v[156:159], v[172:175], v[62:65]
	v_mfma_f32_16x16x32_bf16 v[58:61], v[164:167], v[172:175], v[58:61]
	v_mfma_f32_16x16x32_bf16 v[54:57], v[156:159], v[180:183], v[54:57]
	v_mfma_f32_16x16x32_bf16 v[50:53], v[164:167], v[180:183], v[50:53]
	v_mfma_f32_16x16x32_bf16 v[46:49], v[156:159], v[188:191], v[46:49]
	v_mfma_f32_16x16x32_bf16 v[42:45], v[164:167], v[188:191], v[42:45]
	v_mfma_f32_16x16x32_bf16 v[38:41], v[156:159], v[196:199], v[38:41]
	v_mfma_f32_16x16x32_bf16 v[34:37], v[164:167], v[196:199], v[34:37]
	s_setprio 0
	s_barrier
	s_mov_b32 m0, s49
	s_add_u32 s98, s14, s26
	s_addc_u32 s99, s15, s27
	global_load_lds_dwordx4 v131, s[98:99]
	s_mov_b32 m0, s50
	s_add_u32 s98, s14, s28
	s_addc_u32 s99, s15, s29
	global_load_lds_dwordx4 v131, s[98:99]
	s_waitcnt vmcnt(6)
	s_barrier
	s_setprio 1
	v_mfma_f32_16x16x32_bf16 v[30:33], v[200:203], v[168:171], v[30:33]
	v_mfma_f32_16x16x32_bf16 v[26:29], v[208:211], v[168:171], v[26:29]
	v_mfma_f32_16x16x32_bf16 v[22:25], v[200:203], v[176:179], v[22:25]
	v_mfma_f32_16x16x32_bf16 v[18:21], v[208:211], v[176:179], v[18:21]
	v_mfma_f32_16x16x32_bf16 v[14:17], v[200:203], v[184:187], v[14:17]
	v_mfma_f32_16x16x32_bf16 v[10:13], v[208:211], v[184:187], v[10:13]
	v_mfma_f32_16x16x32_bf16 v[6:9], v[200:203], v[192:195], v[6:9]
	v_mfma_f32_16x16x32_bf16 v[2:5], v[208:211], v[192:195], v[2:5]
	v_mfma_f32_16x16x32_bf16 v[30:33], v[204:207], v[172:175], v[30:33]
	v_mfma_f32_16x16x32_bf16 v[26:29], v[212:215], v[172:175], v[26:29]
	v_mfma_f32_16x16x32_bf16 v[22:25], v[204:207], v[180:183], v[22:25]
	v_mfma_f32_16x16x32_bf16 v[18:21], v[212:215], v[180:183], v[18:21]
	v_mfma_f32_16x16x32_bf16 v[14:17], v[204:207], v[188:191], v[14:17]
	v_mfma_f32_16x16x32_bf16 v[10:13], v[212:215], v[188:191], v[10:13]
	v_mfma_f32_16x16x32_bf16 v[6:9], v[204:207], v[196:199], v[6:9]
	v_mfma_f32_16x16x32_bf16 v[2:5], v[212:215], v[196:199], v[2:5]
	s_setprio 0
	s_add_i32 s21, s21, 2
	s_add_u32 s10, s10, 0x100
	s_addc_u32 s11, s11, 0
	s_cmp_lt_u32 s21, 12
	s_barrier
	s_cbranch_scc1 .LBB0_410
	v_add_u32_e32 v212, 16, v140
	v_add_u32_e32 v0, 0x10000, v212
	ds_read_b128 v[144:147], v0
	ds_read_b128 v[152:155], v0 offset:1024
	ds_read_b128 v[156:159], v0 offset:2048
	ds_read_b128 v[160:163], v0 offset:3072
	ds_read_b128 v[164:167], v143
	ds_read_b128 v[168:171], v143 offset:1024
	ds_read_b128 v[172:175], v143 offset:2048
	ds_read_b128 v[176:179], v143 offset:3072
	ds_read_b128 v[180:183], v143 offset:4096
	ds_read_b128 v[184:187], v143 offset:5120
	ds_read_b128 v[188:191], v143 offset:6144
	ds_read_b128 v[192:195], v143 offset:7168
	v_mov_b32_e32 v0, v131
	s_mov_b64 s[0:1], 0x40780
	v_lshl_add_u64 v[148:149], s[8:9], 0, v[0:1]
	v_lshl_add_u64 v[196:197], v[148:149], 0, s[0:1]
	v_readfirstlane_b32 s0, v150
	s_mov_b32 m0, s0
	s_mov_b64 s[0:1], 0x60780
	v_lshl_add_u64 v[148:149], v[148:149], 0, s[0:1]
	v_readfirstlane_b32 s0, v151
	global_load_lds_dwordx4 v[196:197], off
	s_mov_b32 m0, s0
	s_nop 0
	global_load_lds_dwordx4 v[148:149], off
	s_barrier
	s_waitcnt lgkmcnt(0)
	s_setprio 1
	s_waitcnt lgkmcnt(0)
	v_mfma_f32_16x16x32_bf16 v[126:129], v[144:147], v[164:167], v[126:129]
	v_mfma_f32_16x16x32_bf16 v[122:125], v[156:159], v[164:167], v[122:125]
	v_mfma_f32_16x16x32_bf16 v[118:121], v[144:147], v[172:175], v[118:121]
	v_mfma_f32_16x16x32_bf16 v[114:117], v[156:159], v[172:175], v[114:117]
	v_mfma_f32_16x16x32_bf16 v[110:113], v[144:147], v[180:183], v[110:113]
	v_mfma_f32_16x16x32_bf16 v[106:109], v[156:159], v[180:183], v[106:109]
	v_mfma_f32_16x16x32_bf16 v[102:105], v[144:147], v[188:191], v[102:105]
	v_mfma_f32_16x16x32_bf16 v[126:129], v[152:155], v[168:171], v[126:129]
	v_mfma_f32_16x16x32_bf16 v[122:125], v[160:163], v[168:171], v[122:125]
	v_mfma_f32_16x16x32_bf16 v[118:121], v[152:155], v[176:179], v[118:121]
	v_mfma_f32_16x16x32_bf16 v[114:117], v[160:163], v[176:179], v[114:117]
	v_mfma_f32_16x16x32_bf16 v[110:113], v[152:155], v[184:187], v[110:113]
	v_mfma_f32_16x16x32_bf16 v[106:109], v[160:163], v[184:187], v[106:109]
	v_mfma_f32_16x16x32_bf16 v[102:105], v[152:155], v[192:195], v[102:105]
	v_mfma_f32_16x16x32_bf16 v[98:101], v[156:159], v[188:191], v[98:101]
	v_mfma_f32_16x16x32_bf16 v[148:151], v[160:163], v[192:195], v[98:101]
	s_setprio 0
	v_add_u32_e32 v0, 0x14000, v212
	s_barrier
	s_nop 3
	ds_read_b128 v[98:101], v0
	ds_read_b128 v[196:199], v0 offset:1024
	ds_read_b128 v[200:203], v0 offset:2048
	ds_read_b128 v[204:207], v0 offset:3072
	s_barrier
; #define LDA(dst, b, h) for (int m = 0; m < 4; ++m) for (int k = 0; k < 2; ++k) \
;     dst[m][k] = *reinterpret_cast<const bf16x8*>((char*)SA(b, h) + a_thr + (m * 2 + k) * 1024)
; #define LDB(dst, b, h) for (int n = 0; n < 2; ++n) for (int k = 0; k < 2; ++k) \
;     dst[n][k] = *reinterpret_cast<const bf16x8*>((char*)SB(b, h) + b_thr + (n * 2 + k) * 1024)
; #define MMA(ai, bj, At, Btf) do { __builtin_amdgcn_s_setprio(1); \
;     for (int m = 0; m < 4; ++m) for (int n = 0; n < 2; ++n) for (int k = 0; k < 2; ++k) \
;       acc[ai][bj][m][n] = __builtin_amdgcn_mfma_f32_16x16x32_bf16(Btf[n][k], At[m][k], acc[ai][bj][m][n], 0, 0, 0); \
;     __builtin_amdgcn_s_setprio(0); } while (0)
; #define WAIT_V(n) asm volatile("s_waitcnt vmcnt(" #n ")" ::: "memory")
; #define WAIT_L(n) asm volatile("s_waitcnt lgkmcnt(" #n ")" ::: "memory")
; #define BAR __builtin_amdgcn_s_barrier()
; template <bool OVL, bool PANEL = false, class Epi>
; __device__ __forceinline__ void gemm_phase(const bf16_t* __restrict__ A, long lda, const bf16_t* __restrict__ Bt, long ldb, int nM, int nN, int K,
;                                            const Epi& epi, bf16_t* shm, int w0) {
;     ...
;       LDA(At, 0, 1); WAIT_V(4); BAR; WAIT_L(0); MMA(1, 0, At, B0); MMA(1, 1, At, B1); BAR; }
;     { LDB(B0, 1, 0); LDA(At, 1, 0); WAIT_V(2); BAR; WAIT_L(0); MMA(0, 0, At, B0); BAR;
;       LDB(B1, 1, 1); WAIT_V(0); BAR; WAIT_L(0); MMA(0, 1, At, B1); BAR;
	s_waitcnt lgkmcnt(0)
	s_setprio 1
	s_waitcnt lgkmcnt(0)
	v_mfma_f32_16x16x32_bf16 v[94:97], v[98:101], v[164:167], v[94:97]
	v_mfma_f32_16x16x32_bf16 v[86:89], v[98:101], v[172:175], v[86:89]
	v_mfma_f32_16x16x32_bf16 v[82:85], v[200:203], v[172:175], v[82:85]
	v_mfma_f32_16x16x32_bf16 v[78:81], v[98:101], v[180:183], v[78:81]
	v_mfma_f32_16x16x32_bf16 v[74:77], v[200:203], v[180:183], v[74:77]
	v_mfma_f32_16x16x32_bf16 v[94:97], v[196:199], v[168:171], v[94:97]
	v_mfma_f32_16x16x32_bf16 v[90:93], v[200:203], v[164:167], v[90:93]
	v_mfma_f32_16x16x32_bf16 v[86:89], v[196:199], v[176:179], v[86:89]
	v_mfma_f32_16x16x32_bf16 v[82:85], v[204:207], v[176:179], v[82:85]
	v_mfma_f32_16x16x32_bf16 v[78:81], v[196:199], v[184:187], v[78:81]
	v_mfma_f32_16x16x32_bf16 v[74:77], v[204:207], v[184:187], v[74:77]
	v_mfma_f32_16x16x32_bf16 v[70:73], v[98:101], v[188:191], v[70:73]
	v_mfma_f32_16x16x32_bf16 v[66:69], v[200:203], v[188:191], v[66:69]
	v_mfma_f32_16x16x32_bf16 v[164:167], v[204:207], v[168:171], v[90:93]
	v_mfma_f32_16x16x32_bf16 v[168:171], v[196:199], v[192:195], v[70:73]
	v_mfma_f32_16x16x32_bf16 v[172:175], v[204:207], v[192:195], v[66:69]
	s_setprio 0
	s_barrier
	s_nop 2
	ds_read_b128 v[66:69], v143 offset:16384
	ds_read_b128 v[70:73], v143 offset:17408
	ds_read_b128 v[90:93], v143 offset:18432
	ds_read_b128 v[176:179], v143 offset:19456
	ds_read_b128 v[180:183], v143 offset:20480
	ds_read_b128 v[184:187], v143 offset:21504
	ds_read_b128 v[188:191], v143 offset:22528
	ds_read_b128 v[192:195], v143 offset:23552
	s_waitcnt vmcnt(4)
	s_barrier
	s_waitcnt lgkmcnt(0)
	s_setprio 1
	s_waitcnt lgkmcnt(0)
	v_mfma_f32_16x16x32_bf16 v[62:65], v[144:147], v[66:69], v[62:65]
	v_mfma_f32_16x16x32_bf16 v[54:57], v[144:147], v[90:93], v[54:57]
	v_mfma_f32_16x16x32_bf16 v[50:53], v[156:159], v[90:93], v[50:53]
	v_mfma_f32_16x16x32_bf16 v[46:49], v[144:147], v[180:183], v[46:49]
	v_mfma_f32_16x16x32_bf16 v[42:45], v[156:159], v[180:183], v[42:45]
	v_mfma_f32_16x16x32_bf16 v[38:41], v[144:147], v[188:191], v[38:41]
	v_mfma_f32_16x16x32_bf16 v[34:37], v[156:159], v[188:191], v[34:37]
	v_mfma_f32_16x16x32_bf16 v[62:65], v[152:155], v[70:73], v[62:65]
	v_mfma_f32_16x16x32_bf16 v[58:61], v[156:159], v[66:69], v[58:61]
	v_mfma_f32_16x16x32_bf16 v[54:57], v[152:155], v[176:179], v[54:57]
	v_mfma_f32_16x16x32_bf16 v[50:53], v[160:163], v[176:179], v[50:53]
	v_mfma_f32_16x16x32_bf16 v[46:49], v[152:155], v[184:187], v[46:49]
	v_mfma_f32_16x16x32_bf16 v[42:45], v[160:163], v[184:187], v[42:45]
	v_mfma_f32_16x16x32_bf16 v[38:41], v[152:155], v[192:195], v[38:41]
	v_mfma_f32_16x16x32_bf16 v[34:37], v[160:163], v[192:195], v[34:37]
	v_mfma_f32_16x16x32_bf16 v[208:211], v[160:163], v[70:73], v[58:61]
	s_setprio 0
	s_setprio 1
	v_mfma_f32_16x16x32_bf16 v[30:33], v[98:101], v[66:69], v[30:33]
	v_mfma_f32_16x16x32_bf16 v[26:29], v[200:203], v[66:69], v[26:29]
	v_mfma_f32_16x16x32_bf16 v[22:25], v[98:101], v[90:93], v[22:25]
	v_mfma_f32_16x16x32_bf16 v[18:21], v[200:203], v[90:93], v[18:21]
	v_mfma_f32_16x16x32_bf16 v[14:17], v[98:101], v[180:183], v[14:17]
	v_mfma_f32_16x16x32_bf16 v[10:13], v[200:203], v[180:183], v[10:13]
	v_mfma_f32_16x16x32_bf16 v[6:9], v[98:101], v[188:191], v[6:9]
	v_mfma_f32_16x16x32_bf16 v[2:5], v[200:203], v[188:191], v[2:5]
	v_mfma_f32_16x16x32_bf16 v[30:33], v[196:199], v[70:73], v[30:33]
	v_mfma_f32_16x16x32_bf16 v[26:29], v[204:207], v[70:73], v[26:29]
	v_mfma_f32_16x16x32_bf16 v[22:25], v[196:199], v[176:179], v[22:25]
	v_mfma_f32_16x16x32_bf16 v[18:21], v[204:207], v[176:179], v[18:21]
	v_mfma_f32_16x16x32_bf16 v[14:17], v[196:199], v[184:187], v[14:17]
	v_mfma_f32_16x16x32_bf16 v[10:13], v[204:207], v[184:187], v[10:13]
	v_mfma_f32_16x16x32_bf16 v[6:9], v[196:199], v[192:195], v[6:9]
	v_mfma_f32_16x16x32_bf16 v[2:5], v[204:207], v[192:195], v[2:5]
	s_setprio 0
	v_add_u32_e32 v0, 0x18000, v212
	s_barrier
	ds_read_b128 v[144:147], v0
	ds_read_b128 v[152:155], v0 offset:1024
	ds_read_b128 v[156:159], v0 offset:2048
	ds_read_b128 v[160:163], v0 offset:3072
	ds_read_b128 v[58:61], v143 offset:32768
	ds_read_b128 v[66:69], v143 offset:33792
	ds_read_b128 v[70:73], v143 offset:34816
	ds_read_b128 v[176:179], v143 offset:35840
	ds_read_b128 v[180:183], v143 offset:36864
	ds_read_b128 v[184:187], v143 offset:37888
	ds_read_b128 v[188:191], v143 offset:38912
	ds_read_b128 v[192:195], v143 offset:39936
	s_waitcnt vmcnt(2)
	s_barrier
; #define LDA(dst, b, h) for (int m = 0; m < 4; ++m) for (int k = 0; k < 2; ++k) \
;     dst[m][k] = *reinterpret_cast<const bf16x8*>((char*)SA(b, h) + a_thr + (m * 2 + k) * 1024)
; #define LDB(dst, b, h) for (int n = 0; n < 2; ++n) for (int k = 0; k < 2; ++k) \
;     dst[n][k] = *reinterpret_cast<const bf16x8*>((char*)SB(b, h) + b_thr + (n * 2 + k) * 1024)
; #define MMA(ai, bj, At, Btf) do { __builtin_amdgcn_s_setprio(1); \
;     for (int m = 0; m < 4; ++m) for (int n = 0; n < 2; ++n) for (int k = 0; k < 2; ++k) \
;       acc[ai][bj][m][n] = __builtin_amdgcn_mfma_f32_16x16x32_bf16(Btf[n][k], At[m][k], acc[ai][bj][m][n], 0, 0, 0); \
;     __builtin_amdgcn_s_setprio(0); } while (0)
; #define WAIT_V(n) asm volatile("s_waitcnt vmcnt(" #n ")" ::: "memory")
; #define WAIT_L(n) asm volatile("s_waitcnt lgkmcnt(" #n ")" ::: "memory")
; #define BAR __builtin_amdgcn_s_barrier()
; template <bool OVL, bool PANEL = false, class Epi>
; __device__ __forceinline__ void gemm_phase(const bf16_t* __restrict__ A, long lda, const bf16_t* __restrict__ Bt, long ldb, int nM, int nN, int K,
;                                            const Epi& epi, bf16_t* shm, int w0) {
;     ...
;     { LDB(B0, 1, 0); LDA(At, 1, 0); WAIT_V(2); BAR; WAIT_L(0); MMA(0, 0, At, B0); BAR;
;       LDB(B1, 1, 1); WAIT_V(0); BAR; WAIT_L(0); MMA(0, 1, At, B1); BAR;
;       LDA(At, 1, 1); BAR; WAIT_L(0); MMA(1, 0, At, B0); MMA(1, 1, At, B1); BAR; }
;     if (wr == 0) BAR;
	s_waitcnt lgkmcnt(0)
	s_setprio 1
	s_waitcnt lgkmcnt(0)
	v_mfma_f32_16x16x32_bf16 v[90:93], v[144:147], v[58:61], v[126:129]
	v_mfma_f32_16x16x32_bf16 v[126:129], v[152:155], v[66:69], v[90:93]
	v_mfma_f32_16x16x32_bf16 v[90:93], v[156:159], v[58:61], v[122:125]
	v_mfma_f32_16x16x32_bf16 v[122:125], v[160:163], v[66:69], v[90:93]
	v_mfma_f32_16x16x32_bf16 v[90:93], v[144:147], v[70:73], v[118:121]
	v_mfma_f32_16x16x32_bf16 v[118:121], v[152:155], v[176:179], v[90:93]
	v_mfma_f32_16x16x32_bf16 v[90:93], v[156:159], v[70:73], v[114:117]
	v_mfma_f32_16x16x32_bf16 v[114:117], v[160:163], v[176:179], v[90:93]
	v_mfma_f32_16x16x32_bf16 v[90:93], v[144:147], v[180:183], v[110:113]
	v_mfma_f32_16x16x32_bf16 v[110:113], v[152:155], v[184:187], v[90:93]
	v_mfma_f32_16x16x32_bf16 v[90:93], v[156:159], v[180:183], v[106:109]
	v_mfma_f32_16x16x32_bf16 v[106:109], v[160:163], v[184:187], v[90:93]
	v_mfma_f32_16x16x32_bf16 v[90:93], v[144:147], v[188:191], v[102:105]
	v_mfma_f32_16x16x32_bf16 v[98:101], v[152:155], v[192:195], v[90:93]
	v_mfma_f32_16x16x32_bf16 v[90:93], v[156:159], v[188:191], v[148:151]
	v_mfma_f32_16x16x32_bf16 v[90:93], v[160:163], v[192:195], v[90:93]
	s_setprio 0
	v_add_u32_e32 v0, 0x1c000, v212
	s_barrier
	ds_read_b128 v[148:151], v0
	ds_read_b128 v[196:199], v0 offset:1024
	ds_read_b128 v[200:203], v0 offset:2048
	ds_read_b128 v[204:207], v0 offset:3072
	s_waitcnt vmcnt(0)
	s_barrier
	s_waitcnt lgkmcnt(0)
	s_setprio 1
	s_waitcnt lgkmcnt(0)
	v_mfma_f32_16x16x32_bf16 v[94:97], v[148:151], v[58:61], v[94:97]
	v_mfma_f32_16x16x32_bf16 v[58:61], v[200:203], v[58:61], v[164:167]
	v_mfma_f32_16x16x32_bf16 v[102:105], v[196:199], v[66:69], v[94:97]
	v_mfma_f32_16x16x32_bf16 v[94:97], v[204:207], v[66:69], v[58:61]
	v_mfma_f32_16x16x32_bf16 v[58:61], v[148:151], v[70:73], v[86:89]
	v_mfma_f32_16x16x32_bf16 v[86:89], v[196:199], v[176:179], v[58:61]
	v_mfma_f32_16x16x32_bf16 v[58:61], v[200:203], v[70:73], v[82:85]
	v_mfma_f32_16x16x32_bf16 v[82:85], v[204:207], v[176:179], v[58:61]
	v_mfma_f32_16x16x32_bf16 v[58:61], v[148:151], v[180:183], v[78:81]
	v_mfma_f32_16x16x32_bf16 v[78:81], v[196:199], v[184:187], v[58:61]
	v_mfma_f32_16x16x32_bf16 v[58:61], v[200:203], v[180:183], v[74:77]
	v_mfma_f32_16x16x32_bf16 v[70:73], v[204:207], v[184:187], v[58:61]
	v_mfma_f32_16x16x32_bf16 v[58:61], v[148:151], v[188:191], v[168:171]
	v_mfma_f32_16x16x32_bf16 v[66:69], v[196:199], v[192:195], v[58:61]
	v_mfma_f32_16x16x32_bf16 v[58:61], v[200:203], v[188:191], v[172:175]
	v_mfma_f32_16x16x32_bf16 v[58:61], v[204:207], v[192:195], v[58:61]
	s_setprio 0
	s_barrier
	ds_read_b128 v[164:167], v143 offset:49152
	ds_read_b128 v[168:171], v143 offset:50176
	ds_read_b128 v[172:175], v143 offset:51200
	ds_read_b128 v[176:179], v143 offset:52224
	ds_read_b128 v[180:183], v143 offset:53248
	ds_read_b128 v[184:187], v143 offset:54272
	ds_read_b128 v[188:191], v143 offset:55296
	ds_read_b128 v[192:195], v143 offset:56320
	s_barrier
	s_waitcnt lgkmcnt(0)
	s_setprio 1
	s_waitcnt lgkmcnt(0)
	v_mfma_f32_16x16x32_bf16 v[62:65], v[144:147], v[164:167], v[62:65]
	v_mfma_f32_16x16x32_bf16 v[74:77], v[152:155], v[168:171], v[62:65]
	v_mfma_f32_16x16x32_bf16 v[62:65], v[156:159], v[164:167], v[208:211]
	v_mfma_f32_16x16x32_bf16 v[54:57], v[144:147], v[172:175], v[54:57]
	v_mfma_f32_16x16x32_bf16 v[50:53], v[156:159], v[172:175], v[50:53]
	v_mfma_f32_16x16x32_bf16 v[46:49], v[144:147], v[180:183], v[46:49]
	v_mfma_f32_16x16x32_bf16 v[42:45], v[156:159], v[180:183], v[42:45]
	v_mfma_f32_16x16x32_bf16 v[38:41], v[144:147], v[188:191], v[38:41]
	v_mfma_f32_16x16x32_bf16 v[34:37], v[156:159], v[188:191], v[34:37]
	v_mfma_f32_16x16x32_bf16 v[62:65], v[160:163], v[168:171], v[62:65]
	v_mfma_f32_16x16x32_bf16 v[54:57], v[152:155], v[176:179], v[54:57]
	v_mfma_f32_16x16x32_bf16 v[50:53], v[160:163], v[176:179], v[50:53]
	v_mfma_f32_16x16x32_bf16 v[46:49], v[152:155], v[184:187], v[46:49]
	v_mfma_f32_16x16x32_bf16 v[42:45], v[160:163], v[184:187], v[42:45]
	v_mfma_f32_16x16x32_bf16 v[38:41], v[152:155], v[192:195], v[38:41]
	v_mfma_f32_16x16x32_bf16 v[34:37], v[160:163], v[192:195], v[34:37]
	s_setprio 0
	s_setprio 1
	v_mfma_f32_16x16x32_bf16 v[30:33], v[148:151], v[164:167], v[30:33]
	v_mfma_f32_16x16x32_bf16 v[26:29], v[200:203], v[164:167], v[26:29]
	v_mfma_f32_16x16x32_bf16 v[22:25], v[148:151], v[172:175], v[22:25]
	v_mfma_f32_16x16x32_bf16 v[18:21], v[200:203], v[172:175], v[18:21]
	v_mfma_f32_16x16x32_bf16 v[14:17], v[148:151], v[180:183], v[14:17]
	v_mfma_f32_16x16x32_bf16 v[10:13], v[200:203], v[180:183], v[10:13]
	v_mfma_f32_16x16x32_bf16 v[6:9], v[148:151], v[188:191], v[6:9]
	v_mfma_f32_16x16x32_bf16 v[2:5], v[200:203], v[188:191], v[2:5]
	v_mfma_f32_16x16x32_bf16 v[30:33], v[196:199], v[168:171], v[30:33]
	v_mfma_f32_16x16x32_bf16 v[26:29], v[204:207], v[168:171], v[26:29]
	v_mfma_f32_16x16x32_bf16 v[22:25], v[196:199], v[176:179], v[22:25]
	v_mfma_f32_16x16x32_bf16 v[18:21], v[204:207], v[176:179], v[18:21]
	v_mfma_f32_16x16x32_bf16 v[14:17], v[196:199], v[184:187], v[14:17]
	v_mfma_f32_16x16x32_bf16 v[10:13], v[204:207], v[184:187], v[10:13]
	v_mfma_f32_16x16x32_bf16 v[6:9], v[196:199], v[192:195], v[6:9]
	v_mfma_f32_16x16x32_bf16 v[2:5], v[204:207], v[192:195], v[2:5]
	s_setprio 0
	s_barrier
	s_and_saveexec_b64 s[0:1], s[6:7]
	s_cbranch_execz .LBB0_413
	s_barrier

; #define WAIT_V(n) asm volatile("s_waitcnt vmcnt(" #n ")" ::: "memory")
; #define BAR __builtin_amdgcn_s_barrier()
; template <bool OVL, bool PANEL = false, class Epi>
; __device__ __forceinline__ void gemm_phase(const bf16_t* __restrict__ A, long lda, const bf16_t* __restrict__ Bt, long ldb, int nM, int nN, int K,
;                                            const Epi& epi, bf16_t* shm, int w0) {
;     ...
;   if (have) { const int brow = pm * BM, bcol = pn * BM;
;     STAGE(SB(0, 0), Bt, ldb, boff, bcol, 0); STAGE(SA(0, 0), A, lda, aoff, brow, 0);
;     STAGE(SB(0, 1), Bt, ldb, boff, bcol + HALF, 0); STAGE(SA(0, 1), A, lda, aoff, brow + HALF, 0); }
;   for (int it = 0; have; ++it) {
;     const int brow = pm * BM, bcol = pn * BM;
;     f32x4 acc[2][2][4][2];
; #pragma unroll
;     for (int a0 = 0; a0 < 2; ++a0)
; #pragma unroll
;       for (int a1 = 0; a1 < 2; ++a1)
; #pragma unroll
;         for (int a2 = 0; a2 < 4; ++a2)
; #pragma unroll
;           for (int a3 = 0; a3 < 2; ++a3) acc[a0][a1][a2][a3] = (f32x4){0.f, 0.f, 0.f, 0.f};
;     bf16x8 At[4][2], B0[2][2], B1[2][2];
;     if (wr == 1) BAR;
;     WAIT_V(4); BAR;
;     STAGE(SB(1, 0), Bt, ldb, boff, bcol, 1); STAGE(SA(1, 0), A, lda, aoff, brow, 1); STAGE(SB(1, 1), Bt, ldb, boff, bcol + HALF, 1);
;     WAIT_V(6); BAR;
.LBB0_471:
	s_or_b64 exec, exec, s[0:1]
	s_lshl_b32 s2, s25, 18
	v_readlane_b32 s44, v252, 3
	s_lshl_b32 s82, s4, 8
	s_lshl_b64 s[0:1], s[2:3], 1
	v_readlane_b32 s58, v252, 17
	v_readlane_b32 s59, v252, 18
	s_add_u32 s6, s58, s0
	s_addc_u32 s7, s59, s1
	v_mov_b32_e32 v0, v221
	v_add_u32_e32 v130, s96, v220
	s_waitcnt vmcnt(4)
	s_barrier
	v_readlane_b32 s45, v252, 4
	v_readlane_b32 s46, v252, 5
	v_readlane_b32 s47, v252, 6
	v_readlane_b32 s48, v252, 7
	v_readlane_b32 s49, v252, 8
	v_readlane_b32 s50, v252, 9
	v_readlane_b32 s51, v252, 10
	v_readlane_b32 s52, v252, 11
	v_readlane_b32 s53, v252, 12
	v_readlane_b32 s54, v252, 13
	v_readlane_b32 s55, v252, 14
	v_readlane_b32 s56, v252, 15
	v_readlane_b32 s57, v252, 16
	s_mov_b64 s[12:13], 0x80
	v_lshl_add_u64 v[2:3], s[6:7], 0, v[0:1]
	v_readfirstlane_b32 s0, v130
	v_add_u32_e32 v131, 0x2000, v130
	v_lshl_add_u64 v[4:5], v[2:3], 0, s[12:13]
	s_mov_b32 m0, s0
	v_readfirstlane_b32 s0, v131
	s_ashr_i32 s83, s82, 31
	v_readlane_b32 s44, v252, 20
	global_load_lds_dwordx4 v[4:5], off
	s_mov_b32 m0, s0
	s_lshl_b64 s[0:1], s[82:83], 11
	v_readlane_b32 s50, v252, 26
	s_mov_b64 s[14:15], 0x20080
	v_readlane_b32 s51, v252, 27
	s_add_u32 s8, s50, s0
	v_lshl_add_u64 v[2:3], v[2:3], 0, s[14:15]
	s_addc_u32 s9, s51, s1
	v_mov_b32_e32 v0, v221
	v_add_u32_e32 v132, 0x8000, v234
	global_load_lds_dwordx4 v[2:3], off
	v_readfirstlane_b32 s0, v132
	v_lshl_add_u64 v[2:3], s[8:9], 0, v[0:1]
	v_add_u32_e32 v133, 0xa000, v234
	v_lshl_add_u64 v[4:5], v[2:3], 0, s[12:13]
	s_mov_b32 m0, s0
	v_readfirstlane_b32 s0, v133
	global_load_lds_dwordx4 v[4:5], off
	v_lshl_add_u64 v[2:3], v[2:3], 0, s[14:15]
	s_mov_b32 m0, s0
	v_mov_b32_e32 v0, v221
	v_add_u32_e32 v134, s75, v220
	global_load_lds_dwordx4 v[2:3], off
	s_mov_b64 s[12:13], 0x40080
	v_lshl_add_u64 v[2:3], s[6:7], 0, v[0:1]
	v_readfirstlane_b32 s0, v134
	v_add_u32_e32 v135, 0x2000, v134
	v_lshl_add_u64 v[4:5], v[2:3], 0, s[12:13]
	s_mov_b32 m0, s0
	v_readfirstlane_b32 s0, v135
	global_load_lds_dwordx4 v[4:5], off
	v_lshl_add_u64 v[2:3], v[2:3], 0, s[36:37]
	s_mov_b32 m0, s0
	s_mov_b32 s2, -2
	global_load_lds_dwordx4 v[2:3], off
	s_waitcnt vmcnt(6)
	v_mov_b32_e32 v2, 0
	s_mov_b64 s[80:81], 0
	v_mov_b32_e32 v3, v2
	v_mov_b32_e32 v4, v2
	v_mov_b32_e32 v5, v2
	v_mov_b32_e32 v6, v2
	v_mov_b32_e32 v7, v2
	v_mov_b32_e32 v8, v2
	v_mov_b32_e32 v9, v2
	s_waitcnt vmcnt(0)
	v_mov_b32_e32 v10, v2
	v_mov_b32_e32 v11, v2
	v_mov_b32_e32 v12, v2
	v_mov_b32_e32 v13, v2
	s_waitcnt lgkmcnt(0)
	v_mov_b32_e32 v14, v2
	v_mov_b32_e32 v15, v2
	v_mov_b32_e32 v16, v2
	v_mov_b32_e32 v17, v2
	v_mov_b32_e32 v18, v2
	v_mov_b32_e32 v19, v2
	v_mov_b32_e32 v20, v2
	v_mov_b32_e32 v21, v2
	v_mov_b32_e32 v22, v2
	v_mov_b32_e32 v23, v2
	v_mov_b32_e32 v24, v2
	v_mov_b32_e32 v25, v2
	v_mov_b32_e32 v26, v2
	v_mov_b32_e32 v27, v2
	v_mov_b32_e32 v28, v2
	v_mov_b32_e32 v29, v2
	v_mov_b32_e32 v30, v2
	v_mov_b32_e32 v31, v2
	v_mov_b32_e32 v32, v2
	v_mov_b32_e32 v33, v2
	v_mov_b32_e32 v34, v2
	v_mov_b32_e32 v35, v2
	v_mov_b32_e32 v36, v2
	v_mov_b32_e32 v37, v2
	v_mov_b32_e32 v38, v2
	v_mov_b32_e32 v39, v2
	v_mov_b32_e32 v40, v2
	v_mov_b32_e32 v41, v2
	v_mov_b32_e32 v42, v2
	v_mov_b32_e32 v43, v2
	v_mov_b32_e32 v44, v2
	v_mov_b32_e32 v45, v2
	v_mov_b32_e32 v46, v2
	v_mov_b32_e32 v47, v2
	v_mov_b32_e32 v48, v2
	v_mov_b32_e32 v49, v2
	v_mov_b32_e32 v50, v2
	v_mov_b32_e32 v51, v2
	v_mov_b32_e32 v52, v2
	v_mov_b32_e32 v53, v2
	v_mov_b32_e32 v54, v2
	v_mov_b32_e32 v55, v2
	v_mov_b32_e32 v56, v2
	v_mov_b32_e32 v57, v2
	v_mov_b32_e32 v58, v2
	v_mov_b32_e32 v59, v2
	v_mov_b32_e32 v60, v2
	v_mov_b32_e32 v61, v2
	v_mov_b32_e32 v62, v2
	v_mov_b32_e32 v63, v2
	v_mov_b32_e32 v64, v2
	v_mov_b32_e32 v65, v2
	v_mov_b32_e32 v66, v2
	v_mov_b32_e32 v67, v2
	v_mov_b32_e32 v68, v2
	v_mov_b32_e32 v69, v2
	v_mov_b32_e32 v70, v2
	v_mov_b32_e32 v71, v2
	v_mov_b32_e32 v72, v2
	v_mov_b32_e32 v73, v2
	v_mov_b32_e32 v74, v2
	v_mov_b32_e32 v75, v2
	v_mov_b32_e32 v76, v2
	v_mov_b32_e32 v77, v2
	v_mov_b32_e32 v78, v2
	v_mov_b32_e32 v79, v2
	v_mov_b32_e32 v80, v2
	v_mov_b32_e32 v81, v2
	v_mov_b32_e32 v82, v2
	v_mov_b32_e32 v83, v2
	v_mov_b32_e32 v84, v2
	v_mov_b32_e32 v85, v2
	v_mov_b32_e32 v86, v2
	v_mov_b32_e32 v87, v2
	v_mov_b32_e32 v88, v2
	v_mov_b32_e32 v89, v2
	v_mov_b32_e32 v90, v2
	v_mov_b32_e32 v91, v2
	v_mov_b32_e32 v92, v2
	v_mov_b32_e32 v93, v2
	v_mov_b32_e32 v94, v2
	v_mov_b32_e32 v95, v2
	v_mov_b32_e32 v96, v2
	v_mov_b32_e32 v97, v2
	v_mov_b32_e32 v98, v2
	v_mov_b32_e32 v99, v2
	v_mov_b32_e32 v100, v2
	v_mov_b32_e32 v101, v2
	v_mov_b32_e32 v102, v2
	v_mov_b32_e32 v103, v2
	v_mov_b32_e32 v104, v2
	v_mov_b32_e32 v105, v2
	v_mov_b32_e32 v106, v2
	v_mov_b32_e32 v107, v2
	v_mov_b32_e32 v108, v2
	v_mov_b32_e32 v109, v2
	v_mov_b32_e32 v110, v2
	v_mov_b32_e32 v111, v2
	v_mov_b32_e32 v112, v2
	v_mov_b32_e32 v113, v2
	v_mov_b32_e32 v114, v2
	v_mov_b32_e32 v115, v2
	v_mov_b32_e32 v116, v2
	v_mov_b32_e32 v117, v2
	v_mov_b32_e32 v118, v2
	v_mov_b32_e32 v119, v2
	v_mov_b32_e32 v120, v2
	v_mov_b32_e32 v121, v2
	v_mov_b32_e32 v122, v2
	v_mov_b32_e32 v123, v2
	v_mov_b32_e32 v124, v2
	v_mov_b32_e32 v125, v2
	v_mov_b32_e32 v126, v2
	v_mov_b32_e32 v127, v2
	v_mov_b32_e32 v128, v2
	v_mov_b32_e32 v129, v2
	s_mov_b64 s[14:15], 0x40180
	s_mov_b64 s[18:19], 0x60180
	v_readlane_b32 s45, v252, 21
	v_readlane_b32 s46, v252, 22
	v_readlane_b32 s47, v252, 23
	v_readlane_b32 s48, v252, 24
	v_readlane_b32 s49, v252, 25
	v_readlane_b32 s52, v252, 28
	v_readlane_b32 s53, v252, 29
	v_readlane_b32 s54, v252, 30
	v_readlane_b32 s55, v252, 31
	v_readlane_b32 s56, v252, 32
	v_readlane_b32 s57, v252, 33
	v_readlane_b32 s58, v252, 34
	v_readlane_b32 s59, v252, 35
	s_barrier
	v_add_u32_e32 v206, s20, v240
	v_readfirstlane_b32 s16, v234
	s_add_u32 s16, s16, 0xc000
	v_readfirstlane_b32 s32, v234
	s_add_u32 s32, s32, 0xe000
	v_add_u32_e32 v207, s33, v240
	v_readfirstlane_b32 s44, v222
	v_readfirstlane_b32 s45, v223
	v_readfirstlane_b32 s46, v234
	v_readfirstlane_b32 s47, v235
	v_readfirstlane_b32 s48, v236
	v_readfirstlane_b32 s49, v237
	v_add_u32_e32 v208, s96, v240
	v_readfirstlane_b32 s50, v238
	v_readfirstlane_b32 s51, v239
	v_add_u32_e32 v209, s75, v240
	v_readfirstlane_b32 s52, v130
	v_readfirstlane_b32 s53, v131
	v_readfirstlane_b32 s54, v132
	v_readfirstlane_b32 s55, v133
	v_readfirstlane_b32 s56, v134
	v_readfirstlane_b32 s57, v135
	v_add_u32_e32 v136, 0xc000, v234
	v_add_u32_e32 v137, 0xe000, v234
; #define LDA(dst, b, h) for (int m = 0; m < 4; ++m) for (int k = 0; k < 2; ++k) \
;     dst[m][k] = *reinterpret_cast<const bf16x8*>((char*)SA(b, h) + a_thr + (m * 2 + k) * 1024)
; #define LDB(dst, b, h) for (int n = 0; n < 2; ++n) for (int k = 0; k < 2; ++k) \
;     dst[n][k] = *reinterpret_cast<const bf16x8*>((char*)SB(b, h) + b_thr + (n * 2 + k) * 1024)
; #define MMA(ai, bj, At, Btf) do { __builtin_amdgcn_s_setprio(1); \
;     for (int m = 0; m < 4; ++m) for (int n = 0; n < 2; ++n) for (int k = 0; k < 2; ++k) \
;       acc[ai][bj][m][n] = __builtin_amdgcn_mfma_f32_16x16x32_bf16(Btf[n][k], At[m][k], acc[ai][bj][m][n], 0, 0, 0); \
;     __builtin_amdgcn_s_setprio(0); } while (0)
; #define WAIT_V(n) asm volatile("s_waitcnt vmcnt(" #n ")" ::: "memory")
; #define WAIT_L(n) asm volatile("s_waitcnt lgkmcnt(" #n ")" ::: "memory")
; #define BAR __builtin_amdgcn_s_barrier()
; #define SCHED __builtin_amdgcn_sched_barrier(0)
; template <bool OVL, bool PANEL = false, class Epi>
; __device__ __forceinline__ void gemm_phase(const bf16_t* __restrict__ A, long lda, const bf16_t* __restrict__ Bt, long ldb, int nM, int nN, int K,
;                                            const Epi& epi, bf16_t* shm, int w0) {
;     ...
;     for (int t = 0; t < nt - 2; t += 2) {
;       LDB(B0, 0, 0); SCHED; LDA(At, 0, 0); STAGE(SA(1, 1), A, lda, aoff, brow + HALF, t + 1);
;       WAIT_L(8); BAR; WAIT_L(0); MMA(0, 0, At, B0); BAR; SCHED;
;       LDB(B1, 0, 1); STAGE(SB(0, 0), Bt, ldb, boff, bcol, t + 2);
;       BAR; WAIT_L(0); MMA(0, 1, At, B1); BAR;
;       LDA(At, 0, 1); STAGE(SA(0, 0), A, lda, aoff, brow, t + 2);
;       BAR; WAIT_L(0); MMA(1, 0, At, B0); BAR; SCHED;
;       STAGE(SB(0, 1), Bt, ldb, boff, bcol + HALF, t + 2);
;       WAIT_V(6); BAR; MMA(1, 1, At, B1); BAR;
.LBB0_472:
	ds_read_b128 v[138:141], v206
	ds_read_b128 v[142:145], v206 offset:1024
	ds_read_b128 v[146:149], v206 offset:2048
	ds_read_b128 v[150:153], v206 offset:3072
	s_add_u32 vcc_lo, s8, s80
	s_addc_u32 vcc_hi, s9, s81
	ds_read_b128 v[154:157], v241
	ds_read_b128 v[158:161], v241 offset:1024
	ds_read_b128 v[162:165], v241 offset:2048
	ds_read_b128 v[166:169], v241 offset:3072
	ds_read_b128 v[170:173], v241 offset:4096
	ds_read_b128 v[174:177], v241 offset:5120
	ds_read_b128 v[178:181], v241 offset:6144
	ds_read_b128 v[182:185], v241 offset:7168
	s_mov_b32 m0, s16
	s_add_u32 s98, vcc_lo, s12
	s_addc_u32 s99, vcc_hi, s13
	global_load_lds_dwordx4 v221, s[98:99]
	s_mov_b32 m0, s32
	s_add_u32 s98, vcc_lo, s36
	s_addc_u32 s99, vcc_hi, s37
	global_load_lds_dwordx4 v221, s[98:99]
	s_waitcnt lgkmcnt(8)
	s_barrier
	s_waitcnt lgkmcnt(0)
	s_setprio 1
	s_waitcnt lgkmcnt(0)
	v_mfma_f32_16x16x32_bf16 v[126:129], v[138:141], v[154:157], v[126:129]
	v_mfma_f32_16x16x32_bf16 v[122:125], v[146:149], v[154:157], v[122:125]
	v_mfma_f32_16x16x32_bf16 v[118:121], v[138:141], v[162:165], v[118:121]
	v_mfma_f32_16x16x32_bf16 v[114:117], v[146:149], v[162:165], v[114:117]
	v_mfma_f32_16x16x32_bf16 v[110:113], v[138:141], v[170:173], v[110:113]
	v_mfma_f32_16x16x32_bf16 v[106:109], v[146:149], v[170:173], v[106:109]
	v_mfma_f32_16x16x32_bf16 v[102:105], v[138:141], v[178:181], v[102:105]
	v_mfma_f32_16x16x32_bf16 v[98:101], v[146:149], v[178:181], v[98:101]
	v_mfma_f32_16x16x32_bf16 v[126:129], v[142:145], v[158:161], v[126:129]
	v_mfma_f32_16x16x32_bf16 v[122:125], v[150:153], v[158:161], v[122:125]
	v_mfma_f32_16x16x32_bf16 v[118:121], v[142:145], v[166:169], v[118:121]
	v_mfma_f32_16x16x32_bf16 v[114:117], v[150:153], v[166:169], v[114:117]
	v_mfma_f32_16x16x32_bf16 v[110:113], v[142:145], v[174:177], v[110:113]
	v_mfma_f32_16x16x32_bf16 v[106:109], v[150:153], v[174:177], v[106:109]
	v_mfma_f32_16x16x32_bf16 v[102:105], v[142:145], v[182:185], v[102:105]
	v_mfma_f32_16x16x32_bf16 v[98:101], v[150:153], v[182:185], v[98:101]
	s_setprio 0
	s_barrier
	s_add_u32 s0, s6, s80
	ds_read_b128 v[186:189], v207
	ds_read_b128 v[190:193], v207 offset:1024
	ds_read_b128 v[194:197], v207 offset:2048
	ds_read_b128 v[198:201], v207 offset:3072
	s_addc_u32 s1, s7, s81
	s_mov_b32 m0, s44
	s_add_u32 s98, s0, s34
	s_addc_u32 s99, s1, s35
	global_load_lds_dwordx4 v221, s[98:99]
	s_mov_b32 m0, s45
	s_add_u32 s98, s0, s64
	s_addc_u32 s99, s1, s65
	global_load_lds_dwordx4 v221, s[98:99]
	s_barrier
	s_waitcnt lgkmcnt(0)
	s_setprio 1
	s_waitcnt lgkmcnt(0)
	v_mfma_f32_16x16x32_bf16 v[94:97], v[186:189], v[154:157], v[94:97]
	v_mfma_f32_16x16x32_bf16 v[90:93], v[194:197], v[154:157], v[90:93]
	v_mfma_f32_16x16x32_bf16 v[86:89], v[186:189], v[162:165], v[86:89]
	v_mfma_f32_16x16x32_bf16 v[82:85], v[194:197], v[162:165], v[82:85]
	v_mfma_f32_16x16x32_bf16 v[78:81], v[186:189], v[170:173], v[78:81]
	v_mfma_f32_16x16x32_bf16 v[74:77], v[194:197], v[170:173], v[74:77]
	v_mfma_f32_16x16x32_bf16 v[70:73], v[186:189], v[178:181], v[70:73]
	v_mfma_f32_16x16x32_bf16 v[66:69], v[194:197], v[178:181], v[66:69]
	v_mfma_f32_16x16x32_bf16 v[94:97], v[190:193], v[158:161], v[94:97]
	v_mfma_f32_16x16x32_bf16 v[90:93], v[198:201], v[158:161], v[90:93]
	v_mfma_f32_16x16x32_bf16 v[86:89], v[190:193], v[166:169], v[86:89]
	v_mfma_f32_16x16x32_bf16 v[82:85], v[198:201], v[166:169], v[82:85]
	v_mfma_f32_16x16x32_bf16 v[78:81], v[190:193], v[174:177], v[78:81]
	v_mfma_f32_16x16x32_bf16 v[74:77], v[198:201], v[174:177], v[74:77]
	v_mfma_f32_16x16x32_bf16 v[70:73], v[190:193], v[182:185], v[70:73]
	v_mfma_f32_16x16x32_bf16 v[66:69], v[198:201], v[182:185], v[66:69]
	s_setprio 0
	s_barrier
	ds_read_b128 v[154:157], v241 offset:16384
	ds_read_b128 v[158:161], v241 offset:17408
	ds_read_b128 v[162:165], v241 offset:18432
	ds_read_b128 v[166:169], v241 offset:19456
	ds_read_b128 v[170:173], v241 offset:20480
	ds_read_b128 v[174:177], v241 offset:21504
	ds_read_b128 v[178:181], v241 offset:22528
	ds_read_b128 v[182:185], v241 offset:23552
	s_mov_b32 m0, s46
	s_add_u32 s98, vcc_lo, s34
	s_addc_u32 s99, vcc_hi, s35
	global_load_lds_dwordx4 v221, s[98:99]
	s_mov_b32 m0, s47
	s_add_u32 s98, vcc_lo, s64
	s_addc_u32 s99, vcc_hi, s65
	global_load_lds_dwordx4 v221, s[98:99]
	s_barrier
	s_waitcnt lgkmcnt(0)
	s_setprio 1
	s_waitcnt lgkmcnt(0)
	v_mfma_f32_16x16x32_bf16 v[62:65], v[138:141], v[154:157], v[62:65]
	v_mfma_f32_16x16x32_bf16 v[58:61], v[146:149], v[154:157], v[58:61]
	v_mfma_f32_16x16x32_bf16 v[54:57], v[138:141], v[162:165], v[54:57]
	v_mfma_f32_16x16x32_bf16 v[50:53], v[146:149], v[162:165], v[50:53]
	v_mfma_f32_16x16x32_bf16 v[46:49], v[138:141], v[170:173], v[46:49]
	v_mfma_f32_16x16x32_bf16 v[42:45], v[146:149], v[170:173], v[42:45]
	v_mfma_f32_16x16x32_bf16 v[38:41], v[138:141], v[178:181], v[38:41]
	v_mfma_f32_16x16x32_bf16 v[34:37], v[146:149], v[178:181], v[34:37]
	v_mfma_f32_16x16x32_bf16 v[62:65], v[142:145], v[158:161], v[62:65]
	v_mfma_f32_16x16x32_bf16 v[58:61], v[150:153], v[158:161], v[58:61]
	v_mfma_f32_16x16x32_bf16 v[54:57], v[142:145], v[166:169], v[54:57]
	v_mfma_f32_16x16x32_bf16 v[50:53], v[150:153], v[166:169], v[50:53]
	v_mfma_f32_16x16x32_bf16 v[46:49], v[142:145], v[174:177], v[46:49]
	v_mfma_f32_16x16x32_bf16 v[42:45], v[150:153], v[174:177], v[42:45]
	v_mfma_f32_16x16x32_bf16 v[38:41], v[142:145], v[182:185], v[38:41]
	v_mfma_f32_16x16x32_bf16 v[34:37], v[150:153], v[182:185], v[34:37]
	s_setprio 0
	s_barrier
	s_mov_b32 m0, s48
	s_add_u32 s98, s0, s68
	s_addc_u32 s99, s1, s69
	global_load_lds_dwordx4 v221, s[98:99]
	s_mov_b32 m0, s49
	s_add_u32 s98, s0, s70
	s_addc_u32 s99, s1, s71
	global_load_lds_dwordx4 v221, s[98:99]
	s_waitcnt vmcnt(6)
	s_barrier
; #define LDA(dst, b, h) for (int m = 0; m < 4; ++m) for (int k = 0; k < 2; ++k) \
;     dst[m][k] = *reinterpret_cast<const bf16x8*>((char*)SA(b, h) + a_thr + (m * 2 + k) * 1024)
; #define LDB(dst, b, h) for (int n = 0; n < 2; ++n) for (int k = 0; k < 2; ++k) \
;     dst[n][k] = *reinterpret_cast<const bf16x8*>((char*)SB(b, h) + b_thr + (n * 2 + k) * 1024)
; #define MMA(ai, bj, At, Btf) do { __builtin_amdgcn_s_setprio(1); \
;     for (int m = 0; m < 4; ++m) for (int n = 0; n < 2; ++n) for (int k = 0; k < 2; ++k) \
;       acc[ai][bj][m][n] = __builtin_amdgcn_mfma_f32_16x16x32_bf16(Btf[n][k], At[m][k], acc[ai][bj][m][n], 0, 0, 0); \
;     __builtin_amdgcn_s_setprio(0); } while (0)
; #define WAIT_V(n) asm volatile("s_waitcnt vmcnt(" #n ")" ::: "memory")
; #define WAIT_L(n) asm volatile("s_waitcnt lgkmcnt(" #n ")" ::: "memory")
; #define BAR __builtin_amdgcn_s_barrier()
; #define SCHED __builtin_amdgcn_sched_barrier(0)
; template <bool OVL, bool PANEL = false, class Epi>
; __device__ __forceinline__ void gemm_phase(const bf16_t* __restrict__ A, long lda, const bf16_t* __restrict__ Bt, long ldb, int nM, int nN, int K,
;                                            const Epi& epi, bf16_t* shm, int w0) {
;     ...
;       WAIT_V(6); BAR; MMA(1, 1, At, B1); BAR;
;       LDB(B0, 1, 0); SCHED; LDA(At, 1, 0); STAGE(SA(0, 1), A, lda, aoff, brow + HALF, t + 2);
;       WAIT_L(8); BAR; WAIT_L(0); MMA(0, 0, At, B0); BAR; SCHED;
;       LDB(B1, 1, 1); STAGE(SB(1, 0), Bt, ldb, boff, bcol, t + 3);
;       BAR; WAIT_L(0); MMA(0, 1, At, B1); BAR;
;       LDA(At, 1, 1); STAGE(SA(1, 0), A, lda, aoff, brow, t + 3);
	s_setprio 1
	v_mfma_f32_16x16x32_bf16 v[30:33], v[186:189], v[154:157], v[30:33]
	v_mfma_f32_16x16x32_bf16 v[26:29], v[194:197], v[154:157], v[26:29]
	v_mfma_f32_16x16x32_bf16 v[22:25], v[186:189], v[162:165], v[22:25]
	v_mfma_f32_16x16x32_bf16 v[18:21], v[194:197], v[162:165], v[18:21]
	v_mfma_f32_16x16x32_bf16 v[14:17], v[186:189], v[170:173], v[14:17]
	v_mfma_f32_16x16x32_bf16 v[10:13], v[194:197], v[170:173], v[10:13]
	v_mfma_f32_16x16x32_bf16 v[6:9], v[186:189], v[178:181], v[6:9]
	v_mfma_f32_16x16x32_bf16 v[2:5], v[194:197], v[178:181], v[2:5]
	v_mfma_f32_16x16x32_bf16 v[30:33], v[190:193], v[158:161], v[30:33]
	v_mfma_f32_16x16x32_bf16 v[26:29], v[198:201], v[158:161], v[26:29]
	v_mfma_f32_16x16x32_bf16 v[22:25], v[190:193], v[166:169], v[22:25]
	v_mfma_f32_16x16x32_bf16 v[18:21], v[198:201], v[166:169], v[18:21]
	v_mfma_f32_16x16x32_bf16 v[14:17], v[190:193], v[174:177], v[14:17]
	v_mfma_f32_16x16x32_bf16 v[10:13], v[198:201], v[174:177], v[10:13]
	v_mfma_f32_16x16x32_bf16 v[6:9], v[190:193], v[182:185], v[6:9]
	v_mfma_f32_16x16x32_bf16 v[2:5], v[198:201], v[182:185], v[2:5]
	s_setprio 0
	s_barrier
	ds_read_b128 v[138:141], v208
	ds_read_b128 v[142:145], v208 offset:1024
	ds_read_b128 v[146:149], v208 offset:2048
	ds_read_b128 v[150:153], v208 offset:3072
	ds_read_b128 v[154:157], v241 offset:32768
	ds_read_b128 v[158:161], v241 offset:33792
	ds_read_b128 v[162:165], v241 offset:34816
	ds_read_b128 v[166:169], v241 offset:35840
	ds_read_b128 v[170:173], v241 offset:36864
	ds_read_b128 v[174:177], v241 offset:37888
	ds_read_b128 v[178:181], v241 offset:38912
	ds_read_b128 v[182:185], v241 offset:39936
	s_mov_b32 m0, s50
	s_add_u32 s98, vcc_lo, s68
	s_addc_u32 s99, vcc_hi, s69
	global_load_lds_dwordx4 v221, s[98:99]
	s_mov_b32 m0, s51
	s_add_u32 s98, vcc_lo, s70
	s_addc_u32 s99, vcc_hi, s71
	global_load_lds_dwordx4 v221, s[98:99]
	s_waitcnt lgkmcnt(8)
	s_barrier
	s_waitcnt lgkmcnt(0)
	s_setprio 1
	s_waitcnt lgkmcnt(0)
	v_mfma_f32_16x16x32_bf16 v[126:129], v[138:141], v[154:157], v[126:129]
	v_mfma_f32_16x16x32_bf16 v[122:125], v[146:149], v[154:157], v[122:125]
	v_mfma_f32_16x16x32_bf16 v[118:121], v[138:141], v[162:165], v[118:121]
	v_mfma_f32_16x16x32_bf16 v[114:117], v[146:149], v[162:165], v[114:117]
	v_mfma_f32_16x16x32_bf16 v[110:113], v[138:141], v[170:173], v[110:113]
	v_mfma_f32_16x16x32_bf16 v[106:109], v[146:149], v[170:173], v[106:109]
	v_mfma_f32_16x16x32_bf16 v[102:105], v[138:141], v[178:181], v[102:105]
	v_mfma_f32_16x16x32_bf16 v[98:101], v[146:149], v[178:181], v[98:101]
	v_mfma_f32_16x16x32_bf16 v[126:129], v[142:145], v[158:161], v[126:129]
	v_mfma_f32_16x16x32_bf16 v[122:125], v[150:153], v[158:161], v[122:125]
	v_mfma_f32_16x16x32_bf16 v[118:121], v[142:145], v[166:169], v[118:121]
	v_mfma_f32_16x16x32_bf16 v[114:117], v[150:153], v[166:169], v[114:117]
	v_mfma_f32_16x16x32_bf16 v[110:113], v[142:145], v[174:177], v[110:113]
	v_mfma_f32_16x16x32_bf16 v[106:109], v[150:153], v[174:177], v[106:109]
	v_mfma_f32_16x16x32_bf16 v[102:105], v[142:145], v[182:185], v[102:105]
	v_mfma_f32_16x16x32_bf16 v[98:101], v[150:153], v[182:185], v[98:101]
	s_setprio 0
	s_barrier
	ds_read_b128 v[186:189], v209
	ds_read_b128 v[190:193], v209 offset:1024
	ds_read_b128 v[194:197], v209 offset:2048
	ds_read_b128 v[198:201], v209 offset:3072
	s_mov_b32 m0, s52
	s_add_u32 s98, s0, s94
	s_addc_u32 s99, s1, s95
	global_load_lds_dwordx4 v221, s[98:99]
	s_mov_b32 m0, s53
	s_add_u32 s98, s0, s72
	s_addc_u32 s99, s1, s73
	global_load_lds_dwordx4 v221, s[98:99]
	s_barrier
	s_waitcnt lgkmcnt(0)
	s_setprio 1
	s_waitcnt lgkmcnt(0)
	v_mfma_f32_16x16x32_bf16 v[94:97], v[186:189], v[154:157], v[94:97]
	v_mfma_f32_16x16x32_bf16 v[90:93], v[194:197], v[154:157], v[90:93]
	v_mfma_f32_16x16x32_bf16 v[86:89], v[186:189], v[162:165], v[86:89]
	v_mfma_f32_16x16x32_bf16 v[82:85], v[194:197], v[162:165], v[82:85]
	v_mfma_f32_16x16x32_bf16 v[78:81], v[186:189], v[170:173], v[78:81]
	v_mfma_f32_16x16x32_bf16 v[74:77], v[194:197], v[170:173], v[74:77]
	v_mfma_f32_16x16x32_bf16 v[70:73], v[186:189], v[178:181], v[70:73]
	v_mfma_f32_16x16x32_bf16 v[66:69], v[194:197], v[178:181], v[66:69]
	v_mfma_f32_16x16x32_bf16 v[94:97], v[190:193], v[158:161], v[94:97]
	v_mfma_f32_16x16x32_bf16 v[90:93], v[198:201], v[158:161], v[90:93]
	v_mfma_f32_16x16x32_bf16 v[86:89], v[190:193], v[166:169], v[86:89]
	v_mfma_f32_16x16x32_bf16 v[82:85], v[198:201], v[166:169], v[82:85]
	v_mfma_f32_16x16x32_bf16 v[78:81], v[190:193], v[174:177], v[78:81]
	v_mfma_f32_16x16x32_bf16 v[74:77], v[198:201], v[174:177], v[74:77]
	v_mfma_f32_16x16x32_bf16 v[70:73], v[190:193], v[182:185], v[70:73]
	v_mfma_f32_16x16x32_bf16 v[66:69], v[198:201], v[182:185], v[66:69]
	s_setprio 0
	s_barrier
	ds_read_b128 v[154:157], v241 offset:49152
	ds_read_b128 v[158:161], v241 offset:50176
	ds_read_b128 v[162:165], v241 offset:51200
	ds_read_b128 v[166:169], v241 offset:52224
	ds_read_b128 v[170:173], v241 offset:53248
	ds_read_b128 v[174:177], v241 offset:54272
	ds_read_b128 v[178:181], v241 offset:55296
	ds_read_b128 v[182:185], v241 offset:56320
	s_mov_b32 m0, s54
	s_add_u32 s98, vcc_lo, s94
	s_addc_u32 s99, vcc_hi, s95
	global_load_lds_dwordx4 v221, s[98:99]
	s_mov_b32 m0, s55
	s_add_u32 s98, vcc_lo, s72
	s_addc_u32 s99, vcc_hi, s73
	global_load_lds_dwordx4 v221, s[98:99]
	s_barrier
; #define LDA(dst, b, h) for (int m = 0; m < 4; ++m) for (int k = 0; k < 2; ++k) \
;     dst[m][k] = *reinterpret_cast<const bf16x8*>((char*)SA(b, h) + a_thr + (m * 2 + k) * 1024)
; #define LDB(dst, b, h) for (int n = 0; n < 2; ++n) for (int k = 0; k < 2; ++k) \
;     dst[n][k] = *reinterpret_cast<const bf16x8*>((char*)SB(b, h) + b_thr + (n * 2 + k) * 1024)
; #define MMA(ai, bj, At, Btf) do { __builtin_amdgcn_s_setprio(1); \
;     for (int m = 0; m < 4; ++m) for (int n = 0; n < 2; ++n) for (int k = 0; k < 2; ++k) \
;       acc[ai][bj][m][n] = __builtin_amdgcn_mfma_f32_16x16x32_bf16(Btf[n][k], At[m][k], acc[ai][bj][m][n], 0, 0, 0); \
;     __builtin_amdgcn_s_setprio(0); } while (0)
; #define WAIT_V(n) asm volatile("s_waitcnt vmcnt(" #n ")" ::: "memory")
; #define WAIT_L(n) asm volatile("s_waitcnt lgkmcnt(" #n ")" ::: "memory")
; #define BAR __builtin_amdgcn_s_barrier()
; #define SCHED __builtin_amdgcn_sched_barrier(0)
; template <bool OVL, bool PANEL = false, class Epi>
; __device__ __forceinline__ void gemm_phase(const bf16_t* __restrict__ A, long lda, const bf16_t* __restrict__ Bt, long ldb, int nM, int nN, int K,
;                                            const Epi& epi, bf16_t* shm, int w0) {
;     ...
;       BAR; WAIT_L(0); MMA(1, 0, At, B0); BAR; SCHED;
;       STAGE(SB(1, 1), Bt, ldb, boff, bcol + HALF, t + 3);
;       WAIT_V(6); BAR; MMA(1, 1, At, B1); BAR;
;     }
;     { LDB(B0, 0, 0); LDA(At, 0, 0); STAGE(SA(1, 1), A, lda, aoff, brow + HALF, nt - 1);
;       BAR; WAIT_L(0); MMA(0, 0, At, B0); BAR;
;       LDB(B1, 0, 1); BAR; WAIT_L(0); MMA(0, 1, At, B1); BAR;
;       LDA(At, 0, 1); WAIT_V(4); BAR; WAIT_L(0); MMA(1, 0, At, B0); MMA(1, 1, At, B1); BAR; }
	s_waitcnt lgkmcnt(0)
	s_setprio 1
	s_waitcnt lgkmcnt(0)
	v_mfma_f32_16x16x32_bf16 v[62:65], v[138:141], v[154:157], v[62:65]
	v_mfma_f32_16x16x32_bf16 v[58:61], v[146:149], v[154:157], v[58:61]
	v_mfma_f32_16x16x32_bf16 v[54:57], v[138:141], v[162:165], v[54:57]
	v_mfma_f32_16x16x32_bf16 v[50:53], v[146:149], v[162:165], v[50:53]
	v_mfma_f32_16x16x32_bf16 v[46:49], v[138:141], v[170:173], v[46:49]
	v_mfma_f32_16x16x32_bf16 v[42:45], v[146:149], v[170:173], v[42:45]
	v_mfma_f32_16x16x32_bf16 v[38:41], v[138:141], v[178:181], v[38:41]
	v_mfma_f32_16x16x32_bf16 v[34:37], v[146:149], v[178:181], v[34:37]
	v_mfma_f32_16x16x32_bf16 v[62:65], v[142:145], v[158:161], v[62:65]
	v_mfma_f32_16x16x32_bf16 v[58:61], v[150:153], v[158:161], v[58:61]
	v_mfma_f32_16x16x32_bf16 v[54:57], v[142:145], v[166:169], v[54:57]
	v_mfma_f32_16x16x32_bf16 v[50:53], v[150:153], v[166:169], v[50:53]
	v_mfma_f32_16x16x32_bf16 v[46:49], v[142:145], v[174:177], v[46:49]
	v_mfma_f32_16x16x32_bf16 v[42:45], v[150:153], v[174:177], v[42:45]
	v_mfma_f32_16x16x32_bf16 v[38:41], v[142:145], v[182:185], v[38:41]
	v_mfma_f32_16x16x32_bf16 v[34:37], v[150:153], v[182:185], v[34:37]
	s_setprio 0
	s_barrier
	s_mov_b32 m0, s56
	s_add_u32 s98, s0, s14
	s_addc_u32 s99, s1, s15
	global_load_lds_dwordx4 v221, s[98:99]
	s_mov_b32 m0, s57
	s_add_u32 s98, s0, s18
	s_addc_u32 s99, s1, s19
	global_load_lds_dwordx4 v221, s[98:99]
	s_waitcnt vmcnt(6)
	s_barrier
	s_setprio 1
	v_mfma_f32_16x16x32_bf16 v[30:33], v[186:189], v[154:157], v[30:33]
	v_mfma_f32_16x16x32_bf16 v[26:29], v[194:197], v[154:157], v[26:29]
	v_mfma_f32_16x16x32_bf16 v[22:25], v[186:189], v[162:165], v[22:25]
	v_mfma_f32_16x16x32_bf16 v[18:21], v[194:197], v[162:165], v[18:21]
	v_mfma_f32_16x16x32_bf16 v[14:17], v[186:189], v[170:173], v[14:17]
	v_mfma_f32_16x16x32_bf16 v[10:13], v[194:197], v[170:173], v[10:13]
	v_mfma_f32_16x16x32_bf16 v[6:9], v[186:189], v[178:181], v[6:9]
	v_mfma_f32_16x16x32_bf16 v[2:5], v[194:197], v[178:181], v[2:5]
	v_mfma_f32_16x16x32_bf16 v[30:33], v[190:193], v[158:161], v[30:33]
	v_mfma_f32_16x16x32_bf16 v[26:29], v[198:201], v[158:161], v[26:29]
	v_mfma_f32_16x16x32_bf16 v[22:25], v[190:193], v[166:169], v[22:25]
	v_mfma_f32_16x16x32_bf16 v[18:21], v[198:201], v[166:169], v[18:21]
	v_mfma_f32_16x16x32_bf16 v[14:17], v[190:193], v[174:177], v[14:17]
	v_mfma_f32_16x16x32_bf16 v[10:13], v[198:201], v[174:177], v[10:13]
	v_mfma_f32_16x16x32_bf16 v[6:9], v[190:193], v[182:185], v[6:9]
	v_mfma_f32_16x16x32_bf16 v[2:5], v[198:201], v[182:185], v[2:5]
	s_setprio 0
	s_add_i32 s2, s2, 2
	s_add_u32 s80, s80, 0x100
	s_addc_u32 s81, s81, 0
	s_cmp_gt_u32 s2, 11
	s_barrier
	s_cbranch_scc0 .LBB0_472
	s_or_b32 s0, s82, 0x80
	s_ashr_i32 s1, s0, 31
	v_readlane_b32 s44, v252, 20
	s_lshl_b64 s[0:1], s[0:1], 11
	v_readlane_b32 s50, v252, 26
	v_add_u32_e32 v206, 16, v240
	v_readlane_b32 s51, v252, 27
	s_add_u32 s0, s50, s0
	v_add_u32_e32 v0, 0x10000, v206
	s_addc_u32 s1, s51, s1
	ds_read_b128 v[130:133], v0
	ds_read_b128 v[138:141], v0 offset:1024
	ds_read_b128 v[142:145], v0 offset:2048
	ds_read_b128 v[146:149], v0 offset:3072
	ds_read_b128 v[150:153], v241
	ds_read_b128 v[154:157], v241 offset:1024
	ds_read_b128 v[158:161], v241 offset:2048
	ds_read_b128 v[162:165], v241 offset:3072
	ds_read_b128 v[166:169], v241 offset:4096
	ds_read_b128 v[170:173], v241 offset:5120
	ds_read_b128 v[174:177], v241 offset:6144
	ds_read_b128 v[178:181], v241 offset:7168
	v_mov_b32_e32 v0, v221
	v_readlane_b32 s45, v252, 21
	v_lshl_add_u64 v[134:135], s[0:1], 0, v[0:1]
	s_mov_b64 s[0:1], 0x780
	v_lshl_add_u64 v[182:183], v[134:135], 0, s[0:1]
	v_readfirstlane_b32 s0, v136
	s_mov_b32 m0, s0
	s_mov_b64 s[0:1], 0x20780
	v_lshl_add_u64 v[134:135], v[134:135], 0, s[0:1]
	v_readfirstlane_b32 s0, v137
	global_load_lds_dwordx4 v[182:183], off
	s_mov_b32 m0, s0
	v_readlane_b32 s46, v252, 22
	global_load_lds_dwordx4 v[134:135], off
	s_barrier
	s_waitcnt lgkmcnt(0)
	v_readlane_b32 s47, v252, 23
	v_readlane_b32 s48, v252, 24
	v_readlane_b32 s49, v252, 25
	v_readlane_b32 s52, v252, 28
	v_readlane_b32 s53, v252, 29
	v_readlane_b32 s54, v252, 30
	v_readlane_b32 s55, v252, 31
	v_readlane_b32 s56, v252, 32
	v_readlane_b32 s57, v252, 33
	v_readlane_b32 s58, v252, 34
	v_readlane_b32 s59, v252, 35
	s_setprio 1
	s_waitcnt lgkmcnt(0)
	v_mfma_f32_16x16x32_bf16 v[126:129], v[130:133], v[150:153], v[126:129]
	v_mfma_f32_16x16x32_bf16 v[122:125], v[142:145], v[150:153], v[122:125]
	v_mfma_f32_16x16x32_bf16 v[118:121], v[130:133], v[158:161], v[118:121]
	v_mfma_f32_16x16x32_bf16 v[114:117], v[142:145], v[158:161], v[114:117]
	v_mfma_f32_16x16x32_bf16 v[106:109], v[142:145], v[166:169], v[106:109]
	v_mfma_f32_16x16x32_bf16 v[102:105], v[130:133], v[174:177], v[102:105]
	v_mfma_f32_16x16x32_bf16 v[98:101], v[142:145], v[174:177], v[98:101]
	v_mfma_f32_16x16x32_bf16 v[126:129], v[138:141], v[154:157], v[126:129]
	v_mfma_f32_16x16x32_bf16 v[122:125], v[146:149], v[154:157], v[122:125]
	v_mfma_f32_16x16x32_bf16 v[118:121], v[138:141], v[162:165], v[118:121]
	v_mfma_f32_16x16x32_bf16 v[114:117], v[146:149], v[162:165], v[114:117]
	v_mfma_f32_16x16x32_bf16 v[110:113], v[130:133], v[166:169], v[110:113]
	v_mfma_f32_16x16x32_bf16 v[106:109], v[146:149], v[170:173], v[106:109]
	v_mfma_f32_16x16x32_bf16 v[102:105], v[138:141], v[178:181], v[102:105]
	v_mfma_f32_16x16x32_bf16 v[98:101], v[146:149], v[178:181], v[98:101]
	v_mfma_f32_16x16x32_bf16 v[134:137], v[138:141], v[170:173], v[110:113]
	s_setprio 0
	v_add_u32_e32 v0, 0x14000, v206
	s_barrier
	s_nop 0
	ds_read_b128 v[110:113], v0
	ds_read_b128 v[182:185], v0 offset:1024
	ds_read_b128 v[186:189], v0 offset:2048
	ds_read_b128 v[190:193], v0 offset:3072
	s_barrier
; #define LDA(dst, b, h) for (int m = 0; m < 4; ++m) for (int k = 0; k < 2; ++k) \
;     dst[m][k] = *reinterpret_cast<const bf16x8*>((char*)SA(b, h) + a_thr + (m * 2 + k) * 1024)
; #define LDB(dst, b, h) for (int n = 0; n < 2; ++n) for (int k = 0; k < 2; ++k) \
;     dst[n][k] = *reinterpret_cast<const bf16x8*>((char*)SB(b, h) + b_thr + (n * 2 + k) * 1024)
; #define MMA(ai, bj, At, Btf) do { __builtin_amdgcn_s_setprio(1); \
;     for (int m = 0; m < 4; ++m) for (int n = 0; n < 2; ++n) for (int k = 0; k < 2; ++k) \
;       acc[ai][bj][m][n] = __builtin_amdgcn_mfma_f32_16x16x32_bf16(Btf[n][k], At[m][k], acc[ai][bj][m][n], 0, 0, 0); \
;     __builtin_amdgcn_s_setprio(0); } while (0)
; #define WAIT_V(n) asm volatile("s_waitcnt vmcnt(" #n ")" ::: "memory")
; #define WAIT_L(n) asm volatile("s_waitcnt lgkmcnt(" #n ")" ::: "memory")
; #define BAR __builtin_amdgcn_s_barrier()
; template <bool OVL, bool PANEL = false, class Epi>
; __device__ __forceinline__ void gemm_phase(const bf16_t* __restrict__ A, long lda, const bf16_t* __restrict__ Bt, long ldb, int nM, int nN, int K,
;                                            const Epi& epi, bf16_t* shm, int w0) {
;     ...
;       LDB(B1, 0, 1); BAR; WAIT_L(0); MMA(0, 1, At, B1); BAR;
;       LDA(At, 0, 1); WAIT_V(4); BAR; WAIT_L(0); MMA(1, 0, At, B0); MMA(1, 1, At, B1); BAR; }
;     { LDB(B0, 1, 0); LDA(At, 1, 0); WAIT_V(2); BAR; WAIT_L(0); MMA(0, 0, At, B0); BAR;
	s_waitcnt lgkmcnt(0)
	s_setprio 1
	s_waitcnt lgkmcnt(0)
	v_mfma_f32_16x16x32_bf16 v[90:93], v[186:189], v[150:153], v[90:93]
	v_mfma_f32_16x16x32_bf16 v[74:77], v[186:189], v[166:169], v[74:77]
	v_mfma_f32_16x16x32_bf16 v[70:73], v[110:113], v[174:177], v[70:73]
	v_mfma_f32_16x16x32_bf16 v[66:69], v[186:189], v[174:177], v[66:69]
	v_mfma_f32_16x16x32_bf16 v[94:97], v[110:113], v[150:153], v[94:97]
	v_mfma_f32_16x16x32_bf16 v[90:93], v[190:193], v[154:157], v[90:93]
	v_mfma_f32_16x16x32_bf16 v[86:89], v[110:113], v[158:161], v[86:89]
	v_mfma_f32_16x16x32_bf16 v[82:85], v[186:189], v[158:161], v[82:85]
	v_mfma_f32_16x16x32_bf16 v[78:81], v[110:113], v[166:169], v[78:81]
	v_mfma_f32_16x16x32_bf16 v[74:77], v[190:193], v[170:173], v[74:77]
	v_mfma_f32_16x16x32_bf16 v[70:73], v[182:185], v[178:181], v[70:73]
	v_mfma_f32_16x16x32_bf16 v[66:69], v[190:193], v[178:181], v[66:69]
	v_mfma_f32_16x16x32_bf16 v[194:197], v[182:185], v[154:157], v[94:97]
	v_mfma_f32_16x16x32_bf16 v[150:153], v[182:185], v[162:165], v[86:89]
	v_mfma_f32_16x16x32_bf16 v[154:157], v[190:193], v[162:165], v[82:85]
	v_mfma_f32_16x16x32_bf16 v[158:161], v[182:185], v[170:173], v[78:81]
	s_setprio 0
	s_barrier
	s_nop 0
	ds_read_b128 v[78:81], v241 offset:16384
	ds_read_b128 v[82:85], v241 offset:17408
	ds_read_b128 v[86:89], v241 offset:18432
	ds_read_b128 v[94:97], v241 offset:19456
	ds_read_b128 v[162:165], v241 offset:20480
	ds_read_b128 v[166:169], v241 offset:21504
	ds_read_b128 v[170:173], v241 offset:22528
	ds_read_b128 v[174:177], v241 offset:23552
	s_waitcnt vmcnt(4)
	s_barrier
	s_waitcnt lgkmcnt(0)
	s_setprio 1
	s_waitcnt lgkmcnt(0)
	v_mfma_f32_16x16x32_bf16 v[62:65], v[130:133], v[78:81], v[62:65]
	v_mfma_f32_16x16x32_bf16 v[58:61], v[142:145], v[78:81], v[58:61]
	v_mfma_f32_16x16x32_bf16 v[54:57], v[130:133], v[86:89], v[54:57]
	v_mfma_f32_16x16x32_bf16 v[50:53], v[142:145], v[86:89], v[50:53]
	v_mfma_f32_16x16x32_bf16 v[46:49], v[130:133], v[162:165], v[46:49]
	v_mfma_f32_16x16x32_bf16 v[42:45], v[142:145], v[162:165], v[42:45]
	v_mfma_f32_16x16x32_bf16 v[34:37], v[142:145], v[170:173], v[34:37]
	v_mfma_f32_16x16x32_bf16 v[62:65], v[138:141], v[82:85], v[62:65]
	v_mfma_f32_16x16x32_bf16 v[58:61], v[146:149], v[82:85], v[58:61]
	v_mfma_f32_16x16x32_bf16 v[54:57], v[138:141], v[94:97], v[54:57]
	v_mfma_f32_16x16x32_bf16 v[50:53], v[146:149], v[94:97], v[50:53]
	v_mfma_f32_16x16x32_bf16 v[46:49], v[138:141], v[166:169], v[46:49]
	v_mfma_f32_16x16x32_bf16 v[42:45], v[146:149], v[166:169], v[42:45]
	v_mfma_f32_16x16x32_bf16 v[38:41], v[130:133], v[170:173], v[38:41]
	v_mfma_f32_16x16x32_bf16 v[34:37], v[146:149], v[174:177], v[34:37]
	v_mfma_f32_16x16x32_bf16 v[130:133], v[138:141], v[174:177], v[38:41]
	s_setprio 0
	s_setprio 1
	v_mfma_f32_16x16x32_bf16 v[30:33], v[110:113], v[78:81], v[30:33]
	v_mfma_f32_16x16x32_bf16 v[26:29], v[186:189], v[78:81], v[26:29]
	v_mfma_f32_16x16x32_bf16 v[22:25], v[110:113], v[86:89], v[22:25]
	v_mfma_f32_16x16x32_bf16 v[18:21], v[186:189], v[86:89], v[18:21]
	v_mfma_f32_16x16x32_bf16 v[14:17], v[110:113], v[162:165], v[14:17]
	v_mfma_f32_16x16x32_bf16 v[10:13], v[186:189], v[162:165], v[10:13]
	v_mfma_f32_16x16x32_bf16 v[6:9], v[110:113], v[170:173], v[6:9]
	v_mfma_f32_16x16x32_bf16 v[2:5], v[186:189], v[170:173], v[2:5]
	v_mfma_f32_16x16x32_bf16 v[138:141], v[182:185], v[82:85], v[30:33]
	v_mfma_f32_16x16x32_bf16 v[142:145], v[190:193], v[82:85], v[26:29]
	v_mfma_f32_16x16x32_bf16 v[146:149], v[182:185], v[94:97], v[22:25]
	v_mfma_f32_16x16x32_bf16 v[178:181], v[190:193], v[94:97], v[18:21]
	v_mfma_f32_16x16x32_bf16 v[198:201], v[182:185], v[166:169], v[14:17]
	v_mfma_f32_16x16x32_bf16 v[162:165], v[190:193], v[166:169], v[10:13]
	v_mfma_f32_16x16x32_bf16 v[166:169], v[182:185], v[174:177], v[6:9]
	v_mfma_f32_16x16x32_bf16 v[170:173], v[190:193], v[174:177], v[2:5]
	s_setprio 0
	v_add_u32_e32 v0, 0x18000, v206
	s_barrier
	ds_read_b128 v[174:177], v0
	ds_read_b128 v[182:185], v0 offset:1024
	ds_read_b128 v[186:189], v0 offset:2048
	ds_read_b128 v[190:193], v0 offset:3072
	ds_read_b128 v[6:9], v241 offset:32768
	ds_read_b128 v[14:17], v241 offset:33792
	ds_read_b128 v[18:21], v241 offset:34816
	ds_read_b128 v[22:25], v241 offset:35840
	ds_read_b128 v[26:29], v241 offset:36864
	ds_read_b128 v[30:33], v241 offset:37888
	ds_read_b128 v[38:41], v241 offset:38912
	ds_read_b128 v[202:205], v241 offset:39936
	s_waitcnt vmcnt(2)
	s_barrier
; #define LDA(dst, b, h) for (int m = 0; m < 4; ++m) for (int k = 0; k < 2; ++k) \
;     dst[m][k] = *reinterpret_cast<const bf16x8*>((char*)SA(b, h) + a_thr + (m * 2 + k) * 1024)
; #define LDB(dst, b, h) for (int n = 0; n < 2; ++n) for (int k = 0; k < 2; ++k) \
;     dst[n][k] = *reinterpret_cast<const bf16x8*>((char*)SB(b, h) + b_thr + (n * 2 + k) * 1024)
; #define MMA(ai, bj, At, Btf) do { __builtin_amdgcn_s_setprio(1); \
;     for (int m = 0; m < 4; ++m) for (int n = 0; n < 2; ++n) for (int k = 0; k < 2; ++k) \
;       acc[ai][bj][m][n] = __builtin_amdgcn_mfma_f32_16x16x32_bf16(Btf[n][k], At[m][k], acc[ai][bj][m][n], 0, 0, 0); \
;     __builtin_amdgcn_s_setprio(0); } while (0)
; #define WAIT_V(n) asm volatile("s_waitcnt vmcnt(" #n ")" ::: "memory")
; #define WAIT_L(n) asm volatile("s_waitcnt lgkmcnt(" #n ")" ::: "memory")
; #define BAR __builtin_amdgcn_s_barrier()
; template <bool OVL, bool PANEL = false, class Epi>
; __device__ __forceinline__ void gemm_phase(const bf16_t* __restrict__ A, long lda, const bf16_t* __restrict__ Bt, long ldb, int nM, int nN, int K,
;                                            const Epi& epi, bf16_t* shm, int w0) {
;     ...
;     { LDB(B0, 1, 0); LDA(At, 1, 0); WAIT_V(2); BAR; WAIT_L(0); MMA(0, 0, At, B0); BAR;
;       LDB(B1, 1, 1); WAIT_V(0); BAR; WAIT_L(0); MMA(0, 1, At, B1); BAR;
;       LDA(At, 1, 1); BAR; WAIT_L(0); MMA(1, 0, At, B0); MMA(1, 1, At, B1); BAR; }
;     if (wr == 0) BAR;
	s_waitcnt lgkmcnt(0)
	s_setprio 1
	s_waitcnt lgkmcnt(0)
	v_mfma_f32_16x16x32_bf16 v[2:5], v[174:177], v[6:9], v[126:129]
	v_mfma_f32_16x16x32_bf16 v[126:129], v[182:185], v[14:17], v[2:5]
	v_mfma_f32_16x16x32_bf16 v[2:5], v[186:189], v[6:9], v[122:125]
	v_mfma_f32_16x16x32_bf16 v[82:85], v[190:193], v[14:17], v[2:5]
	v_mfma_f32_16x16x32_bf16 v[2:5], v[174:177], v[18:21], v[118:121]
	v_mfma_f32_16x16x32_bf16 v[110:113], v[182:185], v[22:25], v[2:5]
	v_mfma_f32_16x16x32_bf16 v[2:5], v[186:189], v[18:21], v[114:117]
	v_mfma_f32_16x16x32_bf16 v[86:89], v[190:193], v[22:25], v[2:5]
	v_mfma_f32_16x16x32_bf16 v[2:5], v[174:177], v[26:29], v[134:137]
	v_mfma_f32_16x16x32_bf16 v[94:97], v[182:185], v[30:33], v[2:5]
	v_mfma_f32_16x16x32_bf16 v[2:5], v[186:189], v[26:29], v[106:109]
	v_mfma_f32_16x16x32_bf16 v[78:81], v[190:193], v[30:33], v[2:5]
	v_mfma_f32_16x16x32_bf16 v[2:5], v[174:177], v[38:41], v[102:105]
	v_mfma_f32_16x16x32_bf16 v[10:13], v[186:189], v[38:41], v[98:101]
	v_mfma_f32_16x16x32_bf16 v[2:5], v[182:185], v[202:205], v[2:5]
	v_mfma_f32_16x16x32_bf16 v[10:13], v[190:193], v[202:205], v[10:13]
	s_setprio 0
	v_add_u32_e32 v0, 0x1c000, v206
	s_barrier
	ds_read_b128 v[122:125], v0
	ds_read_b128 v[134:137], v0 offset:1024
	ds_read_b128 v[206:209], v0 offset:2048
	ds_read_b128 v[210:213], v0 offset:3072
	s_waitcnt vmcnt(0)
	s_barrier
	s_waitcnt lgkmcnt(0)
	s_setprio 1
	s_waitcnt lgkmcnt(0)
	v_mfma_f32_16x16x32_bf16 v[98:101], v[122:125], v[6:9], v[194:197]
	v_mfma_f32_16x16x32_bf16 v[6:9], v[206:209], v[6:9], v[90:93]
	v_mfma_f32_16x16x32_bf16 v[114:117], v[210:213], v[14:17], v[6:9]
	v_mfma_f32_16x16x32_bf16 v[6:9], v[122:125], v[18:21], v[150:153]
	v_mfma_f32_16x16x32_bf16 v[102:105], v[134:137], v[22:25], v[6:9]
	v_mfma_f32_16x16x32_bf16 v[6:9], v[206:209], v[18:21], v[154:157]
	v_mfma_f32_16x16x32_bf16 v[118:121], v[210:213], v[22:25], v[6:9]
	v_mfma_f32_16x16x32_bf16 v[6:9], v[122:125], v[26:29], v[158:161]
	v_mfma_f32_16x16x32_bf16 v[90:93], v[134:137], v[30:33], v[6:9]
	v_mfma_f32_16x16x32_bf16 v[6:9], v[206:209], v[26:29], v[74:77]
	v_mfma_f32_16x16x32_bf16 v[106:109], v[210:213], v[30:33], v[6:9]
	v_mfma_f32_16x16x32_bf16 v[6:9], v[122:125], v[38:41], v[70:73]
	v_mfma_f32_16x16x32_bf16 v[22:25], v[134:137], v[202:205], v[6:9]
	v_mfma_f32_16x16x32_bf16 v[6:9], v[206:209], v[38:41], v[66:69]
	v_mfma_f32_16x16x32_bf16 v[98:101], v[134:137], v[14:17], v[98:101]
	v_mfma_f32_16x16x32_bf16 v[38:41], v[210:213], v[202:205], v[6:9]
	s_setprio 0
	s_barrier
	ds_read_b128 v[70:73], v241 offset:49152
	ds_read_b128 v[74:77], v241 offset:50176
	ds_read_b128 v[150:153], v241 offset:51200
	ds_read_b128 v[154:157], v241 offset:52224
	ds_read_b128 v[158:161], v241 offset:53248
	ds_read_b128 v[194:197], v241 offset:54272
	ds_read_b128 v[202:205], v241 offset:55296
	ds_read_b128 v[214:217], v241 offset:56320
	s_barrier
	s_waitcnt lgkmcnt(0)
	s_setprio 1
	s_waitcnt lgkmcnt(0)
	v_mfma_f32_16x16x32_bf16 v[14:17], v[186:189], v[70:73], v[58:61]
	v_mfma_f32_16x16x32_bf16 v[42:45], v[186:189], v[158:161], v[42:45]
	v_mfma_f32_16x16x32_bf16 v[6:9], v[174:177], v[70:73], v[62:65]
	v_mfma_f32_16x16x32_bf16 v[18:21], v[190:193], v[74:77], v[14:17]
	v_mfma_f32_16x16x32_bf16 v[14:17], v[174:177], v[150:153], v[54:57]
	v_mfma_f32_16x16x32_bf16 v[26:29], v[186:189], v[150:153], v[50:53]
	v_mfma_f32_16x16x32_bf16 v[30:33], v[174:177], v[158:161], v[46:49]
	v_mfma_f32_16x16x32_bf16 v[46:49], v[190:193], v[194:197], v[42:45]
	v_mfma_f32_16x16x32_bf16 v[42:45], v[174:177], v[202:205], v[130:133]
	v_mfma_f32_16x16x32_bf16 v[34:37], v[186:189], v[202:205], v[34:37]
	v_mfma_f32_16x16x32_bf16 v[6:9], v[182:185], v[74:77], v[6:9]
	v_mfma_f32_16x16x32_bf16 v[14:17], v[182:185], v[154:157], v[14:17]
	v_mfma_f32_16x16x32_bf16 v[26:29], v[190:193], v[154:157], v[26:29]
	v_mfma_f32_16x16x32_bf16 v[30:33], v[182:185], v[194:197], v[30:33]
	v_mfma_f32_16x16x32_bf16 v[54:57], v[182:185], v[214:217], v[42:45]
	v_mfma_f32_16x16x32_bf16 v[66:69], v[190:193], v[214:217], v[34:37]
	s_setprio 0
	s_setprio 1
	v_mfma_f32_16x16x32_bf16 v[34:37], v[122:125], v[70:73], v[138:141]
	v_mfma_f32_16x16x32_bf16 v[42:45], v[206:209], v[70:73], v[142:145]
	v_mfma_f32_16x16x32_bf16 v[34:37], v[134:137], v[74:77], v[34:37]
	v_mfma_f32_16x16x32_bf16 v[50:53], v[210:213], v[74:77], v[42:45]
	v_mfma_f32_16x16x32_bf16 v[42:45], v[122:125], v[150:153], v[146:149]
	v_mfma_f32_16x16x32_bf16 v[58:61], v[206:209], v[150:153], v[178:181]
	v_mfma_f32_16x16x32_bf16 v[62:65], v[122:125], v[158:161], v[198:201]
	v_mfma_f32_16x16x32_bf16 v[70:73], v[206:209], v[158:161], v[162:165]
	v_mfma_f32_16x16x32_bf16 v[74:77], v[122:125], v[202:205], v[166:169]
	v_mfma_f32_16x16x32_bf16 v[122:125], v[206:209], v[202:205], v[170:173]
	v_mfma_f32_16x16x32_bf16 v[42:45], v[134:137], v[154:157], v[42:45]
	v_mfma_f32_16x16x32_bf16 v[58:61], v[210:213], v[154:157], v[58:61]
	v_mfma_f32_16x16x32_bf16 v[62:65], v[134:137], v[194:197], v[62:65]
	v_mfma_f32_16x16x32_bf16 v[70:73], v[210:213], v[194:197], v[70:73]
	v_mfma_f32_16x16x32_bf16 v[74:77], v[134:137], v[214:217], v[74:77]
	v_mfma_f32_16x16x32_bf16 v[122:125], v[210:213], v[214:217], v[122:125]
	s_setprio 0
	s_barrier
	s_and_saveexec_b64 s[0:1], s[90:91]
	s_cbranch_execz .LBB0_475
	s_barrier

; #define WAIT_V(n) asm volatile("s_waitcnt vmcnt(" #n ")" ::: "memory")
; #define BAR __builtin_amdgcn_s_barrier()
; template <bool OVL, bool PANEL = false, class Epi>
; __device__ __forceinline__ void gemm_phase(const bf16_t* __restrict__ A, long lda, const bf16_t* __restrict__ Bt, long ldb, int nM, int nN, int K,
;                                            const Epi& epi, bf16_t* shm, int w0) {
;     ...
;   for (int it = 0; have; ++it) {
;     const int brow = pm * BM, bcol = pn * BM;
;     f32x4 acc[2][2][4][2];
; #pragma unroll
;     for (int a0 = 0; a0 < 2; ++a0)
; #pragma unroll
;       for (int a1 = 0; a1 < 2; ++a1)
; #pragma unroll
;         for (int a2 = 0; a2 < 4; ++a2)
; #pragma unroll
;           for (int a3 = 0; a3 < 2; ++a3) acc[a0][a1][a2][a3] = (f32x4){0.f, 0.f, 0.f, 0.f};
;     bf16x8 At[4][2], B0[2][2], B1[2][2];
;     if (wr == 1) BAR;
;     WAIT_V(4); BAR;
;     STAGE(SB(1, 0), Bt, ldb, boff, bcol, 1); STAGE(SA(1, 0), A, lda, aoff, brow, 1); STAGE(SB(1, 1), Bt, ldb, boff, bcol + HALF, 1);
;     WAIT_V(6); BAR;
.LBB0_1052:
	s_or_b64 exec, exec, s[0:1]
	s_lshl_b32 s12, s57, 8
	s_ashr_i32 s13, s12, 31
	v_readlane_b32 s16, v252, 3
	s_lshl_b32 s0, s58, 8
	s_lshl_b64 s[8:9], s[12:13], 11
	v_readlane_b32 s22, v252, 9
	v_readlane_b32 s23, v252, 10
	s_add_u32 s8, s22, s8
	v_readlane_b32 s17, v252, 4
	s_addc_u32 s9, s23, s9
	v_mov_b32_e32 v0, v135
	v_add_u32_e32 v130, s96, v134
	s_waitcnt vmcnt(4)
	s_barrier
	s_mov_b64 s[16:17], 0x80
	v_lshl_add_u64 v[2:3], s[8:9], 0, v[0:1]
	v_readfirstlane_b32 s1, v130
	v_add_u32_e32 v131, 0x2000, v130
	v_lshl_add_u64 v[4:5], v[2:3], 0, s[16:17]
	s_mov_b32 m0, s1
	v_readfirstlane_b32 s1, v131
	global_load_lds_dwordx4 v[4:5], off
	s_mov_b32 m0, s1
	s_ashr_i32 s1, s0, 31
	v_readlane_b32 s40, v252, 20
	s_lshl_b64 s[10:11], s[0:1], 11
	v_readlane_b32 s46, v252, 26
	v_readlane_b32 s18, v252, 5
	v_readlane_b32 s19, v252, 6
	v_readlane_b32 s47, v252, 27
	s_add_u32 s10, s46, s10
	s_mov_b64 s[18:19], 0x20080
	s_addc_u32 s11, s47, s11
	s_or_b32 s14, s12, 0x80
	v_lshl_add_u64 v[2:3], v[2:3], 0, s[18:19]
	v_mov_b32_e32 v0, v135
	v_add_u32_e32 v132, 0x8000, v138
	s_ashr_i32 s15, s14, 31
	global_load_lds_dwordx4 v[2:3], off
	v_readfirstlane_b32 s1, v132
	v_lshl_add_u64 v[2:3], s[10:11], 0, v[0:1]
	v_add_u32_e32 v133, 0xa000, v138
	s_lshl_b64 s[14:15], s[14:15], 11
	v_lshl_add_u64 v[4:5], v[2:3], 0, s[16:17]
	s_mov_b32 m0, s1
	v_readfirstlane_b32 s1, v133
	s_add_u32 s14, s22, s14
	global_load_lds_dwordx4 v[4:5], off
	v_lshl_add_u64 v[2:3], v[2:3], 0, s[18:19]
	s_mov_b32 m0, s1
	s_addc_u32 s15, s23, s15
	v_mov_b32_e32 v0, v135
	v_add_u32_e32 v148, s75, v134
	global_load_lds_dwordx4 v[2:3], off
	v_readfirstlane_b32 s1, v148
	v_lshl_add_u64 v[2:3], s[14:15], 0, v[0:1]
	v_add_u32_e32 v149, 0x2000, v148
	v_lshl_add_u64 v[4:5], v[2:3], 0, s[16:17]
	s_mov_b32 m0, s1
	v_readfirstlane_b32 s1, v149
	global_load_lds_dwordx4 v[4:5], off
	v_lshl_add_u64 v[2:3], v[2:3], 0, s[18:19]
	s_mov_b32 m0, s1
	v_readlane_b32 s20, v252, 7
	global_load_lds_dwordx4 v[2:3], off
	s_waitcnt vmcnt(6)
	v_readlane_b32 s21, v252, 8
	v_mov_b32_e32 v2, 0
	s_mov_b32 s1, -2
	s_mov_b64 s[14:15], 0
	v_mov_b32_e32 v3, v2
	v_mov_b32_e32 v4, v2
	v_mov_b32_e32 v5, v2
	v_mov_b32_e32 v6, v2
	v_mov_b32_e32 v7, v2
	v_mov_b32_e32 v8, v2
	v_mov_b32_e32 v9, v2
	v_mov_b32_e32 v10, v2
	v_mov_b32_e32 v11, v2
	v_mov_b32_e32 v12, v2
	v_mov_b32_e32 v13, v2
	s_waitcnt lgkmcnt(0)
	v_mov_b32_e32 v14, v2
	v_mov_b32_e32 v15, v2
	v_mov_b32_e32 v16, v2
	v_mov_b32_e32 v17, v2
	v_mov_b32_e32 v18, v2
	v_mov_b32_e32 v19, v2
	v_mov_b32_e32 v20, v2
	v_mov_b32_e32 v21, v2
	v_mov_b32_e32 v22, v2
	v_mov_b32_e32 v23, v2
	v_mov_b32_e32 v24, v2
	v_mov_b32_e32 v25, v2
	v_mov_b32_e32 v26, v2
	v_mov_b32_e32 v27, v2
	v_mov_b32_e32 v28, v2
	v_mov_b32_e32 v29, v2
	v_mov_b32_e32 v30, v2
	v_mov_b32_e32 v31, v2
	v_mov_b32_e32 v32, v2
	v_mov_b32_e32 v33, v2
	v_mov_b32_e32 v34, v2
	v_mov_b32_e32 v35, v2
	v_mov_b32_e32 v36, v2
	v_mov_b32_e32 v37, v2
	v_mov_b32_e32 v38, v2
	v_mov_b32_e32 v39, v2
	v_mov_b32_e32 v40, v2
	v_mov_b32_e32 v41, v2
	v_mov_b32_e32 v42, v2
	v_mov_b32_e32 v43, v2
	v_mov_b32_e32 v44, v2
	v_mov_b32_e32 v45, v2
	v_mov_b32_e32 v46, v2
	v_mov_b32_e32 v47, v2
	v_mov_b32_e32 v48, v2
	v_mov_b32_e32 v49, v2
	v_mov_b32_e32 v50, v2
	v_mov_b32_e32 v51, v2
	v_mov_b32_e32 v52, v2
	v_mov_b32_e32 v53, v2
	v_mov_b32_e32 v54, v2
	v_mov_b32_e32 v55, v2
	v_mov_b32_e32 v56, v2
	v_mov_b32_e32 v57, v2
	v_mov_b32_e32 v58, v2
	v_mov_b32_e32 v59, v2
	v_mov_b32_e32 v60, v2
	v_mov_b32_e32 v61, v2
	v_mov_b32_e32 v62, v2
	v_mov_b32_e32 v63, v2
	v_mov_b32_e32 v64, v2
	v_mov_b32_e32 v65, v2
	v_mov_b32_e32 v66, v2
	v_mov_b32_e32 v67, v2
	v_mov_b32_e32 v68, v2
	v_mov_b32_e32 v69, v2
	v_mov_b32_e32 v70, v2
	v_mov_b32_e32 v71, v2
	v_mov_b32_e32 v72, v2
	v_mov_b32_e32 v73, v2
	v_mov_b32_e32 v74, v2
	v_mov_b32_e32 v75, v2
	v_mov_b32_e32 v76, v2
	v_mov_b32_e32 v77, v2
	v_mov_b32_e32 v78, v2
	v_mov_b32_e32 v79, v2
	v_mov_b32_e32 v80, v2
	v_mov_b32_e32 v81, v2
	v_mov_b32_e32 v82, v2
	v_mov_b32_e32 v83, v2
	v_mov_b32_e32 v84, v2
	v_mov_b32_e32 v85, v2
	v_mov_b32_e32 v86, v2
	v_mov_b32_e32 v87, v2
	v_mov_b32_e32 v88, v2
	v_mov_b32_e32 v89, v2
	v_mov_b32_e32 v90, v2
	v_mov_b32_e32 v91, v2
	v_mov_b32_e32 v92, v2
	v_mov_b32_e32 v93, v2
	v_mov_b32_e32 v94, v2
	v_mov_b32_e32 v95, v2
	v_mov_b32_e32 v96, v2
	v_mov_b32_e32 v97, v2
	v_mov_b32_e32 v98, v2
	v_mov_b32_e32 v99, v2
	v_mov_b32_e32 v100, v2
	v_mov_b32_e32 v101, v2
	v_mov_b32_e32 v102, v2
	v_mov_b32_e32 v103, v2
	v_mov_b32_e32 v104, v2
	v_mov_b32_e32 v105, v2
	v_mov_b32_e32 v106, v2
	v_mov_b32_e32 v107, v2
	v_mov_b32_e32 v108, v2
	v_mov_b32_e32 v109, v2
	v_mov_b32_e32 v110, v2
	v_mov_b32_e32 v111, v2
	v_mov_b32_e32 v112, v2
	v_mov_b32_e32 v113, v2
	v_mov_b32_e32 v114, v2
	v_mov_b32_e32 v115, v2
	v_mov_b32_e32 v116, v2
	v_mov_b32_e32 v117, v2
	v_mov_b32_e32 v118, v2
	v_mov_b32_e32 v119, v2
	v_mov_b32_e32 v120, v2
	v_mov_b32_e32 v121, v2
	v_mov_b32_e32 v122, v2
	v_mov_b32_e32 v123, v2
	v_mov_b32_e32 v124, v2
	v_mov_b32_e32 v125, v2
	v_mov_b32_e32 v126, v2
	v_mov_b32_e32 v127, v2
	v_mov_b32_e32 v128, v2
	v_mov_b32_e32 v129, v2
	s_mov_b64 s[16:17], 0x40080
	s_mov_b64 s[18:19], 0x40180
	s_mov_b64 s[20:21], 0x60180
	v_readlane_b32 s24, v252, 11
	v_readlane_b32 s25, v252, 12
	v_readlane_b32 s26, v252, 13
	v_readlane_b32 s27, v252, 14
	v_readlane_b32 s28, v252, 15
	v_readlane_b32 s29, v252, 16
	v_readlane_b32 s30, v252, 17
	v_readlane_b32 s31, v252, 18
	v_readlane_b32 s41, v252, 21
	v_readlane_b32 s42, v252, 22
	v_readlane_b32 s43, v252, 23
	v_readlane_b32 s44, v252, 24
	v_readlane_b32 s45, v252, 25
	v_readlane_b32 s48, v252, 28
	v_readlane_b32 s49, v252, 29
	v_readlane_b32 s50, v252, 30
	v_readlane_b32 s51, v252, 31
	v_readlane_b32 s52, v252, 32
	v_readlane_b32 s53, v252, 33
	v_readlane_b32 s54, v252, 34
	v_readlane_b32 s55, v252, 35
	s_barrier
	v_add_u32_e32 v184, s2, v144
	v_readfirstlane_b32 s22, v138
	s_add_u32 s22, s22, 0xc000
	v_readfirstlane_b32 s23, v138
	s_add_u32 s23, s23, 0xe000
	v_add_u32_e32 v185, s33, v144
	v_readfirstlane_b32 s24, v136
	v_readfirstlane_b32 s25, v137
	v_readfirstlane_b32 s26, v138
	v_readfirstlane_b32 s27, v139
	v_readfirstlane_b32 s28, v140
	v_readfirstlane_b32 s29, v141
	v_add_u32_e32 v186, s96, v144
	v_readfirstlane_b32 s30, v142
	v_readfirstlane_b32 s31, v143
	v_add_u32_e32 v187, s75, v144
	v_readfirstlane_b32 s32, v130
	v_readfirstlane_b32 s44, v131
	v_readfirstlane_b32 s45, v132
	v_readfirstlane_b32 s46, v133
	v_readfirstlane_b32 s47, v148
	v_readfirstlane_b32 s48, v149
	v_add_u32_e32 v150, 0xc000, v138
	v_add_u32_e32 v151, 0xe000, v138
; #define LDA(dst, b, h) for (int m = 0; m < 4; ++m) for (int k = 0; k < 2; ++k) \
;     dst[m][k] = *reinterpret_cast<const bf16x8*>((char*)SA(b, h) + a_thr + (m * 2 + k) * 1024)
; #define LDB(dst, b, h) for (int n = 0; n < 2; ++n) for (int k = 0; k < 2; ++k) \
;     dst[n][k] = *reinterpret_cast<const bf16x8*>((char*)SB(b, h) + b_thr + (n * 2 + k) * 1024)
; #define MMA(ai, bj, At, Btf) do { __builtin_amdgcn_s_setprio(1); \
;     for (int m = 0; m < 4; ++m) for (int n = 0; n < 2; ++n) for (int k = 0; k < 2; ++k) \
;       acc[ai][bj][m][n] = __builtin_amdgcn_mfma_f32_16x16x32_bf16(Btf[n][k], At[m][k], acc[ai][bj][m][n], 0, 0, 0); \
;     __builtin_amdgcn_s_setprio(0); } while (0)
; #define WAIT_V(n) asm volatile("s_waitcnt vmcnt(" #n ")" ::: "memory")
; #define WAIT_L(n) asm volatile("s_waitcnt lgkmcnt(" #n ")" ::: "memory")
; #define BAR __builtin_amdgcn_s_barrier()
; #define SCHED __builtin_amdgcn_sched_barrier(0)
; template <bool OVL, bool PANEL = false, class Epi>
; __device__ __forceinline__ void gemm_phase(const bf16_t* __restrict__ A, long lda, const bf16_t* __restrict__ Bt, long ldb, int nM, int nN, int K,
;                                            const Epi& epi, bf16_t* shm, int w0) {
;     ...
;     for (int t = 0; t < nt - 2; t += 2) {
;       LDB(B0, 0, 0); SCHED; LDA(At, 0, 0); STAGE(SA(1, 1), A, lda, aoff, brow + HALF, t + 1);
;       WAIT_L(8); BAR; WAIT_L(0); MMA(0, 0, At, B0); BAR; SCHED;
;       LDB(B1, 0, 1); STAGE(SB(0, 0), Bt, ldb, boff, bcol, t + 2);
;       BAR; WAIT_L(0); MMA(0, 1, At, B1); BAR;
;       LDA(At, 0, 1); STAGE(SA(0, 0), A, lda, aoff, brow, t + 2);
;       BAR; WAIT_L(0); MMA(1, 0, At, B0); BAR; SCHED;
;       STAGE(SB(0, 1), Bt, ldb, boff, bcol + HALF, t + 2);
;       WAIT_V(6); BAR; MMA(1, 1, At, B1); BAR;
.LBB0_1053:
	ds_read_b128 v[152:155], v184
	ds_read_b128 v[156:159], v184 offset:1024
	ds_read_b128 v[160:163], v184 offset:2048
	ds_read_b128 v[164:167], v184 offset:3072
	s_add_u32 s40, s10, s14
	s_addc_u32 s41, s11, s15
	ds_read_b128 v[168:171], v147
	ds_read_b128 v[172:175], v147 offset:1024
	ds_read_b128 v[176:179], v147 offset:2048
	ds_read_b128 v[194:197], v147 offset:3072
	ds_read_b128 v[198:201], v147 offset:4096
	ds_read_b128 v[202:205], v147 offset:5120
	ds_read_b128 v[206:209], v147 offset:6144
	ds_read_b128 v[210:213], v147 offset:7168
	s_mov_b32 m0, s22
	s_add_u32 s98, s40, s16
	s_addc_u32 s99, s41, s17
	global_load_lds_dwordx4 v135, s[98:99]
	s_mov_b32 m0, s23
	s_add_u32 s98, s40, s36
	s_addc_u32 s99, s41, s37
	global_load_lds_dwordx4 v135, s[98:99]
	s_waitcnt lgkmcnt(8)
	s_barrier
	s_waitcnt lgkmcnt(0)
	s_setprio 1
	s_waitcnt lgkmcnt(0)
	v_mfma_f32_16x16x32_bf16 v[126:129], v[152:155], v[168:171], v[126:129]
	v_mfma_f32_16x16x32_bf16 v[122:125], v[160:163], v[168:171], v[122:125]
	v_mfma_f32_16x16x32_bf16 v[118:121], v[152:155], v[176:179], v[118:121]
	v_mfma_f32_16x16x32_bf16 v[114:117], v[160:163], v[176:179], v[114:117]
	v_mfma_f32_16x16x32_bf16 v[110:113], v[152:155], v[198:201], v[110:113]
	v_mfma_f32_16x16x32_bf16 v[106:109], v[160:163], v[198:201], v[106:109]
	v_mfma_f32_16x16x32_bf16 v[102:105], v[152:155], v[206:209], v[102:105]
	v_mfma_f32_16x16x32_bf16 v[98:101], v[160:163], v[206:209], v[98:101]
	v_mfma_f32_16x16x32_bf16 v[126:129], v[156:159], v[172:175], v[126:129]
	v_mfma_f32_16x16x32_bf16 v[122:125], v[164:167], v[172:175], v[122:125]
	v_mfma_f32_16x16x32_bf16 v[118:121], v[156:159], v[194:197], v[118:121]
	v_mfma_f32_16x16x32_bf16 v[114:117], v[164:167], v[194:197], v[114:117]
	v_mfma_f32_16x16x32_bf16 v[110:113], v[156:159], v[202:205], v[110:113]
	v_mfma_f32_16x16x32_bf16 v[106:109], v[164:167], v[202:205], v[106:109]
	v_mfma_f32_16x16x32_bf16 v[102:105], v[156:159], v[210:213], v[102:105]
	v_mfma_f32_16x16x32_bf16 v[98:101], v[164:167], v[210:213], v[98:101]
	s_setprio 0
	s_barrier
	s_add_u32 s42, s8, s14
	ds_read_b128 v[214:217], v185
	ds_read_b128 v[218:221], v185 offset:1024
	ds_read_b128 v[234:237], v185 offset:2048
	ds_read_b128 v[238:241], v185 offset:3072
	s_addc_u32 s43, s9, s15
	s_mov_b32 m0, s24
	s_add_u32 s98, s42, s34
	s_addc_u32 s99, s43, s35
	global_load_lds_dwordx4 v135, s[98:99]
	s_mov_b32 m0, s25
	s_add_u32 s98, s42, s64
	s_addc_u32 s99, s43, s65
	global_load_lds_dwordx4 v135, s[98:99]
	s_barrier
	s_waitcnt lgkmcnt(0)
	s_setprio 1
	s_waitcnt lgkmcnt(0)
	v_mfma_f32_16x16x32_bf16 v[94:97], v[214:217], v[168:171], v[94:97]
	v_mfma_f32_16x16x32_bf16 v[90:93], v[234:237], v[168:171], v[90:93]
	v_mfma_f32_16x16x32_bf16 v[86:89], v[214:217], v[176:179], v[86:89]
	v_mfma_f32_16x16x32_bf16 v[82:85], v[234:237], v[176:179], v[82:85]
	v_mfma_f32_16x16x32_bf16 v[78:81], v[214:217], v[198:201], v[78:81]
	v_mfma_f32_16x16x32_bf16 v[74:77], v[234:237], v[198:201], v[74:77]
	v_mfma_f32_16x16x32_bf16 v[70:73], v[214:217], v[206:209], v[70:73]
	v_mfma_f32_16x16x32_bf16 v[66:69], v[234:237], v[206:209], v[66:69]
	v_mfma_f32_16x16x32_bf16 v[94:97], v[218:221], v[172:175], v[94:97]
	v_mfma_f32_16x16x32_bf16 v[90:93], v[238:241], v[172:175], v[90:93]
	v_mfma_f32_16x16x32_bf16 v[86:89], v[218:221], v[194:197], v[86:89]
	v_mfma_f32_16x16x32_bf16 v[82:85], v[238:241], v[194:197], v[82:85]
	v_mfma_f32_16x16x32_bf16 v[78:81], v[218:221], v[202:205], v[78:81]
	v_mfma_f32_16x16x32_bf16 v[74:77], v[238:241], v[202:205], v[74:77]
	v_mfma_f32_16x16x32_bf16 v[70:73], v[218:221], v[210:213], v[70:73]
	v_mfma_f32_16x16x32_bf16 v[66:69], v[238:241], v[210:213], v[66:69]
	s_setprio 0
	s_barrier
	ds_read_b128 v[168:171], v147 offset:16384
	ds_read_b128 v[172:175], v147 offset:17408
	ds_read_b128 v[176:179], v147 offset:18432
	ds_read_b128 v[194:197], v147 offset:19456
	ds_read_b128 v[198:201], v147 offset:20480
	ds_read_b128 v[202:205], v147 offset:21504
	ds_read_b128 v[206:209], v147 offset:22528
	ds_read_b128 v[210:213], v147 offset:23552
	s_mov_b32 m0, s26
	s_add_u32 s98, s40, s34
	s_addc_u32 s99, s41, s35
	global_load_lds_dwordx4 v135, s[98:99]
	s_mov_b32 m0, s27
	s_add_u32 s98, s40, s64
	s_addc_u32 s99, s41, s65
	global_load_lds_dwordx4 v135, s[98:99]
	s_barrier
	s_waitcnt lgkmcnt(0)
	s_setprio 1
	s_waitcnt lgkmcnt(0)
	v_mfma_f32_16x16x32_bf16 v[62:65], v[152:155], v[168:171], v[62:65]
	v_mfma_f32_16x16x32_bf16 v[58:61], v[160:163], v[168:171], v[58:61]
	v_mfma_f32_16x16x32_bf16 v[54:57], v[152:155], v[176:179], v[54:57]
	v_mfma_f32_16x16x32_bf16 v[50:53], v[160:163], v[176:179], v[50:53]
	v_mfma_f32_16x16x32_bf16 v[46:49], v[152:155], v[198:201], v[46:49]
	v_mfma_f32_16x16x32_bf16 v[42:45], v[160:163], v[198:201], v[42:45]
	v_mfma_f32_16x16x32_bf16 v[38:41], v[152:155], v[206:209], v[38:41]
	v_mfma_f32_16x16x32_bf16 v[34:37], v[160:163], v[206:209], v[34:37]
	v_mfma_f32_16x16x32_bf16 v[62:65], v[156:159], v[172:175], v[62:65]
	v_mfma_f32_16x16x32_bf16 v[58:61], v[164:167], v[172:175], v[58:61]
	v_mfma_f32_16x16x32_bf16 v[54:57], v[156:159], v[194:197], v[54:57]
	v_mfma_f32_16x16x32_bf16 v[50:53], v[164:167], v[194:197], v[50:53]
	v_mfma_f32_16x16x32_bf16 v[46:49], v[156:159], v[202:205], v[46:49]
	v_mfma_f32_16x16x32_bf16 v[42:45], v[164:167], v[202:205], v[42:45]
	v_mfma_f32_16x16x32_bf16 v[38:41], v[156:159], v[210:213], v[38:41]
	v_mfma_f32_16x16x32_bf16 v[34:37], v[164:167], v[210:213], v[34:37]
	s_setprio 0
	s_barrier
	s_mov_b32 m0, s28
	s_add_u32 s98, s42, s68
	s_addc_u32 s99, s43, s69
	global_load_lds_dwordx4 v135, s[98:99]
	s_mov_b32 m0, s29
	s_add_u32 s98, s42, s70
	s_addc_u32 s99, s43, s71
	global_load_lds_dwordx4 v135, s[98:99]
	s_waitcnt vmcnt(6)
	s_barrier
; #define LDA(dst, b, h) for (int m = 0; m < 4; ++m) for (int k = 0; k < 2; ++k) \
;     dst[m][k] = *reinterpret_cast<const bf16x8*>((char*)SA(b, h) + a_thr + (m * 2 + k) * 1024)
; #define LDB(dst, b, h) for (int n = 0; n < 2; ++n) for (int k = 0; k < 2; ++k) \
;     dst[n][k] = *reinterpret_cast<const bf16x8*>((char*)SB(b, h) + b_thr + (n * 2 + k) * 1024)
; #define MMA(ai, bj, At, Btf) do { __builtin_amdgcn_s_setprio(1); \
;     for (int m = 0; m < 4; ++m) for (int n = 0; n < 2; ++n) for (int k = 0; k < 2; ++k) \
;       acc[ai][bj][m][n] = __builtin_amdgcn_mfma_f32_16x16x32_bf16(Btf[n][k], At[m][k], acc[ai][bj][m][n], 0, 0, 0); \
;     __builtin_amdgcn_s_setprio(0); } while (0)
; #define WAIT_V(n) asm volatile("s_waitcnt vmcnt(" #n ")" ::: "memory")
; #define WAIT_L(n) asm volatile("s_waitcnt lgkmcnt(" #n ")" ::: "memory")
; #define BAR __builtin_amdgcn_s_barrier()
; #define SCHED __builtin_amdgcn_sched_barrier(0)
; template <bool OVL, bool PANEL = false, class Epi>
; __device__ __forceinline__ void gemm_phase(const bf16_t* __restrict__ A, long lda, const bf16_t* __restrict__ Bt, long ldb, int nM, int nN, int K,
;                                            const Epi& epi, bf16_t* shm, int w0) {
;     ...
;       WAIT_V(6); BAR; MMA(1, 1, At, B1); BAR;
;       LDB(B0, 1, 0); SCHED; LDA(At, 1, 0); STAGE(SA(0, 1), A, lda, aoff, brow + HALF, t + 2);
;       WAIT_L(8); BAR; WAIT_L(0); MMA(0, 0, At, B0); BAR; SCHED;
;       LDB(B1, 1, 1); STAGE(SB(1, 0), Bt, ldb, boff, bcol, t + 3);
;       BAR; WAIT_L(0); MMA(0, 1, At, B1); BAR;
;       LDA(At, 1, 1); STAGE(SA(1, 0), A, lda, aoff, brow, t + 3);
	s_setprio 1
	v_mfma_f32_16x16x32_bf16 v[30:33], v[214:217], v[168:171], v[30:33]
	v_mfma_f32_16x16x32_bf16 v[26:29], v[234:237], v[168:171], v[26:29]
	v_mfma_f32_16x16x32_bf16 v[22:25], v[214:217], v[176:179], v[22:25]
	v_mfma_f32_16x16x32_bf16 v[18:21], v[234:237], v[176:179], v[18:21]
	v_mfma_f32_16x16x32_bf16 v[14:17], v[214:217], v[198:201], v[14:17]
	v_mfma_f32_16x16x32_bf16 v[10:13], v[234:237], v[198:201], v[10:13]
	v_mfma_f32_16x16x32_bf16 v[6:9], v[214:217], v[206:209], v[6:9]
	v_mfma_f32_16x16x32_bf16 v[2:5], v[234:237], v[206:209], v[2:5]
	v_mfma_f32_16x16x32_bf16 v[30:33], v[218:221], v[172:175], v[30:33]
	v_mfma_f32_16x16x32_bf16 v[26:29], v[238:241], v[172:175], v[26:29]
	v_mfma_f32_16x16x32_bf16 v[22:25], v[218:221], v[194:197], v[22:25]
	v_mfma_f32_16x16x32_bf16 v[18:21], v[238:241], v[194:197], v[18:21]
	v_mfma_f32_16x16x32_bf16 v[14:17], v[218:221], v[202:205], v[14:17]
	v_mfma_f32_16x16x32_bf16 v[10:13], v[238:241], v[202:205], v[10:13]
	v_mfma_f32_16x16x32_bf16 v[6:9], v[218:221], v[210:213], v[6:9]
	v_mfma_f32_16x16x32_bf16 v[2:5], v[238:241], v[210:213], v[2:5]
	s_setprio 0
	s_barrier
	ds_read_b128 v[152:155], v186
	ds_read_b128 v[156:159], v186 offset:1024
	ds_read_b128 v[160:163], v186 offset:2048
	ds_read_b128 v[164:167], v186 offset:3072
	ds_read_b128 v[168:171], v147 offset:32768
	ds_read_b128 v[172:175], v147 offset:33792
	ds_read_b128 v[176:179], v147 offset:34816
	ds_read_b128 v[194:197], v147 offset:35840
	ds_read_b128 v[198:201], v147 offset:36864
	ds_read_b128 v[202:205], v147 offset:37888
	ds_read_b128 v[206:209], v147 offset:38912
	ds_read_b128 v[210:213], v147 offset:39936
	s_mov_b32 m0, s30
	s_add_u32 s98, s40, s68
	s_addc_u32 s99, s41, s69
	global_load_lds_dwordx4 v135, s[98:99]
	s_mov_b32 m0, s31
	s_add_u32 s98, s40, s70
	s_addc_u32 s99, s41, s71
	global_load_lds_dwordx4 v135, s[98:99]
	s_waitcnt lgkmcnt(8)
	s_barrier
	s_waitcnt lgkmcnt(0)
	s_setprio 1
	s_waitcnt lgkmcnt(0)
	v_mfma_f32_16x16x32_bf16 v[126:129], v[152:155], v[168:171], v[126:129]
	v_mfma_f32_16x16x32_bf16 v[122:125], v[160:163], v[168:171], v[122:125]
	v_mfma_f32_16x16x32_bf16 v[118:121], v[152:155], v[176:179], v[118:121]
	v_mfma_f32_16x16x32_bf16 v[114:117], v[160:163], v[176:179], v[114:117]
	v_mfma_f32_16x16x32_bf16 v[110:113], v[152:155], v[198:201], v[110:113]
	v_mfma_f32_16x16x32_bf16 v[106:109], v[160:163], v[198:201], v[106:109]
	v_mfma_f32_16x16x32_bf16 v[102:105], v[152:155], v[206:209], v[102:105]
	v_mfma_f32_16x16x32_bf16 v[98:101], v[160:163], v[206:209], v[98:101]
	v_mfma_f32_16x16x32_bf16 v[126:129], v[156:159], v[172:175], v[126:129]
	v_mfma_f32_16x16x32_bf16 v[122:125], v[164:167], v[172:175], v[122:125]
	v_mfma_f32_16x16x32_bf16 v[118:121], v[156:159], v[194:197], v[118:121]
	v_mfma_f32_16x16x32_bf16 v[114:117], v[164:167], v[194:197], v[114:117]
	v_mfma_f32_16x16x32_bf16 v[110:113], v[156:159], v[202:205], v[110:113]
	v_mfma_f32_16x16x32_bf16 v[106:109], v[164:167], v[202:205], v[106:109]
	v_mfma_f32_16x16x32_bf16 v[102:105], v[156:159], v[210:213], v[102:105]
	v_mfma_f32_16x16x32_bf16 v[98:101], v[164:167], v[210:213], v[98:101]
	s_setprio 0
	s_barrier
	ds_read_b128 v[214:217], v187
	ds_read_b128 v[218:221], v187 offset:1024
	ds_read_b128 v[234:237], v187 offset:2048
	ds_read_b128 v[238:241], v187 offset:3072
	s_mov_b32 m0, s32
	s_add_u32 s98, s42, s94
	s_addc_u32 s99, s43, s95
	global_load_lds_dwordx4 v135, s[98:99]
	s_mov_b32 m0, s44
	s_add_u32 s98, s42, s72
	s_addc_u32 s99, s43, s73
	global_load_lds_dwordx4 v135, s[98:99]
	s_barrier
	s_waitcnt lgkmcnt(0)
	s_setprio 1
	s_waitcnt lgkmcnt(0)
	v_mfma_f32_16x16x32_bf16 v[94:97], v[214:217], v[168:171], v[94:97]
	v_mfma_f32_16x16x32_bf16 v[90:93], v[234:237], v[168:171], v[90:93]
	v_mfma_f32_16x16x32_bf16 v[86:89], v[214:217], v[176:179], v[86:89]
	v_mfma_f32_16x16x32_bf16 v[82:85], v[234:237], v[176:179], v[82:85]
	v_mfma_f32_16x16x32_bf16 v[78:81], v[214:217], v[198:201], v[78:81]
	v_mfma_f32_16x16x32_bf16 v[74:77], v[234:237], v[198:201], v[74:77]
	v_mfma_f32_16x16x32_bf16 v[70:73], v[214:217], v[206:209], v[70:73]
	v_mfma_f32_16x16x32_bf16 v[66:69], v[234:237], v[206:209], v[66:69]
	v_mfma_f32_16x16x32_bf16 v[94:97], v[218:221], v[172:175], v[94:97]
	v_mfma_f32_16x16x32_bf16 v[90:93], v[238:241], v[172:175], v[90:93]
	v_mfma_f32_16x16x32_bf16 v[86:89], v[218:221], v[194:197], v[86:89]
	v_mfma_f32_16x16x32_bf16 v[82:85], v[238:241], v[194:197], v[82:85]
	v_mfma_f32_16x16x32_bf16 v[78:81], v[218:221], v[202:205], v[78:81]
	v_mfma_f32_16x16x32_bf16 v[74:77], v[238:241], v[202:205], v[74:77]
	v_mfma_f32_16x16x32_bf16 v[70:73], v[218:221], v[210:213], v[70:73]
	v_mfma_f32_16x16x32_bf16 v[66:69], v[238:241], v[210:213], v[66:69]
	s_setprio 0
	s_barrier
	ds_read_b128 v[168:171], v147 offset:49152
	ds_read_b128 v[172:175], v147 offset:50176
	ds_read_b128 v[176:179], v147 offset:51200
	ds_read_b128 v[194:197], v147 offset:52224
	ds_read_b128 v[198:201], v147 offset:53248
	ds_read_b128 v[202:205], v147 offset:54272
	ds_read_b128 v[206:209], v147 offset:55296
	ds_read_b128 v[210:213], v147 offset:56320
	s_mov_b32 m0, s45
	s_add_u32 s98, s40, s94
	s_addc_u32 s99, s41, s95
	global_load_lds_dwordx4 v135, s[98:99]
	s_mov_b32 m0, s46
	s_add_u32 s98, s40, s72
	s_addc_u32 s99, s41, s73
	global_load_lds_dwordx4 v135, s[98:99]
	s_barrier
; #define LDA(dst, b, h) for (int m = 0; m < 4; ++m) for (int k = 0; k < 2; ++k) \
;     dst[m][k] = *reinterpret_cast<const bf16x8*>((char*)SA(b, h) + a_thr + (m * 2 + k) * 1024)
; #define LDB(dst, b, h) for (int n = 0; n < 2; ++n) for (int k = 0; k < 2; ++k) \
;     dst[n][k] = *reinterpret_cast<const bf16x8*>((char*)SB(b, h) + b_thr + (n * 2 + k) * 1024)
; #define MMA(ai, bj, At, Btf) do { __builtin_amdgcn_s_setprio(1); \
;     for (int m = 0; m < 4; ++m) for (int n = 0; n < 2; ++n) for (int k = 0; k < 2; ++k) \
;       acc[ai][bj][m][n] = __builtin_amdgcn_mfma_f32_16x16x32_bf16(Btf[n][k], At[m][k], acc[ai][bj][m][n], 0, 0, 0); \
;     __builtin_amdgcn_s_setprio(0); } while (0)
; #define WAIT_V(n) asm volatile("s_waitcnt vmcnt(" #n ")" ::: "memory")
; #define WAIT_L(n) asm volatile("s_waitcnt lgkmcnt(" #n ")" ::: "memory")
; #define BAR __builtin_amdgcn_s_barrier()
; #define SCHED __builtin_amdgcn_sched_barrier(0)
; template <bool OVL, bool PANEL = false, class Epi>
; __device__ __forceinline__ void gemm_phase(const bf16_t* __restrict__ A, long lda, const bf16_t* __restrict__ Bt, long ldb, int nM, int nN, int K,
;                                            const Epi& epi, bf16_t* shm, int w0) {
;     ...
;       LDA(At, 1, 1); STAGE(SA(1, 0), A, lda, aoff, brow, t + 3);
;       BAR; WAIT_L(0); MMA(1, 0, At, B0); BAR; SCHED;
;       STAGE(SB(1, 1), Bt, ldb, boff, bcol + HALF, t + 3);
;       WAIT_V(6); BAR; MMA(1, 1, At, B1); BAR;
;     }
;     { LDB(B0, 0, 0); LDA(At, 0, 0); STAGE(SA(1, 1), A, lda, aoff, brow + HALF, nt - 1);
;       BAR; WAIT_L(0); MMA(0, 0, At, B0); BAR;
;       LDB(B1, 0, 1); BAR; WAIT_L(0); MMA(0, 1, At, B1); BAR;
	s_waitcnt lgkmcnt(0)
	s_setprio 1
	s_waitcnt lgkmcnt(0)
	v_mfma_f32_16x16x32_bf16 v[62:65], v[152:155], v[168:171], v[62:65]
	v_mfma_f32_16x16x32_bf16 v[58:61], v[160:163], v[168:171], v[58:61]
	v_mfma_f32_16x16x32_bf16 v[54:57], v[152:155], v[176:179], v[54:57]
	v_mfma_f32_16x16x32_bf16 v[50:53], v[160:163], v[176:179], v[50:53]
	v_mfma_f32_16x16x32_bf16 v[46:49], v[152:155], v[198:201], v[46:49]
	v_mfma_f32_16x16x32_bf16 v[42:45], v[160:163], v[198:201], v[42:45]
	v_mfma_f32_16x16x32_bf16 v[38:41], v[152:155], v[206:209], v[38:41]
	v_mfma_f32_16x16x32_bf16 v[34:37], v[160:163], v[206:209], v[34:37]
	v_mfma_f32_16x16x32_bf16 v[62:65], v[156:159], v[172:175], v[62:65]
	v_mfma_f32_16x16x32_bf16 v[58:61], v[164:167], v[172:175], v[58:61]
	v_mfma_f32_16x16x32_bf16 v[54:57], v[156:159], v[194:197], v[54:57]
	v_mfma_f32_16x16x32_bf16 v[50:53], v[164:167], v[194:197], v[50:53]
	v_mfma_f32_16x16x32_bf16 v[46:49], v[156:159], v[202:205], v[46:49]
	v_mfma_f32_16x16x32_bf16 v[42:45], v[164:167], v[202:205], v[42:45]
	v_mfma_f32_16x16x32_bf16 v[38:41], v[156:159], v[210:213], v[38:41]
	v_mfma_f32_16x16x32_bf16 v[34:37], v[164:167], v[210:213], v[34:37]
	s_setprio 0
	s_barrier
	s_mov_b32 m0, s47
	s_add_u32 s98, s42, s18
	s_addc_u32 s99, s43, s19
	global_load_lds_dwordx4 v135, s[98:99]
	s_mov_b32 m0, s48
	s_add_u32 s98, s42, s20
	s_addc_u32 s99, s43, s21
	global_load_lds_dwordx4 v135, s[98:99]
	s_waitcnt vmcnt(6)
	s_barrier
	s_setprio 1
	v_mfma_f32_16x16x32_bf16 v[30:33], v[214:217], v[168:171], v[30:33]
	v_mfma_f32_16x16x32_bf16 v[26:29], v[234:237], v[168:171], v[26:29]
	v_mfma_f32_16x16x32_bf16 v[22:25], v[214:217], v[176:179], v[22:25]
	v_mfma_f32_16x16x32_bf16 v[18:21], v[234:237], v[176:179], v[18:21]
	v_mfma_f32_16x16x32_bf16 v[14:17], v[214:217], v[198:201], v[14:17]
	v_mfma_f32_16x16x32_bf16 v[10:13], v[234:237], v[198:201], v[10:13]
	v_mfma_f32_16x16x32_bf16 v[6:9], v[214:217], v[206:209], v[6:9]
	v_mfma_f32_16x16x32_bf16 v[2:5], v[234:237], v[206:209], v[2:5]
	v_mfma_f32_16x16x32_bf16 v[30:33], v[218:221], v[172:175], v[30:33]
	v_mfma_f32_16x16x32_bf16 v[26:29], v[238:241], v[172:175], v[26:29]
	v_mfma_f32_16x16x32_bf16 v[22:25], v[218:221], v[194:197], v[22:25]
	v_mfma_f32_16x16x32_bf16 v[18:21], v[238:241], v[194:197], v[18:21]
	v_mfma_f32_16x16x32_bf16 v[14:17], v[218:221], v[202:205], v[14:17]
	v_mfma_f32_16x16x32_bf16 v[10:13], v[238:241], v[202:205], v[10:13]
	v_mfma_f32_16x16x32_bf16 v[6:9], v[218:221], v[210:213], v[6:9]
	v_mfma_f32_16x16x32_bf16 v[2:5], v[238:241], v[210:213], v[2:5]
	s_setprio 0
	s_add_i32 s1, s1, 2
	s_add_u32 s14, s14, 0x100
	s_addc_u32 s15, s15, 0
	s_cmp_lt_u32 s1, 12
	s_barrier
	s_cbranch_scc1 .LBB0_1053
	s_or_b32 s8, s0, 0x80
	s_ashr_i32 s9, s8, 31
	v_readlane_b32 s40, v252, 20
	s_lshl_b64 s[8:9], s[8:9], 11
	v_readlane_b32 s46, v252, 26
	v_add_u32_e32 v182, 16, v144
	v_readlane_b32 s47, v252, 27
	s_add_u32 s8, s46, s8
	v_add_u32_e32 v0, 0x10000, v182
	s_addc_u32 s9, s47, s9
	ds_read_b128 v[130:133], v0
	ds_read_b128 v[152:155], v0 offset:1024
	ds_read_b128 v[156:159], v0 offset:2048
	ds_read_b128 v[160:163], v0 offset:3072
	ds_read_b128 v[164:167], v147
	ds_read_b128 v[168:171], v147 offset:1024
	ds_read_b128 v[172:175], v147 offset:2048
	ds_read_b128 v[176:179], v147 offset:3072
	ds_read_b128 v[194:197], v147 offset:4096
	ds_read_b128 v[198:201], v147 offset:5120
	ds_read_b128 v[202:205], v147 offset:6144
	ds_read_b128 v[206:209], v147 offset:7168
	v_mov_b32_e32 v0, v135
	v_readfirstlane_b32 s1, v150
	v_lshl_add_u64 v[148:149], s[8:9], 0, v[0:1]
	s_mov_b64 s[8:9], 0x780
	v_lshl_add_u64 v[180:181], v[148:149], 0, s[8:9]
	s_mov_b32 m0, s1
	s_mov_b64 s[8:9], 0x20780
	v_readfirstlane_b32 s1, v151
	global_load_lds_dwordx4 v[180:181], off
	v_lshl_add_u64 v[148:149], v[148:149], 0, s[8:9]
	s_mov_b32 m0, s1
	v_readlane_b32 s41, v252, 21
	global_load_lds_dwordx4 v[148:149], off
	s_barrier
	s_waitcnt lgkmcnt(0)
	v_readlane_b32 s42, v252, 22
	v_readlane_b32 s43, v252, 23
	v_readlane_b32 s44, v252, 24
	v_readlane_b32 s45, v252, 25
	v_readlane_b32 s48, v252, 28
	v_readlane_b32 s49, v252, 29
	v_readlane_b32 s50, v252, 30
	v_readlane_b32 s51, v252, 31
	v_readlane_b32 s52, v252, 32
	v_readlane_b32 s53, v252, 33
	v_readlane_b32 s54, v252, 34
	v_readlane_b32 s55, v252, 35
	s_setprio 1
	s_waitcnt lgkmcnt(0)
	v_mfma_f32_16x16x32_bf16 v[126:129], v[130:133], v[164:167], v[126:129]
	v_mfma_f32_16x16x32_bf16 v[122:125], v[156:159], v[164:167], v[122:125]
	v_mfma_f32_16x16x32_bf16 v[118:121], v[130:133], v[172:175], v[118:121]
	v_mfma_f32_16x16x32_bf16 v[114:117], v[156:159], v[172:175], v[114:117]
	v_mfma_f32_16x16x32_bf16 v[110:113], v[130:133], v[194:197], v[110:113]
	v_mfma_f32_16x16x32_bf16 v[106:109], v[156:159], v[194:197], v[106:109]
	v_mfma_f32_16x16x32_bf16 v[102:105], v[130:133], v[202:205], v[102:105]
	v_mfma_f32_16x16x32_bf16 v[98:101], v[156:159], v[202:205], v[98:101]
	v_mfma_f32_16x16x32_bf16 v[126:129], v[152:155], v[168:171], v[126:129]
	v_mfma_f32_16x16x32_bf16 v[122:125], v[160:163], v[168:171], v[122:125]
	v_mfma_f32_16x16x32_bf16 v[118:121], v[152:155], v[176:179], v[118:121]
	v_mfma_f32_16x16x32_bf16 v[114:117], v[160:163], v[176:179], v[114:117]
	v_mfma_f32_16x16x32_bf16 v[110:113], v[152:155], v[198:201], v[110:113]
	v_mfma_f32_16x16x32_bf16 v[106:109], v[160:163], v[198:201], v[106:109]
	v_mfma_f32_16x16x32_bf16 v[102:105], v[152:155], v[206:209], v[102:105]
	v_mfma_f32_16x16x32_bf16 v[98:101], v[160:163], v[206:209], v[98:101]
	s_setprio 0
	v_add_u32_e32 v0, 0x14000, v182
	s_barrier
	ds_read_b128 v[148:151], v0
	ds_read_b128 v[210:213], v0 offset:1024
	ds_read_b128 v[214:217], v0 offset:2048
	ds_read_b128 v[218:221], v0 offset:3072
	s_barrier
; #define LDA(dst, b, h) for (int m = 0; m < 4; ++m) for (int k = 0; k < 2; ++k) \
;     dst[m][k] = *reinterpret_cast<const bf16x8*>((char*)SA(b, h) + a_thr + (m * 2 + k) * 1024)
; #define LDB(dst, b, h) for (int n = 0; n < 2; ++n) for (int k = 0; k < 2; ++k) \
;     dst[n][k] = *reinterpret_cast<const bf16x8*>((char*)SB(b, h) + b_thr + (n * 2 + k) * 1024)
; #define MMA(ai, bj, At, Btf) do { __builtin_amdgcn_s_setprio(1); \
;     for (int m = 0; m < 4; ++m) for (int n = 0; n < 2; ++n) for (int k = 0; k < 2; ++k) \
;       acc[ai][bj][m][n] = __builtin_amdgcn_mfma_f32_16x16x32_bf16(Btf[n][k], At[m][k], acc[ai][bj][m][n], 0, 0, 0); \
;     __builtin_amdgcn_s_setprio(0); } while (0)
; #define WAIT_V(n) asm volatile("s_waitcnt vmcnt(" #n ")" ::: "memory")
; #define WAIT_L(n) asm volatile("s_waitcnt lgkmcnt(" #n ")" ::: "memory")
; #define BAR __builtin_amdgcn_s_barrier()
; template <bool OVL, bool PANEL = false, class Epi>
; __device__ __forceinline__ void gemm_phase(const bf16_t* __restrict__ A, long lda, const bf16_t* __restrict__ Bt, long ldb, int nM, int nN, int K,
;                                            const Epi& epi, bf16_t* shm, int w0) {
;     ...
;       LDB(B1, 0, 1); BAR; WAIT_L(0); MMA(0, 1, At, B1); BAR;
;       LDA(At, 0, 1); WAIT_V(4); BAR; WAIT_L(0); MMA(1, 0, At, B0); MMA(1, 1, At, B1); BAR; }
;     { LDB(B0, 1, 0); LDA(At, 1, 0); WAIT_V(2); BAR; WAIT_L(0); MMA(0, 0, At, B0); BAR;
	s_waitcnt lgkmcnt(0)
	s_setprio 1
	s_waitcnt lgkmcnt(0)
	v_mfma_f32_16x16x32_bf16 v[94:97], v[148:151], v[164:167], v[94:97]
	v_mfma_f32_16x16x32_bf16 v[90:93], v[214:217], v[164:167], v[90:93]
	v_mfma_f32_16x16x32_bf16 v[86:89], v[148:151], v[172:175], v[86:89]
	v_mfma_f32_16x16x32_bf16 v[82:85], v[214:217], v[172:175], v[82:85]
	v_mfma_f32_16x16x32_bf16 v[78:81], v[148:151], v[194:197], v[78:81]
	v_mfma_f32_16x16x32_bf16 v[74:77], v[214:217], v[194:197], v[74:77]
	v_mfma_f32_16x16x32_bf16 v[70:73], v[148:151], v[202:205], v[70:73]
	v_mfma_f32_16x16x32_bf16 v[66:69], v[214:217], v[202:205], v[66:69]
	v_mfma_f32_16x16x32_bf16 v[94:97], v[210:213], v[168:171], v[94:97]
	v_mfma_f32_16x16x32_bf16 v[90:93], v[218:221], v[168:171], v[90:93]
	v_mfma_f32_16x16x32_bf16 v[86:89], v[210:213], v[176:179], v[86:89]
	v_mfma_f32_16x16x32_bf16 v[82:85], v[218:221], v[176:179], v[82:85]
	v_mfma_f32_16x16x32_bf16 v[78:81], v[210:213], v[198:201], v[78:81]
	v_mfma_f32_16x16x32_bf16 v[74:77], v[218:221], v[198:201], v[74:77]
	v_mfma_f32_16x16x32_bf16 v[70:73], v[210:213], v[206:209], v[70:73]
	v_mfma_f32_16x16x32_bf16 v[66:69], v[218:221], v[206:209], v[66:69]
	s_setprio 0
	s_barrier
	ds_read_b128 v[164:167], v147 offset:16384
	ds_read_b128 v[168:171], v147 offset:17408
	ds_read_b128 v[172:175], v147 offset:18432
	ds_read_b128 v[176:179], v147 offset:19456
	ds_read_b128 v[194:197], v147 offset:20480
	ds_read_b128 v[198:201], v147 offset:21504
	ds_read_b128 v[202:205], v147 offset:22528
	ds_read_b128 v[206:209], v147 offset:23552
	s_waitcnt vmcnt(4)
	s_barrier
	s_waitcnt lgkmcnt(0)
	s_setprio 1
	s_waitcnt lgkmcnt(0)
	v_mfma_f32_16x16x32_bf16 v[62:65], v[130:133], v[164:167], v[62:65]
	v_mfma_f32_16x16x32_bf16 v[58:61], v[156:159], v[164:167], v[58:61]
	v_mfma_f32_16x16x32_bf16 v[54:57], v[130:133], v[172:175], v[54:57]
	v_mfma_f32_16x16x32_bf16 v[50:53], v[156:159], v[172:175], v[50:53]
	v_mfma_f32_16x16x32_bf16 v[46:49], v[130:133], v[194:197], v[46:49]
	v_mfma_f32_16x16x32_bf16 v[42:45], v[156:159], v[194:197], v[42:45]
	v_mfma_f32_16x16x32_bf16 v[38:41], v[130:133], v[202:205], v[38:41]
	v_mfma_f32_16x16x32_bf16 v[34:37], v[156:159], v[202:205], v[34:37]
	v_mfma_f32_16x16x32_bf16 v[62:65], v[152:155], v[168:171], v[62:65]
	v_mfma_f32_16x16x32_bf16 v[58:61], v[160:163], v[168:171], v[58:61]
	v_mfma_f32_16x16x32_bf16 v[54:57], v[152:155], v[176:179], v[54:57]
	v_mfma_f32_16x16x32_bf16 v[50:53], v[160:163], v[176:179], v[50:53]
	v_mfma_f32_16x16x32_bf16 v[46:49], v[152:155], v[198:201], v[46:49]
	v_mfma_f32_16x16x32_bf16 v[42:45], v[160:163], v[198:201], v[42:45]
	v_mfma_f32_16x16x32_bf16 v[38:41], v[152:155], v[206:209], v[38:41]
	v_mfma_f32_16x16x32_bf16 v[34:37], v[160:163], v[206:209], v[34:37]
	s_setprio 0
	s_setprio 1
	v_mfma_f32_16x16x32_bf16 v[30:33], v[148:151], v[164:167], v[30:33]
	v_mfma_f32_16x16x32_bf16 v[26:29], v[214:217], v[164:167], v[26:29]
	v_mfma_f32_16x16x32_bf16 v[22:25], v[148:151], v[172:175], v[22:25]
	v_mfma_f32_16x16x32_bf16 v[18:21], v[214:217], v[172:175], v[18:21]
	v_mfma_f32_16x16x32_bf16 v[14:17], v[148:151], v[194:197], v[14:17]
	v_mfma_f32_16x16x32_bf16 v[10:13], v[214:217], v[194:197], v[10:13]
	v_mfma_f32_16x16x32_bf16 v[6:9], v[148:151], v[202:205], v[6:9]
	v_mfma_f32_16x16x32_bf16 v[2:5], v[214:217], v[202:205], v[2:5]
	v_mfma_f32_16x16x32_bf16 v[30:33], v[210:213], v[168:171], v[30:33]
	v_mfma_f32_16x16x32_bf16 v[26:29], v[218:221], v[168:171], v[26:29]
	v_mfma_f32_16x16x32_bf16 v[22:25], v[210:213], v[176:179], v[22:25]
	v_mfma_f32_16x16x32_bf16 v[18:21], v[218:221], v[176:179], v[18:21]
	v_mfma_f32_16x16x32_bf16 v[14:17], v[210:213], v[198:201], v[14:17]
	v_mfma_f32_16x16x32_bf16 v[10:13], v[218:221], v[198:201], v[10:13]
	v_mfma_f32_16x16x32_bf16 v[6:9], v[210:213], v[206:209], v[6:9]
	v_mfma_f32_16x16x32_bf16 v[2:5], v[218:221], v[206:209], v[2:5]
	s_setprio 0
	v_add_u32_e32 v0, 0x18000, v182
	s_barrier
	ds_read_b128 v[130:133], v0
	ds_read_b128 v[148:151], v0 offset:1024
	ds_read_b128 v[152:155], v0 offset:2048
	ds_read_b128 v[156:159], v0 offset:3072
	ds_read_b128 v[160:163], v147 offset:32768
	ds_read_b128 v[164:167], v147 offset:33792
	ds_read_b128 v[168:171], v147 offset:34816
	ds_read_b128 v[172:175], v147 offset:35840
	ds_read_b128 v[176:179], v147 offset:36864
	ds_read_b128 v[194:197], v147 offset:37888
	ds_read_b128 v[198:201], v147 offset:38912
	ds_read_b128 v[202:205], v147 offset:39936
	s_waitcnt vmcnt(2)
	s_barrier
; #define LDA(dst, b, h) for (int m = 0; m < 4; ++m) for (int k = 0; k < 2; ++k) \
;     dst[m][k] = *reinterpret_cast<const bf16x8*>((char*)SA(b, h) + a_thr + (m * 2 + k) * 1024)
; #define LDB(dst, b, h) for (int n = 0; n < 2; ++n) for (int k = 0; k < 2; ++k) \
;     dst[n][k] = *reinterpret_cast<const bf16x8*>((char*)SB(b, h) + b_thr + (n * 2 + k) * 1024)
; #define MMA(ai, bj, At, Btf) do { __builtin_amdgcn_s_setprio(1); \
;     for (int m = 0; m < 4; ++m) for (int n = 0; n < 2; ++n) for (int k = 0; k < 2; ++k) \
;       acc[ai][bj][m][n] = __builtin_amdgcn_mfma_f32_16x16x32_bf16(Btf[n][k], At[m][k], acc[ai][bj][m][n], 0, 0, 0); \
;     __builtin_amdgcn_s_setprio(0); } while (0)
; #define WAIT_V(n) asm volatile("s_waitcnt vmcnt(" #n ")" ::: "memory")
; #define WAIT_L(n) asm volatile("s_waitcnt lgkmcnt(" #n ")" ::: "memory")
; #define BAR __builtin_amdgcn_s_barrier()
; template <bool OVL, bool PANEL = false, class Epi>
; __device__ __forceinline__ void gemm_phase(const bf16_t* __restrict__ A, long lda, const bf16_t* __restrict__ Bt, long ldb, int nM, int nN, int K,
;                                            const Epi& epi, bf16_t* shm, int w0) {
;     ...
;     { LDB(B0, 1, 0); LDA(At, 1, 0); WAIT_V(2); BAR; WAIT_L(0); MMA(0, 0, At, B0); BAR;
;       LDB(B1, 1, 1); WAIT_V(0); BAR; WAIT_L(0); MMA(0, 1, At, B1); BAR;
;       LDA(At, 1, 1); BAR; WAIT_L(0); MMA(1, 0, At, B0); MMA(1, 1, At, B1); BAR; }
;     if (wr == 0) BAR;
	s_waitcnt lgkmcnt(0)
	s_setprio 1
	s_waitcnt lgkmcnt(0)
	v_mfma_f32_16x16x32_bf16 v[126:129], v[130:133], v[160:163], v[126:129]
	v_mfma_f32_16x16x32_bf16 v[122:125], v[152:155], v[160:163], v[122:125]
	v_mfma_f32_16x16x32_bf16 v[118:121], v[130:133], v[168:171], v[118:121]
	v_mfma_f32_16x16x32_bf16 v[114:117], v[152:155], v[168:171], v[114:117]
	v_mfma_f32_16x16x32_bf16 v[110:113], v[130:133], v[176:179], v[110:113]
	v_mfma_f32_16x16x32_bf16 v[106:109], v[152:155], v[176:179], v[106:109]
	v_mfma_f32_16x16x32_bf16 v[102:105], v[130:133], v[198:201], v[102:105]
	v_mfma_f32_16x16x32_bf16 v[98:101], v[152:155], v[198:201], v[98:101]
	v_mfma_f32_16x16x32_bf16 v[126:129], v[148:151], v[164:167], v[126:129]
	v_mfma_f32_16x16x32_bf16 v[122:125], v[156:159], v[164:167], v[122:125]
	v_mfma_f32_16x16x32_bf16 v[118:121], v[148:151], v[172:175], v[118:121]
	v_mfma_f32_16x16x32_bf16 v[114:117], v[156:159], v[172:175], v[114:117]
	v_mfma_f32_16x16x32_bf16 v[110:113], v[148:151], v[194:197], v[110:113]
	v_mfma_f32_16x16x32_bf16 v[106:109], v[156:159], v[194:197], v[106:109]
	v_mfma_f32_16x16x32_bf16 v[102:105], v[148:151], v[202:205], v[102:105]
	v_mfma_f32_16x16x32_bf16 v[98:101], v[156:159], v[202:205], v[98:101]
	s_setprio 0
	v_add_u32_e32 v0, 0x1c000, v182
	s_barrier
	ds_read_b128 v[206:209], v0
	ds_read_b128 v[210:213], v0 offset:1024
	ds_read_b128 v[214:217], v0 offset:2048
	ds_read_b128 v[218:221], v0 offset:3072
	s_waitcnt vmcnt(0)
	s_barrier
	s_waitcnt lgkmcnt(0)
	s_setprio 1
	s_waitcnt lgkmcnt(0)
	v_mfma_f32_16x16x32_bf16 v[94:97], v[206:209], v[160:163], v[94:97]
	v_mfma_f32_16x16x32_bf16 v[90:93], v[214:217], v[160:163], v[90:93]
	v_mfma_f32_16x16x32_bf16 v[86:89], v[206:209], v[168:171], v[86:89]
	v_mfma_f32_16x16x32_bf16 v[82:85], v[214:217], v[168:171], v[82:85]
	v_mfma_f32_16x16x32_bf16 v[78:81], v[206:209], v[176:179], v[78:81]
	v_mfma_f32_16x16x32_bf16 v[74:77], v[214:217], v[176:179], v[74:77]
	v_mfma_f32_16x16x32_bf16 v[70:73], v[206:209], v[198:201], v[70:73]
	v_mfma_f32_16x16x32_bf16 v[66:69], v[214:217], v[198:201], v[66:69]
	v_mfma_f32_16x16x32_bf16 v[94:97], v[210:213], v[164:167], v[94:97]
	v_mfma_f32_16x16x32_bf16 v[90:93], v[218:221], v[164:167], v[90:93]
	v_mfma_f32_16x16x32_bf16 v[86:89], v[210:213], v[172:175], v[86:89]
	v_mfma_f32_16x16x32_bf16 v[82:85], v[218:221], v[172:175], v[82:85]
	v_mfma_f32_16x16x32_bf16 v[78:81], v[210:213], v[194:197], v[78:81]
	v_mfma_f32_16x16x32_bf16 v[74:77], v[218:221], v[194:197], v[74:77]
	v_mfma_f32_16x16x32_bf16 v[70:73], v[210:213], v[202:205], v[70:73]
	v_mfma_f32_16x16x32_bf16 v[66:69], v[218:221], v[202:205], v[66:69]
	s_setprio 0
	s_barrier
	ds_read_b128 v[160:163], v147 offset:49152
	ds_read_b128 v[164:167], v147 offset:50176
	ds_read_b128 v[168:171], v147 offset:51200
	ds_read_b128 v[172:175], v147 offset:52224
	ds_read_b128 v[176:179], v147 offset:53248
	ds_read_b128 v[194:197], v147 offset:54272
	ds_read_b128 v[198:201], v147 offset:55296
	ds_read_b128 v[202:205], v147 offset:56320
	s_barrier
	s_waitcnt lgkmcnt(0)
	s_setprio 1
	s_waitcnt lgkmcnt(0)
	v_mfma_f32_16x16x32_bf16 v[62:65], v[130:133], v[160:163], v[62:65]
	v_mfma_f32_16x16x32_bf16 v[58:61], v[152:155], v[160:163], v[58:61]
	v_mfma_f32_16x16x32_bf16 v[54:57], v[130:133], v[168:171], v[54:57]
	v_mfma_f32_16x16x32_bf16 v[50:53], v[152:155], v[168:171], v[50:53]
	v_mfma_f32_16x16x32_bf16 v[46:49], v[130:133], v[176:179], v[46:49]
	v_mfma_f32_16x16x32_bf16 v[42:45], v[152:155], v[176:179], v[42:45]
	v_mfma_f32_16x16x32_bf16 v[38:41], v[130:133], v[198:201], v[38:41]
	v_mfma_f32_16x16x32_bf16 v[34:37], v[152:155], v[198:201], v[34:37]
	v_mfma_f32_16x16x32_bf16 v[62:65], v[148:151], v[164:167], v[62:65]
	v_mfma_f32_16x16x32_bf16 v[58:61], v[156:159], v[164:167], v[58:61]
	v_mfma_f32_16x16x32_bf16 v[54:57], v[148:151], v[172:175], v[54:57]
	v_mfma_f32_16x16x32_bf16 v[50:53], v[156:159], v[172:175], v[50:53]
	v_mfma_f32_16x16x32_bf16 v[46:49], v[148:151], v[194:197], v[46:49]
	v_mfma_f32_16x16x32_bf16 v[42:45], v[156:159], v[194:197], v[42:45]
	v_mfma_f32_16x16x32_bf16 v[38:41], v[148:151], v[202:205], v[38:41]
	v_mfma_f32_16x16x32_bf16 v[34:37], v[156:159], v[202:205], v[34:37]
	s_setprio 0
	s_setprio 1
	v_mfma_f32_16x16x32_bf16 v[30:33], v[206:209], v[160:163], v[30:33]
	v_mfma_f32_16x16x32_bf16 v[26:29], v[214:217], v[160:163], v[26:29]
	v_mfma_f32_16x16x32_bf16 v[22:25], v[206:209], v[168:171], v[22:25]
	v_mfma_f32_16x16x32_bf16 v[18:21], v[214:217], v[168:171], v[18:21]
	v_mfma_f32_16x16x32_bf16 v[14:17], v[206:209], v[176:179], v[14:17]
	v_mfma_f32_16x16x32_bf16 v[10:13], v[214:217], v[176:179], v[10:13]
	v_mfma_f32_16x16x32_bf16 v[6:9], v[206:209], v[198:201], v[6:9]
	v_mfma_f32_16x16x32_bf16 v[2:5], v[214:217], v[198:201], v[2:5]
	v_mfma_f32_16x16x32_bf16 v[30:33], v[210:213], v[164:167], v[30:33]
	v_mfma_f32_16x16x32_bf16 v[26:29], v[218:221], v[164:167], v[26:29]
	v_mfma_f32_16x16x32_bf16 v[22:25], v[210:213], v[172:175], v[22:25]
	v_mfma_f32_16x16x32_bf16 v[18:21], v[218:221], v[172:175], v[18:21]
	v_mfma_f32_16x16x32_bf16 v[14:17], v[210:213], v[194:197], v[14:17]
	v_mfma_f32_16x16x32_bf16 v[10:13], v[218:221], v[194:197], v[10:13]
	v_mfma_f32_16x16x32_bf16 v[6:9], v[210:213], v[202:205], v[6:9]
	v_mfma_f32_16x16x32_bf16 v[2:5], v[218:221], v[202:205], v[2:5]
	s_setprio 0
	s_barrier
	s_and_saveexec_b64 s[8:9], s[6:7]
	s_cbranch_execz .LBB0_1056
	s_barrier
